# gate-GEMM sigmoid epilogue: (acc+bias)*(-log2e) as one fma with per-tile pre-scaled bias; attention softmax: exp argument as one fma (f32)
# baseline (speedup 1.0000x reference)
; __device__ __forceinline__ unsigned cvt_pk_bf16(float lo, float hi) { unsigned r; asm volatile("v_cvt_pk_bf16_f32 %0, %1, %2" : "=v"(r) : "v"(lo), "v"(hi)); return r; }
; __device__ __forceinline__ void attnA_item(const Frame& F, const Args& a, int item) {
;     ...
;     float mx = -3.0e38f;
; #pragma unroll
;     for (int ct = 0; ct < 12; ++ct)
; #pragma unroll
;         for (int j = 0; j < 4; ++j) { const int kk = 16 * ct + 4 * fq + j; const int rel = kk - 64 - qq; const int kp = kpw + kk;
;             const bool valid = (rel >= -64) && (rel <= 64) && (kp >= 0) && (kp < L);
;             const float bias = tab[valid ? rel + 64 : 64];
;             const float l = valid ? s[ct][j] * scale + bias : -1e30f; s[ct][j] = l; mx = fmaxf(mx, l); }
;     mx = fmaxf(mx, __shfl_xor(mx, 16)); mx = fmaxf(mx, __shfl_xor(mx, 32));
;     float sum = 0.f;
; #pragma unroll
;     for (int ct = 0; ct < 12; ++ct)
; #pragma unroll
;         for (int j = 0; j < 4; ++j) { const float p = __expf(s[ct][j] - mx); s[ct][j] = p; sum += p; }
;     sum += __shfl_xor(sum, 16); sum += __shfl_xor(sum, 32);
;     bf16x8 pf[6];
; #pragma unroll
;     for (int ks = 0; ks < 6; ++ks) { u32x4 w; w.x = cvt_pk_bf16(s[2 * ks][0], s[2 * ks][1]); w.y = cvt_pk_bf16(s[2 * ks][2], s[2 * ks][3]);
;         w.z = cvt_pk_bf16(s[2 * ks + 1][0], s[2 * ks + 1][1]); w.w = cvt_pk_bf16(s[2 * ks + 1][2], s[2 * ks + 1][3]); pf[ks] = __builtin_bit_cast(bf16x8, w); }
.LBB0_388:
	s_or_b64 exec, exec, s[8:9]
	s_mov_b32 s1, 0xff61b1e6
	v_max3_f32 v2, v49, s1, v48
	v_max3_f32 v2, v2, v45, v44
	v_max3_f32 v2, v2, v47, v46
	v_max3_f32 v2, v2, v41, v40
	v_max3_f32 v2, v2, v43, v42
	v_max3_f32 v2, v2, v37, v36
	v_max3_f32 v2, v2, v39, v38
	v_max3_f32 v2, v2, v33, v32
	v_max3_f32 v2, v2, v50, v35
	v_max3_f32 v2, v2, v21, v20
	v_max3_f32 v2, v2, v23, v22
	v_max3_f32 v2, v2, v17, v16
	v_max3_f32 v2, v2, v19, v18
	v_max3_f32 v2, v2, v29, v28
	v_max3_f32 v2, v2, v31, v30
	v_max3_f32 v2, v2, v25, v24
	v_max3_f32 v2, v2, v27, v26
	v_max3_f32 v2, v2, v13, v12
	v_max3_f32 v2, v2, v15, v14
	v_max3_f32 v2, v2, v9, v8
	v_and_b32_e32 v34, 64, v196
	v_max3_f32 v2, v2, v11, v10
	v_xor_b32_e32 v3, 16, v196
	v_add_u32_e32 v34, 64, v34
	v_max3_f32 v2, v2, v5, v4
	v_cmp_lt_i32_e32 vcc, v3, v34
	v_max3_f32 v2, v2, v7, v6
	v_max3_f32 v2, v2, v1, v0
	v_cndmask_b32_e32 v3, v196, v3, vcc
	v_lshlrev_b32_e32 v3, 2, v3
	ds_bpermute_b32 v51, v3, v2
	s_mov_b64 s[8:9], -1
	s_cmpk_gt_u32 s6, 0x7f
	s_waitcnt lgkmcnt(0)
	v_max_f32_e32 v51, v51, v51
	v_max_f32_e32 v2, v2, v51
	v_xor_b32_e32 v51, 32, v196
	v_cmp_lt_i32_e32 vcc, v51, v34
	s_nop 1
	v_cndmask_b32_e32 v34, v196, v51, vcc
	v_lshlrev_b32_e32 v51, 2, v34
	ds_bpermute_b32 v34, v51, v2
	s_waitcnt lgkmcnt(0)
	v_max_f32_e32 v34, v34, v34
	v_max_f32_e32 v34, v2, v34
	s_mov_b32 s101, 0x3fb8aa3b
	v_mul_f32_e32 v208, 0xbfb8aa3b, v34
	v_fma_f32 v2, v49, s101, v208
	v_exp_f32_e32 v2, v2
	v_fma_f32 v48, v48, s101, v208
	v_exp_f32_e32 v48, v48
	v_fma_f32 v45, v45, s101, v208
	v_exp_f32_e32 v45, v45
	v_fma_f32 v44, v44, s101, v208
	v_exp_f32_e32 v44, v44
	v_fma_f32 v47, v47, s101, v208
	v_add_f32_e32 v49, 0, v2
	v_exp_f32_e32 v47, v47
	v_fma_f32 v46, v46, s101, v208
	v_add_f32_e32 v49, v48, v49
	v_exp_f32_e32 v46, v46
	v_fma_f32 v41, v41, s101, v208
	v_add_f32_e32 v49, v45, v49
	v_exp_f32_e32 v41, v41
	v_fma_f32 v40, v40, s101, v208
	v_add_f32_e32 v49, v44, v49
	v_exp_f32_e32 v40, v40
	v_fma_f32 v43, v43, s101, v208
	v_add_f32_e32 v49, v47, v49
	v_exp_f32_e32 v43, v43
	v_fma_f32 v42, v42, s101, v208
	v_add_f32_e32 v49, v46, v49
	v_exp_f32_e32 v42, v42
	v_fma_f32 v37, v37, s101, v208
	v_add_f32_e32 v49, v41, v49
	v_exp_f32_e32 v37, v37
	v_fma_f32 v36, v36, s101, v208
	v_add_f32_e32 v49, v40, v49
	v_exp_f32_e32 v52, v36
	v_add_f32_e32 v49, v43, v49
	v_fma_f32 v39, v39, s101, v208
	v_add_f32_e32 v49, v42, v49
	v_exp_f32_e32 v39, v39
	v_fma_f32 v38, v38, s101, v208
	v_add_f32_e32 v49, v37, v49
	v_exp_f32_e32 v38, v38
	v_fma_f32 v33, v33, s101, v208
	v_add_f32_e32 v36, v52, v49
	v_exp_f32_e32 v33, v33
	v_fma_f32 v32, v32, s101, v208
	v_exp_f32_e32 v32, v32
	v_fma_f32 v49, v50, s101, v208
	v_add_f32_e32 v36, v39, v36
	v_exp_f32_e32 v49, v49
	v_fma_f32 v35, v35, s101, v208
	v_add_f32_e32 v36, v38, v36
	v_exp_f32_e32 v50, v35
	v_fma_f32 v21, v21, s101, v208
	v_add_f32_e32 v36, v33, v36
	v_exp_f32_e32 v53, v21
	v_fma_f32 v20, v20, s101, v208
	v_add_f32_e32 v36, v32, v36
	v_exp_f32_e32 v54, v20
	v_add_f32_e32 v36, v49, v36
	v_add_f32_e32 v35, v50, v36
	v_add_f32_e32 v21, v53, v35
	v_add_f32_e32 v20, v54, v21
	v_fma_f32 v21, v23, s101, v208
	v_exp_f32_e32 v55, v21
	v_fma_f32 v21, v22, s101, v208
	v_exp_f32_e32 v56, v21
	v_fma_f32 v17, v17, s101, v208
	v_exp_f32_e32 v57, v17
	v_fma_f32 v16, v16, s101, v208
	v_exp_f32_e32 v58, v16
	v_add_f32_e32 v20, v55, v20
	v_add_f32_e32 v20, v56, v20
	v_add_f32_e32 v17, v57, v20
	v_add_f32_e32 v16, v58, v17
	v_fma_f32 v17, v19, s101, v208
	v_exp_f32_e32 v59, v17
	v_fma_f32 v17, v18, s101, v208
	v_exp_f32_e32 v62, v17
	v_fma_f32 v17, v29, s101, v208
	v_exp_f32_e32 v29, v17
	v_fma_f32 v17, v28, s101, v208
	v_exp_f32_e32 v28, v17
	v_fma_f32 v17, v31, s101, v208
	v_exp_f32_e32 v31, v17
	v_fma_f32 v17, v30, s101, v208
	v_exp_f32_e32 v30, v17
	v_fma_f32 v17, v25, s101, v208
	v_exp_f32_e32 v25, v17
	v_add_f32_e32 v16, v59, v16
	v_fma_f32 v17, v24, s101, v208
	v_add_f32_e32 v16, v62, v16
	v_exp_f32_e32 v24, v17
	v_add_f32_e32 v16, v29, v16
	v_fma_f32 v17, v27, s101, v208
	v_add_f32_e32 v16, v28, v16
	v_exp_f32_e32 v27, v17
	v_add_f32_e32 v16, v31, v16
	v_fma_f32 v17, v26, s101, v208
	v_add_f32_e32 v16, v30, v16
	v_exp_f32_e32 v26, v17
	v_fma_f32 v13, v13, s101, v208
	v_add_f32_e32 v16, v25, v16
	v_exp_f32_e32 v63, v13
	v_fma_f32 v12, v12, s101, v208
	v_add_f32_e32 v16, v24, v16
	v_exp_f32_e32 v66, v12
	v_add_f32_e32 v16, v27, v16
	v_add_f32_e32 v16, v26, v16
	v_add_f32_e32 v13, v63, v16
	v_add_f32_e32 v12, v66, v13
	v_fma_f32 v13, v15, s101, v208
	v_exp_f32_e32 v71, v13
	v_fma_f32 v13, v14, s101, v208
	v_exp_f32_e32 v73, v13
	v_fma_f32 v9, v9, s101, v208
	v_exp_f32_e32 v74, v9
	v_fma_f32 v8, v8, s101, v208
	v_exp_f32_e32 v75, v8
	v_add_f32_e32 v12, v71, v12
	v_add_f32_e32 v12, v73, v12
	v_add_f32_e32 v9, v74, v12
	v_add_f32_e32 v8, v75, v9
	v_fma_f32 v9, v11, s101, v208
	v_exp_f32_e32 v198, v9
	v_fma_f32 v9, v10, s101, v208
	v_exp_f32_e32 v199, v9
	v_fma_f32 v5, v5, s101, v208
	v_exp_f32_e32 v200, v5
	v_fma_f32 v4, v4, s101, v208
	v_exp_f32_e32 v201, v4
	v_add_f32_e32 v8, v198, v8
	v_add_f32_e32 v8, v199, v8
	v_add_f32_e32 v5, v200, v8
	v_add_f32_e32 v4, v201, v5
	v_fma_f32 v5, v7, s101, v208
	v_exp_f32_e32 v202, v5
	v_fma_f32 v5, v6, s101, v208
	v_exp_f32_e32 v203, v5
	v_fma_f32 v1, v1, s101, v208
	v_exp_f32_e32 v204, v1
	v_fma_f32 v0, v0, s101, v208
	v_exp_f32_e32 v205, v0
	v_add_f32_e32 v4, v202, v4
	v_add_f32_e32 v4, v203, v4
	v_add_f32_e32 v1, v204, v4
	v_add_f32_e32 v0, v205, v1
	ds_bpermute_b32 v1, v3, v0
	v_cvt_pk_bf16_f32 v20, v2, v48
	v_cvt_pk_bf16_f32 v21, v45, v44
	v_cvt_pk_bf16_f32 v22, v47, v46
	v_cvt_pk_bf16_f32 v23, v41, v40
	s_waitcnt lgkmcnt(0)
; #define LAS __attribute__((address_space(3)))
; __device__ __forceinline__ unsigned cvt_pk_bf16(float lo, float hi) { unsigned r; asm volatile("v_cvt_pk_bf16_f32 %0, %1, %2" : "=v"(r) : "v"(lo), "v"(hi)); return r; }
; __device__ __forceinline__ s16x4 vtr(const LAS char* p) { return __builtin_bit_cast(s16x4, __builtin_amdgcn_ds_read_tr16_b64_v4i16((LAS s16x4*)p)); }
; template <int NKS>
; __device__ __forceinline__ void pv_accum(f32x4 (&o)[8], const LAS unsigned char* Vt, int key_row0, const bf16x8 (&pf)[NKS], int fr, int fq) {
; #pragma unroll
;     for (int ks = 0; ks < NKS; ++ks) {
;         const LAS char* p0 = (const LAS char*)Vt + (key_row0 + 32 * ks + 4 * fq + (fr >> 2)) * AT_PITCH + 8 * (fr & 3);
; #pragma unroll
;         for (int dt = 0; dt < 8; ++dt) { const s16x4 lo = vtr(p0 + 32 * dt), hi = vtr(p0 + 16 * AT_PITCH + 32 * dt);
;             const bf16x8 vf = {lo[0], lo[1], lo[2], lo[3], hi[0], hi[1], hi[2], hi[3]};
;             o[dt] = __builtin_amdgcn_mfma_f32_16x16x32_bf16(vf, pf[ks], o[dt], 0, 0, 0); }
;         asm volatile("" ::: "memory");
;     }
; }
; __device__ __forceinline__ void attnA_item(const Frame& F, const Args& a, int item) {
;     ...
;     sum += __shfl_xor(sum, 16); sum += __shfl_xor(sum, 32);
;     bf16x8 pf[6];
; #pragma unroll
;     for (int ks = 0; ks < 6; ++ks) { u32x4 w; w.x = cvt_pk_bf16(s[2 * ks][0], s[2 * ks][1]); w.y = cvt_pk_bf16(s[2 * ks][2], s[2 * ks][3]);
;         w.z = cvt_pk_bf16(s[2 * ks + 1][0], s[2 * ks + 1][1]); w.w = cvt_pk_bf16(s[2 * ks + 1][2], s[2 * ks + 1][3]); pf[ks] = __builtin_bit_cast(bf16x8, w); }
;     f32x4 o[8];
; #pragma unroll
;     for (int dt = 0; dt < 8; ++dt) o[dt] = (f32x4){0.f, 0.f, 0.f, 0.f};
;     pv_accum<6>(o, R1, 64 * hb, pf, fr, fq);
	v_add_f32_e32 v35, v0, v1
	v_cvt_pk_bf16_f32 v16, v43, v42
	v_cvt_pk_bf16_f32 v17, v37, v52
	v_cvt_pk_bf16_f32 v18, v39, v38
	v_cvt_pk_bf16_f32 v19, v33, v32
	v_cvt_pk_bf16_f32 v12, v49, v50
	v_cvt_pk_bf16_f32 v13, v53, v54
	v_cvt_pk_bf16_f32 v14, v55, v56
	v_cvt_pk_bf16_f32 v15, v57, v58
	v_cvt_pk_bf16_f32 v8, v59, v62
	v_cvt_pk_bf16_f32 v9, v29, v28
	v_cvt_pk_bf16_f32 v10, v31, v30
	v_cvt_pk_bf16_f32 v11, v25, v24
	v_cvt_pk_bf16_f32 v4, v27, v26
	v_cvt_pk_bf16_f32 v5, v63, v66
	v_cvt_pk_bf16_f32 v6, v71, v73
	v_cvt_pk_bf16_f32 v7, v74, v75
	v_cvt_pk_bf16_f32 v0, v198, v199
	v_cvt_pk_bf16_f32 v1, v200, v201
	v_cvt_pk_bf16_f32 v2, v202, v203
	v_cvt_pk_bf16_f32 v3, v204, v205
	ds_read_b64_tr_b16 v[26:27], v181 offset:4352
	ds_read_b64_tr_b16 v[24:25], v181
	ds_read_b64_tr_b16 v[28:29], v181 offset:32
	ds_read_b64_tr_b16 v[30:31], v181 offset:4384
	ds_bpermute_b32 v36, v51, v35
	ds_read_b64_tr_b16 v[38:39], v181 offset:64
	ds_read_b64_tr_b16 v[40:41], v181 offset:4416
	ds_read_b64_tr_b16 v[42:43], v181 offset:96
	ds_read_b64_tr_b16 v[44:45], v181 offset:4448
	ds_read_b64_tr_b16 v[46:47], v181 offset:128
	ds_read_b64_tr_b16 v[48:49], v181 offset:4480
	ds_read_b64_tr_b16 v[50:51], v181 offset:160
	ds_read_b64_tr_b16 v[52:53], v181 offset:4512
	ds_read_b64_tr_b16 v[54:55], v181 offset:192
	ds_read_b64_tr_b16 v[56:57], v181 offset:4544
	ds_read_b64_tr_b16 v[198:199], v181 offset:224
	ds_read_b64_tr_b16 v[200:201], v181 offset:4576
	s_waitcnt lgkmcnt(14)
	v_mfma_f32_16x16x32_bf16 v[24:27], v[24:27], v[20:23], 0
	s_waitcnt lgkmcnt(13)
	v_mfma_f32_16x16x32_bf16 v[28:31], v[28:31], v[20:23], 0
	s_waitcnt lgkmcnt(10)
	v_mfma_f32_16x16x32_bf16 v[38:41], v[38:41], v[20:23], 0
	s_waitcnt lgkmcnt(8)
	v_mfma_f32_16x16x32_bf16 v[42:45], v[42:45], v[20:23], 0
	s_waitcnt lgkmcnt(6)
	v_mfma_f32_16x16x32_bf16 v[46:49], v[46:49], v[20:23], 0
	s_waitcnt lgkmcnt(4)
	v_mfma_f32_16x16x32_bf16 v[50:53], v[50:53], v[20:23], 0
	s_waitcnt lgkmcnt(2)
	v_mfma_f32_16x16x32_bf16 v[54:57], v[54:57], v[20:23], 0
	s_waitcnt lgkmcnt(0)
	v_mfma_f32_16x16x32_bf16 v[20:23], v[198:201], v[20:23], 0
	ds_read_b64_tr_b16 v[200:201], v181 offset:13056
	ds_read_b64_tr_b16 v[198:199], v181 offset:8704
	ds_read_b64_tr_b16 v[202:203], v181 offset:8736
	ds_read_b64_tr_b16 v[204:205], v181 offset:13088
	s_waitcnt lgkmcnt(2)
	v_mfma_f32_16x16x32_bf16 v[24:27], v[198:201], v[16:19], v[24:27]
	ds_read_b64_tr_b16 v[198:199], v181 offset:8768
	ds_read_b64_tr_b16 v[200:201], v181 offset:13120
	s_waitcnt lgkmcnt(0)
	v_mfma_f32_16x16x32_bf16 v[38:41], v[198:201], v[16:19], v[38:41]
	ds_read_b64_tr_b16 v[198:199], v181 offset:8800
	ds_read_b64_tr_b16 v[200:201], v181 offset:13152
	s_waitcnt lgkmcnt(0)
	v_mfma_f32_16x16x32_bf16 v[42:45], v[198:201], v[16:19], v[42:45]
	ds_read_b64_tr_b16 v[198:199], v181 offset:8832
	ds_read_b64_tr_b16 v[200:201], v181 offset:13184
	s_waitcnt lgkmcnt(0)
	v_mfma_f32_16x16x32_bf16 v[46:49], v[198:201], v[16:19], v[46:49]
	ds_read_b64_tr_b16 v[198:199], v181 offset:8864
	ds_read_b64_tr_b16 v[200:201], v181 offset:13216
	s_waitcnt lgkmcnt(0)
	v_mfma_f32_16x16x32_bf16 v[50:53], v[198:201], v[16:19], v[50:53]
	ds_read_b64_tr_b16 v[198:199], v181 offset:8896
	ds_read_b64_tr_b16 v[200:201], v181 offset:13248
	s_waitcnt lgkmcnt(0)
	v_mfma_f32_16x16x32_bf16 v[54:57], v[198:201], v[16:19], v[54:57]
	ds_read_b64_tr_b16 v[198:199], v181 offset:8928
	ds_read_b64_tr_b16 v[200:201], v181 offset:13280
	v_mfma_f32_16x16x32_bf16 v[28:31], v[202:205], v[16:19], v[28:31]
	s_waitcnt lgkmcnt(0)
	v_mfma_f32_16x16x32_bf16 v[16:19], v[198:201], v[16:19], v[20:23]
	s_nop 2
	ds_read_b64_tr_b16 v[22:23], v181 offset:21760
	ds_read_b64_tr_b16 v[20:21], v181 offset:17408
	ds_read_b64_tr_b16 v[198:199], v181 offset:17440
	ds_read_b64_tr_b16 v[200:201], v181 offset:21792
	s_waitcnt lgkmcnt(2)
	v_mfma_f32_16x16x32_bf16 v[20:23], v[20:23], v[12:15], v[24:27]
	s_waitcnt lgkmcnt(0)
	v_mfma_f32_16x16x32_bf16 v[24:27], v[198:201], v[12:15], v[28:31]
	s_nop 2
	ds_read_b64_tr_b16 v[28:29], v181 offset:17472
	ds_read_b64_tr_b16 v[30:31], v181 offset:21824
	s_waitcnt lgkmcnt(0)
	v_mfma_f32_16x16x32_bf16 v[28:31], v[28:31], v[12:15], v[38:41]
	s_nop 2
	ds_read_b64_tr_b16 v[38:39], v181 offset:17504
	ds_read_b64_tr_b16 v[40:41], v181 offset:21856
	s_waitcnt lgkmcnt(0)
	v_mfma_f32_16x16x32_bf16 v[38:41], v[38:41], v[12:15], v[42:45]
	s_nop 2
	ds_read_b64_tr_b16 v[42:43], v181 offset:17536
	ds_read_b64_tr_b16 v[44:45], v181 offset:21888
	s_waitcnt lgkmcnt(0)
	v_mfma_f32_16x16x32_bf16 v[42:45], v[42:45], v[12:15], v[46:49]
	s_nop 2
	ds_read_b64_tr_b16 v[46:47], v181 offset:17568
	ds_read_b64_tr_b16 v[48:49], v181 offset:21920
	s_waitcnt lgkmcnt(0)
	v_mfma_f32_16x16x32_bf16 v[46:49], v[46:49], v[12:15], v[50:53]
	s_nop 2
	ds_read_b64_tr_b16 v[50:51], v181 offset:17600
	ds_read_b64_tr_b16 v[52:53], v181 offset:21952
	s_waitcnt lgkmcnt(0)
	v_mfma_f32_16x16x32_bf16 v[50:53], v[50:53], v[12:15], v[54:57]
	s_nop 2
	ds_read_b64_tr_b16 v[54:55], v181 offset:17632
	ds_read_b64_tr_b16 v[56:57], v181 offset:21984
	s_waitcnt lgkmcnt(0)
; #define LAS __attribute__((address_space(3)))
; __device__ __forceinline__ unsigned cvt_pk_bf16(float lo, float hi) { unsigned r; asm volatile("v_cvt_pk_bf16_f32 %0, %1, %2" : "=v"(r) : "v"(lo), "v"(hi)); return r; }
; __device__ __forceinline__ s16x4 vtr(const LAS char* p) { return __builtin_bit_cast(s16x4, __builtin_amdgcn_ds_read_tr16_b64_v4i16((LAS s16x4*)p)); }
; template <int NKS>
; __device__ __forceinline__ void pv_accum(f32x4 (&o)[8], const LAS unsigned char* Vt, int key_row0, const bf16x8 (&pf)[NKS], int fr, int fq) {
; #pragma unroll
;     for (int ks = 0; ks < NKS; ++ks) {
;         const LAS char* p0 = (const LAS char*)Vt + (key_row0 + 32 * ks + 4 * fq + (fr >> 2)) * AT_PITCH + 8 * (fr & 3);
; #pragma unroll
;         for (int dt = 0; dt < 8; ++dt) { const s16x4 lo = vtr(p0 + 32 * dt), hi = vtr(p0 + 16 * AT_PITCH + 32 * dt);
;             const bf16x8 vf = {lo[0], lo[1], lo[2], lo[3], hi[0], hi[1], hi[2], hi[3]};
;             o[dt] = __builtin_amdgcn_mfma_f32_16x16x32_bf16(vf, pf[ks], o[dt], 0, 0, 0); }
;         asm volatile("" ::: "memory");
;     }
; }
; __device__ __forceinline__ void attnA_item(const Frame& F, const Args& a, int item) {
;     ...
;     pv_accum<6>(o, R1, 64 * hb, pf, fr, fq);
;     const float inv = 1.0f / sum;
;     bf16_t* orow = (g == 0) ? (bf16_t*)a.out + qrow * YP + hh * 128 : (bf16_t*)((unsigned char*)a.out + DO_O12) + qrow * 1024 + (g - 1) * 512 + hh * 128;
; #pragma unroll
;     for (int dt = 0; dt < 8; ++dt) { u32x2 w; w.x = cvt_pk_bf16(o[dt][0] * inv, o[dt][1] * inv); w.y = cvt_pk_bf16(o[dt][2] * inv, o[dt][3] * inv); *(u32x2*)(orow + 16 * dt + 4 * fq) = w; }
	v_mfma_f32_16x16x32_bf16 v[12:15], v[54:57], v[12:15], v[16:19]
	s_nop 2
	ds_read_b64_tr_b16 v[18:19], v181 offset:30464
	ds_read_b64_tr_b16 v[16:17], v181 offset:26112
	ds_read_b64_tr_b16 v[54:55], v181 offset:26144
	ds_read_b64_tr_b16 v[56:57], v181 offset:30496
	s_waitcnt lgkmcnt(2)
	v_mfma_f32_16x16x32_bf16 v[16:19], v[16:19], v[8:11], v[20:23]
	s_waitcnt lgkmcnt(0)
	v_mfma_f32_16x16x32_bf16 v[20:23], v[54:57], v[8:11], v[24:27]
	s_nop 2
	ds_read_b64_tr_b16 v[24:25], v181 offset:26176
	ds_read_b64_tr_b16 v[26:27], v181 offset:30528
	s_waitcnt lgkmcnt(0)
	v_mfma_f32_16x16x32_bf16 v[24:27], v[24:27], v[8:11], v[28:31]
	s_nop 2
	ds_read_b64_tr_b16 v[28:29], v181 offset:26208
	ds_read_b64_tr_b16 v[30:31], v181 offset:30560
	s_waitcnt lgkmcnt(0)
	v_mfma_f32_16x16x32_bf16 v[28:31], v[28:31], v[8:11], v[38:41]
	s_nop 2
	ds_read_b64_tr_b16 v[38:39], v181 offset:26240
	ds_read_b64_tr_b16 v[40:41], v181 offset:30592
	s_waitcnt lgkmcnt(0)
	v_mfma_f32_16x16x32_bf16 v[38:41], v[38:41], v[8:11], v[42:45]
	s_nop 2
	ds_read_b64_tr_b16 v[42:43], v181 offset:26272
	ds_read_b64_tr_b16 v[44:45], v181 offset:30624
	s_waitcnt lgkmcnt(0)
	v_mfma_f32_16x16x32_bf16 v[42:45], v[42:45], v[8:11], v[46:49]
	s_nop 2
	ds_read_b64_tr_b16 v[46:47], v181 offset:26304
	ds_read_b64_tr_b16 v[48:49], v181 offset:30656
	s_waitcnt lgkmcnt(0)
	v_mfma_f32_16x16x32_bf16 v[46:49], v[46:49], v[8:11], v[50:53]
	s_nop 2
	ds_read_b64_tr_b16 v[50:51], v181 offset:26336
	ds_read_b64_tr_b16 v[52:53], v181 offset:30688
	s_waitcnt lgkmcnt(0)
	v_mfma_f32_16x16x32_bf16 v[8:11], v[50:53], v[8:11], v[12:15]
	s_nop 2
	ds_read_b64_tr_b16 v[14:15], v181 offset:39168
	ds_read_b64_tr_b16 v[12:13], v181 offset:34816
	ds_read_b64_tr_b16 v[50:51], v181 offset:34848
	ds_read_b64_tr_b16 v[52:53], v181 offset:39200
	s_waitcnt lgkmcnt(2)
	v_mfma_f32_16x16x32_bf16 v[12:15], v[12:15], v[4:7], v[16:19]
	s_waitcnt lgkmcnt(0)
	v_mfma_f32_16x16x32_bf16 v[16:19], v[50:53], v[4:7], v[20:23]
	s_nop 2
	ds_read_b64_tr_b16 v[20:21], v181 offset:34880
	ds_read_b64_tr_b16 v[22:23], v181 offset:39232
	s_waitcnt lgkmcnt(0)
	v_mfma_f32_16x16x32_bf16 v[20:23], v[20:23], v[4:7], v[24:27]
	s_nop 2
	ds_read_b64_tr_b16 v[24:25], v181 offset:34912
	ds_read_b64_tr_b16 v[26:27], v181 offset:39264
	s_waitcnt lgkmcnt(0)
	v_mfma_f32_16x16x32_bf16 v[24:27], v[24:27], v[4:7], v[28:31]
	s_nop 2
	ds_read_b64_tr_b16 v[28:29], v181 offset:34944
	ds_read_b64_tr_b16 v[30:31], v181 offset:39296
	s_waitcnt lgkmcnt(0)
	v_mfma_f32_16x16x32_bf16 v[28:31], v[28:31], v[4:7], v[38:41]
	s_nop 2
	ds_read_b64_tr_b16 v[38:39], v181 offset:34976
	ds_read_b64_tr_b16 v[40:41], v181 offset:39328
	s_waitcnt lgkmcnt(0)
	v_mfma_f32_16x16x32_bf16 v[38:41], v[38:41], v[4:7], v[42:45]
	s_nop 2
	ds_read_b64_tr_b16 v[42:43], v181 offset:35008
	ds_read_b64_tr_b16 v[44:45], v181 offset:39360
	s_waitcnt lgkmcnt(0)
	v_mfma_f32_16x16x32_bf16 v[42:45], v[42:45], v[4:7], v[46:49]
	s_nop 2
	ds_read_b64_tr_b16 v[46:47], v181 offset:35040
	ds_read_b64_tr_b16 v[48:49], v181 offset:39392
	s_waitcnt lgkmcnt(0)
	v_mfma_f32_16x16x32_bf16 v[46:49], v[46:49], v[4:7], v[8:11]
	ds_read_b64_tr_b16 v[6:7], v181 offset:47872
	ds_read_b64_tr_b16 v[4:5], v181 offset:43520
	s_nop 0
	ds_read_b64_tr_b16 v[8:9], v181 offset:43552
	ds_read_b64_tr_b16 v[10:11], v181 offset:47904
	s_waitcnt lgkmcnt(2)
	v_mfma_f32_16x16x32_bf16 v[4:7], v[4:7], v[0:3], v[12:15]
	s_nop 2
	ds_read_b64_tr_b16 v[12:13], v181 offset:43584
	ds_read_b64_tr_b16 v[14:15], v181 offset:47936
	s_waitcnt lgkmcnt(2)
	v_mfma_f32_16x16x32_bf16 v[8:11], v[8:11], v[0:3], v[16:19]
	s_nop 2
	ds_read_b64_tr_b16 v[16:17], v181 offset:43616
	ds_read_b64_tr_b16 v[18:19], v181 offset:47968
	s_waitcnt lgkmcnt(2)
	v_mfma_f32_16x16x32_bf16 v[12:15], v[12:15], v[0:3], v[20:23]
	s_nop 2
	ds_read_b64_tr_b16 v[20:21], v181 offset:43648
	ds_read_b64_tr_b16 v[22:23], v181 offset:48000
	s_waitcnt lgkmcnt(2)
	v_mfma_f32_16x16x32_bf16 v[16:19], v[16:19], v[0:3], v[24:27]
	s_nop 2
	ds_read_b64_tr_b16 v[24:25], v181 offset:43680
	ds_read_b64_tr_b16 v[26:27], v181 offset:48032
	s_waitcnt lgkmcnt(2)
	v_mfma_f32_16x16x32_bf16 v[20:23], v[20:23], v[0:3], v[28:31]
	s_nop 2
	ds_read_b64_tr_b16 v[28:29], v181 offset:43712
	ds_read_b64_tr_b16 v[30:31], v181 offset:48064
	s_waitcnt lgkmcnt(2)
	v_mfma_f32_16x16x32_bf16 v[24:27], v[24:27], v[0:3], v[38:41]
	s_nop 2
	ds_read_b64_tr_b16 v[38:39], v181 offset:43744
	ds_read_b64_tr_b16 v[40:41], v181 offset:48096
	s_waitcnt lgkmcnt(2)
	v_mfma_f32_16x16x32_bf16 v[28:31], v[28:31], v[0:3], v[42:45]
	s_waitcnt lgkmcnt(0)
	v_mfma_f32_16x16x32_bf16 v[0:3], v[38:41], v[0:3], v[46:49]
	s_cbranch_scc0 .LBB0_390
	v_lshlrev_b64 v[32:33], 11, v[60:61]
	s_lshl_b32 s8, s5, 9
	v_lshl_add_u64 v[32:33], s[20:21], 0, v[32:33]
	s_ashr_i32 s9, s8, 31
	v_lshl_add_u64 v[32:33], s[8:9], 1, v[32:33]
	s_mov_b64 s[8:9], 0x5fffc00
	v_lshl_add_u64 v[32:33], v[32:33], 0, s[8:9]
	s_and_b32 s6, s0, 0x180
	s_mov_b64 s[8:9], 0

; __device__ __forceinline__ void attnC_item(const Frame& F, const Args& a, int item) {
;     ...
;     const bf16_t* kbase = kv + (size_t)b * NMEM * 2048 + head * 256;
;     __syncthreads();
;     STAGE_TILE2(R0, (kbase + (size_t)i * 2048), R1, (kbase + (size_t)i * 2048 + 128));
;     bf16x8 qf[4];
;     f32x4 s[16];
; #pragma unroll
;     for (int ct = 0; ct < 16; ++ct) s[ct] = (f32x4){0.f, 0.f, 0.f, 0.f};
; #pragma unroll
;     for (int ks = 0; ks < 4; ++ks) qf[ks] = *(const bf16x8*)(proj + qrow * NIN + C_QC + head * 256 + 32 * ks + 8 * fq);
;     __syncthreads();
;     qk_accum<16>(s, R0, 0, qf, fr, fq);
.LBB0_396:
	s_ashr_i32 s34, s29, 7
	s_ashr_i32 s35, s34, 31
	s_lshl_b64 s[2:3], s[34:35], 12
	s_and_b32 s30, s13, 0xf80
	s_lshl_b64 s[34:35], s[34:35], 20
	s_add_u32 s31, s10, s34
	s_addc_u32 s33, s11, s35
	s_and_b32 s0, s28, 0x300
	s_lshl_b32 s0, s0, 1
	s_add_u32 s34, s31, s0
	s_addc_u32 s35, s33, 0
	v_lshl_add_u64 v[0:1], s[34:35], 0, v[98:99]
	v_lshl_add_u64 v[8:9], s[34:35], 0, v[100:101]
	v_lshl_add_u64 v[16:17], s[34:35], 0, v[102:103]
	v_lshl_add_u64 v[24:25], s[34:35], 0, v[104:105]
	v_lshl_add_u64 v[32:33], s[34:35], 0, v[106:107]
	v_lshl_add_u64 v[40:41], s[34:35], 0, v[108:109]
	v_lshl_add_u64 v[48:49], s[34:35], 0, v[110:111]
	v_lshl_add_u64 v[56:57], s[34:35], 0, v[112:113]
	v_lshl_add_u64 v[124:125], v[0:1], 0, v[114:115]
	v_lshl_add_u64 v[126:127], v[8:9], 0, v[114:115]
	v_lshl_add_u64 v[128:129], v[16:17], 0, v[114:115]
	v_lshl_add_u64 v[130:131], v[24:25], 0, v[114:115]
	v_lshl_add_u64 v[132:133], v[32:33], 0, v[114:115]
	v_lshl_add_u64 v[134:135], v[40:41], 0, v[114:115]
	v_lshl_add_u64 v[136:137], v[48:49], 0, v[114:115]
	v_lshl_add_u64 v[138:139], v[56:57], 0, v[114:115]
	s_waitcnt vmcnt(0)
	s_barrier
	global_load_dwordx4 v[0:3], v[124:125], off
	global_load_dwordx4 v[4:7], v[124:125], off offset:256
	global_load_dwordx4 v[8:11], v[126:127], off
	global_load_dwordx4 v[12:15], v[126:127], off offset:256
	global_load_dwordx4 v[16:19], v[128:129], off
	global_load_dwordx4 v[20:23], v[128:129], off offset:256
	global_load_dwordx4 v[24:27], v[130:131], off
	global_load_dwordx4 v[28:31], v[130:131], off offset:256
	global_load_dwordx4 v[32:35], v[132:133], off
	global_load_dwordx4 v[36:39], v[132:133], off offset:256
	global_load_dwordx4 v[40:43], v[134:135], off
	global_load_dwordx4 v[44:47], v[134:135], off offset:256
	global_load_dwordx4 v[48:51], v[136:137], off
	global_load_dwordx4 v[52:55], v[136:137], off offset:256
	global_load_dwordx4 v[56:59], v[138:139], off
	global_load_dwordx4 v[60:63], v[138:139], off offset:256
	v_add_u32_e32 v96, s30, v140
	v_lshl_add_u64 v[122:123], s[2:3], 0, v[96:97]
	s_add_i32 s29, s29, s26
	s_add_i32 s13, s13, s14
	s_add_i32 s28, s28, s94
	s_cmpk_gt_i32 s29, 0x1ff
	s_waitcnt vmcnt(15)
	ds_write_b128 v146, v[0:3]
	s_waitcnt vmcnt(14)
	ds_write_b128 v158, v[4:7]
	s_waitcnt vmcnt(13)
	ds_write_b128 v147, v[8:11]
	s_waitcnt vmcnt(12)
	ds_write_b128 v148, v[12:15]
	s_waitcnt vmcnt(11)
	ds_write_b128 v146, v[16:19] offset:17408
	s_waitcnt vmcnt(10)
	ds_write_b128 v149, v[20:23]
	s_waitcnt vmcnt(9)
	ds_write_b128 v150, v[24:27]
	s_waitcnt vmcnt(8)
	ds_write_b128 v151, v[28:31]
	s_waitcnt vmcnt(7)
	ds_write_b128 v146, v[32:35] offset:34816
	s_waitcnt vmcnt(6)
	ds_write_b128 v152, v[36:39]
	s_waitcnt vmcnt(5)
	ds_write_b128 v153, v[40:43]
	s_waitcnt vmcnt(4)
	ds_write_b128 v154, v[44:47]
	s_waitcnt vmcnt(3)
	ds_write_b128 v146, v[48:51] offset:52224
	s_waitcnt vmcnt(2)
	ds_write_b128 v155, v[52:55]
	s_waitcnt vmcnt(1)
	ds_write_b128 v156, v[56:59]
	s_waitcnt vmcnt(0)
	ds_write_b128 v157, v[60:63]
	v_mad_u64_u32 v[0:1], s[2:3], v122, s12, v[120:121]
	v_mad_i32_i24 v1, v123, s12, v1
	v_lshl_add_u64 v[0:1], v[0:1], 0, s[0:1]
	v_lshl_add_u64 v[76:77], v[0:1], 0, v[116:117]
	v_add_co_u32_e32 v78, vcc, s15, v76
	v_lshl_add_u64 v[4:5], v[76:77], 0, s[4:5]
	s_nop 0
	v_addc_co_u32_e32 v79, vcc, 0, v77, vcc
	global_load_dwordx4 v[36:39], v[78:79], off offset:3072
	global_load_dwordx4 v[8:11], v[4:5], off offset:64
	global_load_dwordx4 v[0:3], v[4:5], off offset:128
	s_nop 0
	global_load_dwordx4 v[4:7], v[4:5], off offset:192
	s_waitcnt lgkmcnt(0)
	s_barrier
	ds_read_b128 v[208:211], v141
	ds_read_b128 v[212:215], v141 offset:64
	ds_read_b128 v[216:219], v141 offset:128
	ds_read_b128 v[220:223], v141 offset:192
	ds_read_b128 v[224:227], v141 offset:4352
	ds_read_b128 v[228:231], v141 offset:4416
	ds_read_b128 v[232:235], v141 offset:4480
	ds_read_b128 v[236:239], v141 offset:4544
	ds_read_b128 v[244:247], v141 offset:13120
	ds_read_b128 v[248:251], v141 offset:8704
	ds_read_b128 v[252:255], v141 offset:8768
	s_waitcnt vmcnt(0)
	s_waitcnt lgkmcnt(10)
	v_mfma_f32_16x16x32_bf16 v[12:15], v[208:211], v[36:39], 0
	ds_read_b128 v[208:211], v141 offset:8832
	s_waitcnt lgkmcnt(10)
	v_mfma_f32_16x16x32_bf16 v[12:15], v[212:215], v[8:11], v[12:15]
	ds_read_b128 v[212:215], v141 offset:8896
	s_waitcnt lgkmcnt(10)
	v_mfma_f32_16x16x32_bf16 v[12:15], v[216:219], v[0:3], v[12:15]
	ds_read_b128 v[216:219], v141 offset:13056
	s_waitcnt lgkmcnt(10)
	v_mfma_f32_16x16x32_bf16 v[40:43], v[220:223], v[4:7], v[12:15]
	ds_read_b128 v[220:223], v141 offset:13184
	s_waitcnt lgkmcnt(10)
	v_mfma_f32_16x16x32_bf16 v[12:15], v[224:227], v[36:39], 0
	ds_read_b128 v[224:227], v141 offset:13248
	s_waitcnt lgkmcnt(10)
	v_mfma_f32_16x16x32_bf16 v[12:15], v[228:231], v[8:11], v[12:15]
	ds_read_b128 v[228:231], v141 offset:17472
	s_waitcnt lgkmcnt(10)
	v_mfma_f32_16x16x32_bf16 v[12:15], v[232:235], v[0:3], v[12:15]
	ds_read_b128 v[232:235], v141 offset:17408
	s_waitcnt lgkmcnt(10)
	v_mfma_f32_16x16x32_bf16 v[28:31], v[236:239], v[4:7], v[12:15]
	ds_read_b128 v[236:239], v141 offset:21824
	s_waitcnt lgkmcnt(9)
	v_mfma_f32_16x16x32_bf16 v[12:15], v[248:251], v[36:39], 0
	ds_read_b128 v[248:251], v141 offset:17536
	s_waitcnt lgkmcnt(9)
	v_mfma_f32_16x16x32_bf16 v[12:15], v[252:255], v[8:11], v[12:15]
	ds_read_b128 v[252:255], v141 offset:17600
	s_waitcnt lgkmcnt(9)
	v_mfma_f32_16x16x32_bf16 v[12:15], v[208:211], v[0:3], v[12:15]
	ds_read_b128 v[208:211], v141 offset:21760
	s_waitcnt lgkmcnt(9)
	v_mfma_f32_16x16x32_bf16 v[12:15], v[212:215], v[4:7], v[12:15]
	ds_read_b128 v[212:215], v141 offset:21888
	s_waitcnt lgkmcnt(9)
; #define LAS __attribute__((address_space(3)))
; template <int NCT>
; __device__ __forceinline__ void qk_accum(f32x4 (&s)[NCT], const LAS unsigned char* Kt, int key_row0, const bf16x8 (&qf)[4], int fr, int fq) {
; #pragma unroll
;     for (int ct = 0; ct < NCT; ++ct)
; #pragma unroll
;         for (int ks = 0; ks < 4; ++ks) { const bf16x8 kf = *(const LAS bf16x8*)(Kt + (key_row0 + 16 * ct + fr) * AT_PITCH + 64 * ks + 16 * fq);
;             s[ct] = __builtin_amdgcn_mfma_f32_16x16x32_bf16(kf, qf[ks], s[ct], 0, 0, 0); if (ks == 3 && (ct & 1)) asm volatile("" ::: "memory"); }
; }
	v_mfma_f32_16x16x32_bf16 v[16:19], v[216:219], v[36:39], 0
	ds_read_b128 v[216:219], v141 offset:21952
	s_waitcnt lgkmcnt(15)
	v_mfma_f32_16x16x32_bf16 v[16:19], v[244:247], v[8:11], v[16:19]
	ds_read_b128 v[244:247], v141 offset:30528
	s_waitcnt lgkmcnt(10)
	v_mfma_f32_16x16x32_bf16 v[16:19], v[220:223], v[0:3], v[16:19]
	ds_read_b128 v[220:223], v141 offset:26112
	s_waitcnt lgkmcnt(10)
	v_mfma_f32_16x16x32_bf16 v[20:23], v[224:227], v[4:7], v[16:19]
	ds_read_b128 v[224:227], v141 offset:26176
	s_waitcnt lgkmcnt(9)
	v_mfma_f32_16x16x32_bf16 v[16:19], v[232:235], v[36:39], 0
	ds_read_b128 v[232:235], v141 offset:26240
	s_waitcnt lgkmcnt(11)
	v_mfma_f32_16x16x32_bf16 v[16:19], v[228:231], v[8:11], v[16:19]
	ds_read_b128 v[228:231], v141 offset:26304
	s_waitcnt lgkmcnt(9)
	v_mfma_f32_16x16x32_bf16 v[16:19], v[248:251], v[0:3], v[16:19]
	ds_read_b128 v[248:251], v141 offset:30464
	s_waitcnt lgkmcnt(9)
	v_mfma_f32_16x16x32_bf16 v[16:19], v[252:255], v[4:7], v[16:19]
	ds_read_b128 v[252:255], v141 offset:30592
	s_waitcnt lgkmcnt(9)
	v_mfma_f32_16x16x32_bf16 v[24:27], v[208:211], v[36:39], 0
	ds_read_b128 v[208:211], v141 offset:30656
	s_waitcnt lgkmcnt(13)
	v_mfma_f32_16x16x32_bf16 v[24:27], v[236:239], v[8:11], v[24:27]
	ds_read_b128 v[236:239], v141 offset:39232
	s_waitcnt lgkmcnt(10)
	v_mfma_f32_16x16x32_bf16 v[24:27], v[212:215], v[0:3], v[24:27]
	ds_read_b128 v[212:215], v141 offset:34816
	s_waitcnt lgkmcnt(10)
	v_mfma_f32_16x16x32_bf16 v[48:51], v[216:219], v[4:7], v[24:27]
	ds_read_b128 v[216:219], v141 offset:34880
	s_waitcnt lgkmcnt(9)
	v_mfma_f32_16x16x32_bf16 v[24:27], v[220:223], v[36:39], 0
	ds_read_b128 v[220:223], v141 offset:34944
	s_waitcnt lgkmcnt(9)
	v_mfma_f32_16x16x32_bf16 v[24:27], v[224:227], v[8:11], v[24:27]
	ds_read_b128 v[224:227], v141 offset:35008
	s_waitcnt lgkmcnt(9)
	v_mfma_f32_16x16x32_bf16 v[24:27], v[232:235], v[0:3], v[24:27]
	ds_read_b128 v[232:235], v141 offset:39168
	s_waitcnt lgkmcnt(9)
	v_mfma_f32_16x16x32_bf16 v[24:27], v[228:231], v[4:7], v[24:27]
	ds_read_b128 v[228:231], v141 offset:39296
	s_waitcnt lgkmcnt(9)
	v_mfma_f32_16x16x32_bf16 v[32:35], v[248:251], v[36:39], 0
	ds_read_b128 v[248:251], v141 offset:39360
	s_waitcnt lgkmcnt(15)
	v_mfma_f32_16x16x32_bf16 v[32:35], v[244:247], v[8:11], v[32:35]
	ds_read_b128 v[244:247], v141 offset:47936
	s_waitcnt lgkmcnt(10)
	v_mfma_f32_16x16x32_bf16 v[32:35], v[252:255], v[0:3], v[32:35]
	ds_read_b128 v[252:255], v141 offset:43520
	s_waitcnt lgkmcnt(10)
	v_mfma_f32_16x16x32_bf16 v[60:63], v[208:211], v[4:7], v[32:35]
	ds_read_b128 v[208:211], v141 offset:43584
	s_waitcnt lgkmcnt(9)
	v_mfma_f32_16x16x32_bf16 v[32:35], v[212:215], v[36:39], 0
	ds_read_b128 v[212:215], v141 offset:43648
	s_waitcnt lgkmcnt(9)
	v_mfma_f32_16x16x32_bf16 v[32:35], v[216:219], v[8:11], v[32:35]
	ds_read_b128 v[216:219], v141 offset:43712
	s_waitcnt lgkmcnt(9)
	v_mfma_f32_16x16x32_bf16 v[32:35], v[220:223], v[0:3], v[32:35]
	ds_read_b128 v[220:223], v141 offset:47872
	s_waitcnt lgkmcnt(9)
	v_mfma_f32_16x16x32_bf16 v[32:35], v[224:227], v[4:7], v[32:35]
	ds_read_b128 v[224:227], v141 offset:48000
	s_waitcnt lgkmcnt(9)
	v_mfma_f32_16x16x32_bf16 v[44:47], v[232:235], v[36:39], 0
	ds_read_b128 v[232:235], v141 offset:48064
	s_waitcnt lgkmcnt(15)
	v_mfma_f32_16x16x32_bf16 v[44:47], v[236:239], v[8:11], v[44:47]
	ds_read_b128 v[236:239], v141 offset:56640
	s_waitcnt lgkmcnt(10)
	v_mfma_f32_16x16x32_bf16 v[44:47], v[228:231], v[0:3], v[44:47]
	ds_read_b128 v[228:231], v141 offset:52224
	s_waitcnt lgkmcnt(10)
	v_mfma_f32_16x16x32_bf16 v[56:59], v[248:251], v[4:7], v[44:47]
	ds_read_b128 v[248:251], v141 offset:52288
	s_waitcnt lgkmcnt(9)
	v_mfma_f32_16x16x32_bf16 v[44:47], v[252:255], v[36:39], 0
	ds_read_b128 v[252:255], v141 offset:52352
	s_waitcnt lgkmcnt(9)
	v_mfma_f32_16x16x32_bf16 v[44:47], v[208:211], v[8:11], v[44:47]
	ds_read_b128 v[208:211], v141 offset:52416
	s_waitcnt lgkmcnt(9)
	v_mfma_f32_16x16x32_bf16 v[44:47], v[212:215], v[0:3], v[44:47]
	ds_read_b128 v[212:215], v141 offset:56576
	s_waitcnt lgkmcnt(9)
	v_mfma_f32_16x16x32_bf16 v[44:47], v[216:219], v[4:7], v[44:47]
	ds_read_b128 v[216:219], v141 offset:56704
	s_waitcnt lgkmcnt(9)
	v_mfma_f32_16x16x32_bf16 v[52:55], v[220:223], v[36:39], 0
	ds_read_b128 v[220:223], v141 offset:56768
	s_waitcnt lgkmcnt(15)
	v_mfma_f32_16x16x32_bf16 v[52:55], v[244:247], v[8:11], v[52:55]
	ds_read_b128 v[244:247], v141 offset:60992
	s_waitcnt lgkmcnt(10)
	v_mfma_f32_16x16x32_bf16 v[52:55], v[224:227], v[0:3], v[52:55]
	ds_read_b128 v[224:227], v141 offset:60928
	s_waitcnt lgkmcnt(10)
	v_mfma_f32_16x16x32_bf16 v[68:71], v[232:235], v[4:7], v[52:55]
	ds_read_b128 v[232:235], v141 offset:61056
	s_waitcnt lgkmcnt(9)
	v_mfma_f32_16x16x32_bf16 v[52:55], v[228:231], v[36:39], 0
	ds_read_b128 v[228:231], v141 offset:61120
	s_waitcnt lgkmcnt(9)
	v_mfma_f32_16x16x32_bf16 v[52:55], v[248:251], v[8:11], v[52:55]
	ds_read_b128 v[248:251], v141 offset:65280
	s_waitcnt lgkmcnt(9)
	v_mfma_f32_16x16x32_bf16 v[52:55], v[252:255], v[0:3], v[52:55]
	ds_read_b128 v[252:255], v141 offset:65344
	s_waitcnt lgkmcnt(9)
	v_mfma_f32_16x16x32_bf16 v[52:55], v[208:211], v[4:7], v[52:55]
	ds_read_b128 v[208:211], v141 offset:65408
	s_waitcnt lgkmcnt(9)
	v_mfma_f32_16x16x32_bf16 v[64:67], v[212:215], v[36:39], 0
	ds_read_b128 v[212:215], v141 offset:65472
	s_waitcnt lgkmcnt(15)
	v_mfma_f32_16x16x32_bf16 v[64:67], v[236:239], v[8:11], v[64:67]
	s_waitcnt lgkmcnt(9)
	v_mfma_f32_16x16x32_bf16 v[64:67], v[216:219], v[0:3], v[64:67]
	s_waitcnt lgkmcnt(8)
	v_mfma_f32_16x16x32_bf16 v[72:75], v[220:223], v[4:7], v[64:67]
	s_waitcnt lgkmcnt(6)
; __device__ __forceinline__ void attnC_item(const Frame& F, const Args& a, int item) {
;     ...
;     qk_accum<16>(s, R0, 0, qf, fr, fq);
; #pragma unroll
;     for (int ks = 0; ks < 4; ++ks) qf[ks] = *(const bf16x8*)(proj + qrow * NIN + C_QC + head * 256 + 128 + 32 * ks + 8 * fq);
;     qk_accum<16>(s, R1, 0, qf, fr, fq);
	v_mfma_f32_16x16x32_bf16 v[64:67], v[224:227], v[36:39], 0
	s_waitcnt lgkmcnt(7)
	v_mfma_f32_16x16x32_bf16 v[64:67], v[244:247], v[8:11], v[64:67]
	s_waitcnt lgkmcnt(5)
	v_mfma_f32_16x16x32_bf16 v[64:67], v[232:235], v[0:3], v[64:67]
	s_waitcnt lgkmcnt(4)
	v_mfma_f32_16x16x32_bf16 v[64:67], v[228:231], v[4:7], v[64:67]
	s_waitcnt lgkmcnt(3)
	v_mfma_f32_16x16x32_bf16 v[36:39], v[248:251], v[36:39], 0
	s_waitcnt lgkmcnt(2)
	v_mfma_f32_16x16x32_bf16 v[8:11], v[252:255], v[8:11], v[36:39]
	s_waitcnt lgkmcnt(1)
	v_mfma_f32_16x16x32_bf16 v[0:3], v[208:211], v[0:3], v[8:11]
	s_waitcnt lgkmcnt(0)
	v_mfma_f32_16x16x32_bf16 v[88:91], v[212:215], v[4:7], v[0:3]
	s_nop 2
	v_lshl_add_u64 v[0:1], v[76:77], 0, s[6:7]
	global_load_dwordx4 v[92:95], v[78:79], off offset:3328
	global_load_dwordx4 v[84:87], v[0:1], off offset:64
	global_load_dwordx4 v[80:83], v[0:1], off offset:128
	s_nop 0
	global_load_dwordx4 v[76:79], v[0:1], off offset:192
	ds_read_b128 v[208:211], v142
	ds_read_b128 v[212:215], v142 offset:64
	ds_read_b128 v[216:219], v142 offset:4416
	ds_read_b128 v[220:223], v142 offset:128
	ds_read_b128 v[224:227], v142 offset:192
	ds_read_b128 v[228:231], v142 offset:4352
	ds_read_b128 v[232:235], v142 offset:4480
	ds_read_b128 v[236:239], v142 offset:4544
	ds_read_b128 v[244:247], v142 offset:8704
	ds_read_b128 v[248:251], v142 offset:8768
	ds_read_b128 v[252:255], v142 offset:8832
	s_waitcnt vmcnt(0)
	s_waitcnt lgkmcnt(10)
	v_mfma_f32_16x16x32_bf16 v[0:3], v[208:211], v[92:95], v[40:43]
	ds_read_b128 v[208:211], v142 offset:8896
	s_waitcnt lgkmcnt(10)
	v_mfma_f32_16x16x32_bf16 v[0:3], v[212:215], v[84:87], v[0:3]
	ds_read_b128 v[212:215], v142 offset:13056
	s_waitcnt lgkmcnt(9)
	v_mfma_f32_16x16x32_bf16 v[0:3], v[220:223], v[80:83], v[0:3]
	ds_read_b128 v[220:223], v142 offset:13120
	s_waitcnt lgkmcnt(9)
	v_mfma_f32_16x16x32_bf16 v[0:3], v[224:227], v[76:79], v[0:3]
	ds_read_b128 v[224:227], v142 offset:13184
	s_waitcnt lgkmcnt(9)
	v_mfma_f32_16x16x32_bf16 v[4:7], v[228:231], v[92:95], v[28:31]
	ds_read_b128 v[228:231], v142 offset:13248
	s_waitcnt lgkmcnt(13)
	v_mfma_f32_16x16x32_bf16 v[4:7], v[216:219], v[84:87], v[4:7]
	ds_read_b128 v[216:219], v142 offset:21824
	s_waitcnt lgkmcnt(10)
	v_mfma_f32_16x16x32_bf16 v[4:7], v[232:235], v[80:83], v[4:7]
	ds_read_b128 v[232:235], v142 offset:17408
	s_waitcnt lgkmcnt(10)
	v_mfma_f32_16x16x32_bf16 v[4:7], v[236:239], v[76:79], v[4:7]
	ds_read_b128 v[236:239], v142 offset:17472
	s_waitcnt lgkmcnt(10)
	v_mfma_f32_16x16x32_bf16 v[8:11], v[244:247], v[92:95], v[12:15]
	ds_read_b128 v[244:247], v142 offset:17536
	s_waitcnt lgkmcnt(10)
	v_mfma_f32_16x16x32_bf16 v[8:11], v[248:251], v[84:87], v[8:11]
	ds_read_b128 v[248:251], v142 offset:17600
	s_waitcnt lgkmcnt(10)
	v_mfma_f32_16x16x32_bf16 v[8:11], v[252:255], v[80:83], v[8:11]
	ds_read_b128 v[252:255], v142 offset:21760
	s_waitcnt lgkmcnt(10)
	v_mfma_f32_16x16x32_bf16 v[8:11], v[208:211], v[76:79], v[8:11]
	ds_read_b128 v[208:211], v142 offset:21888
	s_waitcnt lgkmcnt(10)
	v_mfma_f32_16x16x32_bf16 v[12:15], v[212:215], v[92:95], v[20:23]
	ds_read_b128 v[212:215], v142 offset:21952
	s_waitcnt lgkmcnt(10)
	v_mfma_f32_16x16x32_bf16 v[12:15], v[220:223], v[84:87], v[12:15]
	ds_read_b128 v[220:223], v142 offset:30528
	s_waitcnt lgkmcnt(10)
	v_mfma_f32_16x16x32_bf16 v[12:15], v[224:227], v[80:83], v[12:15]
	ds_read_b128 v[224:227], v142 offset:26112
	s_waitcnt lgkmcnt(10)
	v_mfma_f32_16x16x32_bf16 v[12:15], v[228:231], v[76:79], v[12:15]
	ds_read_b128 v[228:231], v142 offset:26176
	s_waitcnt lgkmcnt(9)
	v_mfma_f32_16x16x32_bf16 v[16:19], v[232:235], v[92:95], v[16:19]
	ds_read_b128 v[232:235], v142 offset:26240
	s_waitcnt lgkmcnt(9)
	v_mfma_f32_16x16x32_bf16 v[16:19], v[236:239], v[84:87], v[16:19]
	ds_read_b128 v[236:239], v142 offset:26304
	s_waitcnt lgkmcnt(9)
	v_mfma_f32_16x16x32_bf16 v[16:19], v[244:247], v[80:83], v[16:19]
	ds_read_b128 v[244:247], v142 offset:30464
	s_waitcnt lgkmcnt(9)
	v_mfma_f32_16x16x32_bf16 v[16:19], v[248:251], v[76:79], v[16:19]
	ds_read_b128 v[248:251], v142 offset:30592
	s_waitcnt lgkmcnt(9)
	v_mfma_f32_16x16x32_bf16 v[20:23], v[252:255], v[92:95], v[48:51]
	ds_read_b128 v[252:255], v142 offset:30656
	s_waitcnt lgkmcnt(15)
	v_mfma_f32_16x16x32_bf16 v[20:23], v[216:219], v[84:87], v[20:23]
	ds_read_b128 v[216:219], v142 offset:39232
	s_waitcnt lgkmcnt(10)
	v_mfma_f32_16x16x32_bf16 v[20:23], v[208:211], v[80:83], v[20:23]
	ds_read_b128 v[208:211], v142 offset:34816
	s_waitcnt lgkmcnt(10)
	v_mfma_f32_16x16x32_bf16 v[20:23], v[212:215], v[76:79], v[20:23]
	ds_read_b128 v[212:215], v142 offset:34880
	s_waitcnt lgkmcnt(9)
	v_mfma_f32_16x16x32_bf16 v[24:27], v[224:227], v[92:95], v[24:27]
	ds_read_b128 v[224:227], v142 offset:34944
	s_waitcnt lgkmcnt(9)
	v_mfma_f32_16x16x32_bf16 v[24:27], v[228:231], v[84:87], v[24:27]
	ds_read_b128 v[228:231], v142 offset:35008
	s_waitcnt lgkmcnt(9)
	v_mfma_f32_16x16x32_bf16 v[24:27], v[232:235], v[80:83], v[24:27]
	ds_read_b128 v[232:235], v142 offset:39168
	s_waitcnt lgkmcnt(9)
	v_mfma_f32_16x16x32_bf16 v[24:27], v[236:239], v[76:79], v[24:27]
	ds_read_b128 v[236:239], v142 offset:39296
	s_waitcnt lgkmcnt(9)
	v_mfma_f32_16x16x32_bf16 v[28:31], v[244:247], v[92:95], v[60:63]
	ds_read_b128 v[244:247], v142 offset:39360
	s_waitcnt lgkmcnt(15)
	v_mfma_f32_16x16x32_bf16 v[28:31], v[220:223], v[84:87], v[28:31]
	ds_read_b128 v[220:223], v142 offset:47936
	s_waitcnt lgkmcnt(10)
	v_mfma_f32_16x16x32_bf16 v[28:31], v[248:251], v[80:83], v[28:31]
	ds_read_b128 v[248:251], v142 offset:43520
	s_waitcnt lgkmcnt(10)
	v_mfma_f32_16x16x32_bf16 v[28:31], v[252:255], v[76:79], v[28:31]
	ds_read_b128 v[252:255], v142 offset:43584
	s_waitcnt lgkmcnt(9)
; __device__ __forceinline__ void attnC_item(const Frame& F, const Args& a, int item) {
;     ...
;     qk_accum<16>(s, R1, 0, qf, fr, fq);
;     float mx = -3.0e38f;
; #pragma unroll
;     for (int ct = 0; ct < 16; ++ct)
; #pragma unroll
;         for (int j = 0; j < 4; ++j) { const float l = s[ct][j] * 0.0625f; s[ct][j] = l; mx = fmaxf(mx, l); }
	v_mfma_f32_16x16x32_bf16 v[32:35], v[208:211], v[92:95], v[32:35]
	ds_read_b128 v[208:211], v142 offset:43648
	s_waitcnt lgkmcnt(9)
	v_mfma_f32_16x16x32_bf16 v[32:35], v[212:215], v[84:87], v[32:35]
	ds_read_b128 v[212:215], v142 offset:43712
	s_waitcnt lgkmcnt(9)
	v_mfma_f32_16x16x32_bf16 v[32:35], v[224:227], v[80:83], v[32:35]
	ds_read_b128 v[224:227], v142 offset:47872
	s_waitcnt lgkmcnt(9)
	v_mfma_f32_16x16x32_bf16 v[32:35], v[228:231], v[76:79], v[32:35]
	ds_read_b128 v[228:231], v142 offset:48000
	s_waitcnt lgkmcnt(9)
	v_mfma_f32_16x16x32_bf16 v[36:39], v[232:235], v[92:95], v[56:59]
	ds_read_b128 v[232:235], v142 offset:48064
	s_waitcnt lgkmcnt(15)
	v_mfma_f32_16x16x32_bf16 v[36:39], v[216:219], v[84:87], v[36:39]
	ds_read_b128 v[216:219], v142 offset:56640
	s_waitcnt lgkmcnt(10)
	v_mfma_f32_16x16x32_bf16 v[36:39], v[236:239], v[80:83], v[36:39]
	ds_read_b128 v[236:239], v142 offset:52224
	s_waitcnt lgkmcnt(10)
	v_mfma_f32_16x16x32_bf16 v[40:43], v[244:247], v[76:79], v[36:39]
	ds_read_b128 v[244:247], v142 offset:52288
	s_waitcnt lgkmcnt(9)
	v_mfma_f32_16x16x32_bf16 v[36:39], v[248:251], v[92:95], v[44:47]
	ds_read_b128 v[248:251], v142 offset:52352
	s_waitcnt lgkmcnt(9)
	v_mfma_f32_16x16x32_bf16 v[36:39], v[252:255], v[84:87], v[36:39]
	ds_read_b128 v[252:255], v142 offset:52416
	s_waitcnt lgkmcnt(9)
	v_mfma_f32_16x16x32_bf16 v[36:39], v[208:211], v[80:83], v[36:39]
	ds_read_b128 v[208:211], v142 offset:56576
	s_waitcnt lgkmcnt(9)
	v_mfma_f32_16x16x32_bf16 v[36:39], v[212:215], v[76:79], v[36:39]
	ds_read_b128 v[212:215], v142 offset:56704
	s_waitcnt lgkmcnt(9)
	v_mfma_f32_16x16x32_bf16 v[44:47], v[224:227], v[92:95], v[68:71]
	ds_read_b128 v[224:227], v142 offset:56768
	s_waitcnt lgkmcnt(15)
	v_mfma_f32_16x16x32_bf16 v[44:47], v[220:223], v[84:87], v[44:47]
	ds_read_b128 v[220:223], v142 offset:60992
	s_waitcnt lgkmcnt(10)
	v_mfma_f32_16x16x32_bf16 v[44:47], v[228:231], v[80:83], v[44:47]
	ds_read_b128 v[228:231], v142 offset:60928
	s_waitcnt lgkmcnt(10)
	v_mfma_f32_16x16x32_bf16 v[48:51], v[232:235], v[76:79], v[44:47]
	ds_read_b128 v[232:235], v142 offset:65344
	s_waitcnt lgkmcnt(9)
	v_mfma_f32_16x16x32_bf16 v[44:47], v[236:239], v[92:95], v[52:55]
	ds_read_b128 v[236:239], v142 offset:61056
	s_waitcnt lgkmcnt(9)
	v_mfma_f32_16x16x32_bf16 v[44:47], v[244:247], v[84:87], v[44:47]
	ds_read_b128 v[244:247], v142 offset:61120
	s_waitcnt lgkmcnt(9)
	v_mfma_f32_16x16x32_bf16 v[44:47], v[248:251], v[80:83], v[44:47]
	ds_read_b128 v[248:251], v142 offset:65280
	s_waitcnt lgkmcnt(9)
	v_mfma_f32_16x16x32_bf16 v[44:47], v[252:255], v[76:79], v[44:47]
	ds_read_b128 v[252:255], v142 offset:65408
	s_waitcnt lgkmcnt(9)
	v_mfma_f32_16x16x32_bf16 v[52:55], v[208:211], v[92:95], v[72:75]
	ds_read_b128 v[208:211], v142 offset:65472
	s_waitcnt lgkmcnt(15)
	v_mfma_f32_16x16x32_bf16 v[52:55], v[216:219], v[84:87], v[52:55]
	s_waitcnt lgkmcnt(9)
	v_mfma_f32_16x16x32_bf16 v[52:55], v[212:215], v[80:83], v[52:55]
	s_waitcnt lgkmcnt(8)
	v_mfma_f32_16x16x32_bf16 v[56:59], v[224:227], v[76:79], v[52:55]
	s_waitcnt lgkmcnt(6)
	v_mfma_f32_16x16x32_bf16 v[52:55], v[228:231], v[92:95], v[64:67]
	s_waitcnt lgkmcnt(7)
	v_mfma_f32_16x16x32_bf16 v[52:55], v[220:223], v[84:87], v[52:55]
	s_waitcnt lgkmcnt(4)
	v_mfma_f32_16x16x32_bf16 v[52:55], v[236:239], v[80:83], v[52:55]
	s_waitcnt lgkmcnt(3)
	v_mfma_f32_16x16x32_bf16 v[52:55], v[244:247], v[76:79], v[52:55]
	s_waitcnt lgkmcnt(2)
	v_mfma_f32_16x16x32_bf16 v[60:63], v[248:251], v[92:95], v[88:91]
	s_waitcnt lgkmcnt(5)
	v_mfma_f32_16x16x32_bf16 v[60:63], v[232:235], v[84:87], v[60:63]
	s_waitcnt lgkmcnt(1)
	v_mfma_f32_16x16x32_bf16 v[60:63], v[252:255], v[80:83], v[60:63]
	s_waitcnt lgkmcnt(0)
	v_mfma_f32_16x16x32_bf16 v[60:63], v[208:211], v[76:79], v[60:63]
	v_mul_f32_e32 v64, 0x3d800000, v0
	v_mul_f32_e32 v65, 0x3d800000, v1
	v_max3_f32 v64, v64, s17, v65
	v_mul_f32_e32 v65, 0x3d800000, v2
	v_mul_f32_e32 v66, 0x3d800000, v3
	v_max3_f32 v64, v64, v65, v66
	v_mul_f32_e32 v65, 0x3d800000, v4
	v_mul_f32_e32 v66, 0x3d800000, v5
	v_max3_f32 v64, v64, v65, v66
	v_mul_f32_e32 v65, 0x3d800000, v6
	v_mul_f32_e32 v66, 0x3d800000, v7
	v_max3_f32 v64, v64, v65, v66
	v_mul_f32_e32 v65, 0x3d800000, v8
	v_mul_f32_e32 v66, 0x3d800000, v9
	v_max3_f32 v64, v64, v65, v66
	v_mul_f32_e32 v65, 0x3d800000, v10
	v_mul_f32_e32 v66, 0x3d800000, v11
	v_max3_f32 v64, v64, v65, v66
	v_mul_f32_e32 v65, 0x3d800000, v12
	v_mul_f32_e32 v66, 0x3d800000, v13
	v_max3_f32 v64, v64, v65, v66
	v_mul_f32_e32 v65, 0x3d800000, v14
	v_mul_f32_e32 v66, 0x3d800000, v15
	v_max3_f32 v64, v64, v65, v66
	v_mul_f32_e32 v65, 0x3d800000, v16
	v_mul_f32_e32 v66, 0x3d800000, v17
	v_max3_f32 v64, v64, v65, v66
	v_mul_f32_e32 v65, 0x3d800000, v18
	v_mul_f32_e32 v66, 0x3d800000, v19
	v_max3_f32 v64, v64, v65, v66
	v_mul_f32_e32 v65, 0x3d800000, v20
	v_mul_f32_e32 v66, 0x3d800000, v21
	v_max3_f32 v64, v64, v65, v66
	v_mul_f32_e32 v65, 0x3d800000, v22
	v_mul_f32_e32 v66, 0x3d800000, v23
	v_max3_f32 v64, v64, v65, v66
	v_mul_f32_e32 v65, 0x3d800000, v24
	v_mul_f32_e32 v66, 0x3d800000, v25
	v_max3_f32 v64, v64, v65, v66
	v_mul_f32_e32 v65, 0x3d800000, v26
	v_mul_f32_e32 v66, 0x3d800000, v27
	v_max3_f32 v64, v64, v65, v66
	v_mul_f32_e32 v65, 0x3d800000, v28
	v_mul_f32_e32 v66, 0x3d800000, v29
	v_max3_f32 v64, v64, v65, v66
	v_mul_f32_e32 v65, 0x3d800000, v30
	v_mul_f32_e32 v66, 0x3d800000, v31
	v_max3_f32 v64, v64, v65, v66
	v_mul_f32_e32 v65, 0x3d800000, v32
	v_mul_f32_e32 v66, 0x3d800000, v33
	v_max3_f32 v64, v64, v65, v66
	v_mul_f32_e32 v65, 0x3d800000, v34
	v_mul_f32_e32 v66, 0x3d800000, v35
	v_max3_f32 v64, v64, v65, v66
	v_mul_f32_e32 v65, 0x3d800000, v40
; __device__ __forceinline__ void attnC_item(const Frame& F, const Args& a, int item) {
;     ...
;     float mx = -3.0e38f;
; #pragma unroll
;     for (int ct = 0; ct < 16; ++ct)
; #pragma unroll
;         for (int j = 0; j < 4; ++j) { const float l = s[ct][j] * 0.0625f; s[ct][j] = l; mx = fmaxf(mx, l); }
;     mx = fmaxf(mx, __shfl_xor(mx, 16)); mx = fmaxf(mx, __shfl_xor(mx, 32));
;     float sum = 0.f;
; #pragma unroll
;     for (int ct = 0; ct < 16; ++ct)
; #pragma unroll
;         for (int j = 0; j < 4; ++j) { const float p = __expf(s[ct][j] - mx); s[ct][j] = p; sum += p; }
;     sum += __shfl_xor(sum, 16); sum += __shfl_xor(sum, 32);
	v_mul_f32_e32 v66, 0x3d800000, v41
	v_max3_f32 v64, v64, v65, v66
	v_mul_f32_e32 v65, 0x3d800000, v42
	v_mul_f32_e32 v66, 0x3d800000, v43
	v_max3_f32 v64, v64, v65, v66
	v_mul_f32_e32 v65, 0x3d800000, v36
	v_mul_f32_e32 v66, 0x3d800000, v37
	v_max3_f32 v64, v64, v65, v66
	v_mul_f32_e32 v65, 0x3d800000, v38
	v_mul_f32_e32 v66, 0x3d800000, v39
	v_max3_f32 v64, v64, v65, v66
	v_mul_f32_e32 v65, 0x3d800000, v48
	v_mul_f32_e32 v66, 0x3d800000, v49
	v_max3_f32 v64, v64, v65, v66
	v_mul_f32_e32 v65, 0x3d800000, v50
	v_mul_f32_e32 v66, 0x3d800000, v51
	v_max3_f32 v64, v64, v65, v66
	v_mul_f32_e32 v65, 0x3d800000, v44
	v_mul_f32_e32 v66, 0x3d800000, v45
	v_max3_f32 v64, v64, v65, v66
	v_mul_f32_e32 v65, 0x3d800000, v46
	v_mul_f32_e32 v66, 0x3d800000, v47
	v_max3_f32 v64, v64, v65, v66
	v_mul_f32_e32 v65, 0x3d800000, v56
	v_mul_f32_e32 v66, 0x3d800000, v57
	v_max3_f32 v64, v64, v65, v66
	v_mul_f32_e32 v65, 0x3d800000, v58
	v_mul_f32_e32 v66, 0x3d800000, v59
	v_max3_f32 v64, v64, v65, v66
	v_mul_f32_e32 v65, 0x3d800000, v52
	v_mul_f32_e32 v66, 0x3d800000, v53
	v_max3_f32 v64, v64, v65, v66
	v_mul_f32_e32 v65, 0x3d800000, v54
	v_mul_f32_e32 v66, 0x3d800000, v55
	v_max3_f32 v64, v64, v65, v66
	v_mul_f32_e32 v65, 0x3d800000, v60
	v_mul_f32_e32 v66, 0x3d800000, v61
	v_max3_f32 v64, v64, v65, v66
	v_mul_f32_e32 v65, 0x3d800000, v62
	v_mul_f32_e32 v66, 0x3d800000, v63
	v_max3_f32 v64, v64, v65, v66
	v_and_b32_e32 v65, 64, v159
	v_add_u32_e32 v65, 64, v65
	v_cmp_lt_i32_e32 vcc, v160, v65
	s_nop 1
	v_cndmask_b32_e32 v66, v159, v160, vcc
	v_lshlrev_b32_e32 v66, 2, v66
	ds_bpermute_b32 v67, v66, v64
	s_waitcnt lgkmcnt(0)
	v_max_f32_e32 v67, v67, v67
	v_max_f32_e32 v64, v64, v67
	v_xor_b32_e32 v67, 32, v159
	v_cmp_lt_i32_e32 vcc, v67, v65
	s_nop 1
	v_cndmask_b32_e32 v65, v159, v67, vcc
	v_lshlrev_b32_e32 v65, 2, v65
	ds_bpermute_b32 v67, v65, v64
	s_waitcnt lgkmcnt(0)
	v_max_f32_e32 v67, v67, v67
	v_max_f32_e32 v64, v64, v67
	s_mov_b32 s101, 0x3db8aa3b
	v_mul_f32_e32 v208, 0xbfb8aa3b, v64
	v_fma_f32 v0, v0, s101, v208
	v_exp_f32_e32 v0, v0
	v_fma_f32 v1, v1, s101, v208
	v_exp_f32_e32 v1, v1
	v_fma_f32 v2, v2, s101, v208
	v_exp_f32_e32 v2, v2
	v_fma_f32 v3, v3, s101, v208
	v_exp_f32_e32 v3, v3
	v_fma_f32 v4, v4, s101, v208
	v_add_f32_e32 v67, 0, v0
	v_exp_f32_e32 v4, v4
	v_fma_f32 v5, v5, s101, v208
	v_add_f32_e32 v67, v1, v67
	v_exp_f32_e32 v5, v5
	v_fma_f32 v6, v6, s101, v208
	v_add_f32_e32 v67, v2, v67
	v_exp_f32_e32 v6, v6
	v_fma_f32 v7, v7, s101, v208
	v_add_f32_e32 v67, v3, v67
	v_exp_f32_e32 v7, v7
	v_fma_f32 v8, v8, s101, v208
	v_add_f32_e32 v67, v4, v67
	v_exp_f32_e32 v8, v8
	v_fma_f32 v9, v9, s101, v208
	v_add_f32_e32 v67, v5, v67
	v_exp_f32_e32 v9, v9
	v_fma_f32 v10, v10, s101, v208
	v_add_f32_e32 v67, v6, v67
	v_exp_f32_e32 v10, v10
	v_fma_f32 v11, v11, s101, v208
	v_add_f32_e32 v67, v7, v67
	v_exp_f32_e32 v11, v11
	v_fma_f32 v12, v12, s101, v208
	v_add_f32_e32 v67, v8, v67
	v_exp_f32_e32 v12, v12
	v_fma_f32 v13, v13, s101, v208
	v_add_f32_e32 v67, v9, v67
	v_exp_f32_e32 v13, v13
	v_fma_f32 v14, v14, s101, v208
	v_add_f32_e32 v67, v10, v67
	v_exp_f32_e32 v14, v14
	v_fma_f32 v15, v15, s101, v208
	v_add_f32_e32 v67, v11, v67
	v_exp_f32_e32 v15, v15
	v_fma_f32 v16, v16, s101, v208
	v_add_f32_e32 v67, v12, v67
	v_exp_f32_e32 v16, v16
	v_fma_f32 v17, v17, s101, v208
	v_add_f32_e32 v67, v13, v67
	v_exp_f32_e32 v17, v17
	v_fma_f32 v18, v18, s101, v208
	v_add_f32_e32 v67, v14, v67
	v_exp_f32_e32 v18, v18
	v_fma_f32 v19, v19, s101, v208
	v_add_f32_e32 v67, v15, v67
	v_exp_f32_e32 v19, v19
	v_fma_f32 v20, v20, s101, v208
	v_add_f32_e32 v67, v16, v67
	v_exp_f32_e32 v68, v20
	v_add_f32_e32 v67, v17, v67
	v_add_f32_e32 v67, v18, v67
	v_add_f32_e32 v67, v19, v67
	v_fma_f32 v21, v21, s101, v208
	v_add_f32_e32 v20, v68, v67
	v_exp_f32_e32 v67, v21
	v_fma_f32 v21, v22, s101, v208
	v_exp_f32_e32 v69, v21
	v_fma_f32 v21, v23, s101, v208
	v_exp_f32_e32 v23, v21
	v_fma_f32 v21, v24, s101, v208
	v_exp_f32_e32 v70, v21
	v_fma_f32 v21, v25, s101, v208
	v_exp_f32_e32 v71, v21
	v_fma_f32 v21, v26, s101, v208
	v_exp_f32_e32 v72, v21
	v_fma_f32 v21, v27, s101, v208
	v_exp_f32_e32 v73, v21
	v_fma_f32 v21, v28, s101, v208
	v_exp_f32_e32 v74, v21
	v_fma_f32 v21, v29, s101, v208
	v_exp_f32_e32 v75, v21
	v_fma_f32 v21, v30, s101, v208
	v_exp_f32_e32 v76, v21
	v_fma_f32 v21, v31, s101, v208
	v_exp_f32_e32 v77, v21
	v_fma_f32 v21, v32, s101, v208
	v_exp_f32_e32 v32, v21
	v_fma_f32 v21, v33, s101, v208
	v_exp_f32_e32 v33, v21
	v_fma_f32 v21, v34, s101, v208
	v_exp_f32_e32 v34, v21
	v_fma_f32 v21, v35, s101, v208
	v_exp_f32_e32 v35, v21
	v_fma_f32 v21, v40, s101, v208
	v_exp_f32_e32 v40, v21
	v_fma_f32 v21, v41, s101, v208
	v_exp_f32_e32 v41, v21
	v_fma_f32 v21, v42, s101, v208
	v_exp_f32_e32 v42, v21
	v_fma_f32 v21, v43, s101, v208
	v_exp_f32_e32 v43, v21
	v_fma_f32 v21, v36, s101, v208
	v_exp_f32_e32 v36, v21
	v_fma_f32 v21, v37, s101, v208
	v_exp_f32_e32 v37, v21
	v_fma_f32 v21, v38, s101, v208
	v_exp_f32_e32 v38, v21
	v_fma_f32 v21, v39, s101, v208
	v_exp_f32_e32 v39, v21
	v_fma_f32 v21, v48, s101, v208
	v_add_f32_e32 v20, v67, v20
	v_exp_f32_e32 v48, v21
	v_add_f32_e32 v20, v69, v20
	v_fma_f32 v21, v49, s101, v208
	v_add_f32_e32 v20, v23, v20
	v_exp_f32_e32 v49, v21
	v_add_f32_e32 v20, v70, v20
	v_fma_f32 v21, v50, s101, v208
	v_add_f32_e32 v20, v71, v20
	v_exp_f32_e32 v50, v21
	v_add_f32_e32 v20, v72, v20
	v_fma_f32 v21, v51, s101, v208
	v_add_f32_e32 v20, v73, v20
	v_exp_f32_e32 v51, v21
	v_add_f32_e32 v20, v74, v20
	v_fma_f32 v21, v44, s101, v208
	v_add_f32_e32 v20, v75, v20
	v_exp_f32_e32 v44, v21
	v_add_f32_e32 v20, v76, v20
	v_fma_f32 v21, v45, s101, v208
; __device__ __forceinline__ unsigned cvt_pk_bf16(float lo, float hi) { unsigned r; asm volatile("v_cvt_pk_bf16_f32 %0, %1, %2" : "=v"(r) : "v"(lo), "v"(hi)); return r; }
; __device__ __forceinline__ void attnC_item(const Frame& F, const Args& a, int item) {
;     ...
;     float sum = 0.f;
; #pragma unroll
;     for (int ct = 0; ct < 16; ++ct)
; #pragma unroll
;         for (int j = 0; j < 4; ++j) { const float p = __expf(s[ct][j] - mx); s[ct][j] = p; sum += p; }
;     sum += __shfl_xor(sum, 16); sum += __shfl_xor(sum, 32);
;     bf16x8 pf[8];
; #pragma unroll
;     for (int ks = 0; ks < 8; ++ks) { u32x4 w; w.x = cvt_pk_bf16(s[2 * ks][0], s[2 * ks][1]); w.y = cvt_pk_bf16(s[2 * ks][2], s[2 * ks][3]);
;         w.z = cvt_pk_bf16(s[2 * ks + 1][0], s[2 * ks + 1][1]); w.w = cvt_pk_bf16(s[2 * ks + 1][2], s[2 * ks + 1][3]); pf[ks] = __builtin_bit_cast(bf16x8, w); }
;     __syncthreads();
;     STAGE_TILE2(R0, (kbase + (size_t)i * 2048 + 1024), R1, (kbase + (size_t)i * 2048 + 1024 + 128));
;     __syncthreads();
	v_add_f32_e32 v20, v77, v20
	v_exp_f32_e32 v45, v21
	v_add_f32_e32 v20, v32, v20
	v_fma_f32 v21, v46, s101, v208
	v_add_f32_e32 v20, v33, v20
	v_exp_f32_e32 v46, v21
	v_add_f32_e32 v20, v34, v20
	v_fma_f32 v21, v47, s101, v208
	v_add_f32_e32 v20, v35, v20
	v_exp_f32_e32 v47, v21
	v_add_f32_e32 v20, v40, v20
	v_fma_f32 v21, v56, s101, v208
	v_add_f32_e32 v20, v41, v20
	v_exp_f32_e32 v56, v21
	v_add_f32_e32 v20, v42, v20
	v_fma_f32 v21, v57, s101, v208
	v_add_f32_e32 v20, v43, v20
	v_exp_f32_e32 v57, v21
	v_add_f32_e32 v20, v36, v20
	v_fma_f32 v21, v58, s101, v208
	v_add_f32_e32 v20, v37, v20
	v_exp_f32_e32 v58, v21
	v_add_f32_e32 v20, v38, v20
	v_fma_f32 v21, v59, s101, v208
	v_add_f32_e32 v20, v39, v20
	v_exp_f32_e32 v59, v21
	v_add_f32_e32 v20, v48, v20
	v_fma_f32 v21, v52, s101, v208
	v_add_f32_e32 v20, v49, v20
	v_exp_f32_e32 v52, v21
	v_add_f32_e32 v20, v50, v20
	v_fma_f32 v21, v53, s101, v208
	v_add_f32_e32 v20, v51, v20
	v_exp_f32_e32 v53, v21
	v_add_f32_e32 v20, v44, v20
	v_fma_f32 v21, v54, s101, v208
	v_add_f32_e32 v20, v45, v20
	v_exp_f32_e32 v54, v21
	v_add_f32_e32 v20, v46, v20
	v_fma_f32 v21, v55, s101, v208
	v_add_f32_e32 v20, v47, v20
	v_exp_f32_e32 v55, v21
	v_add_f32_e32 v20, v56, v20
	v_fma_f32 v21, v60, s101, v208
	v_add_f32_e32 v20, v57, v20
	v_exp_f32_e32 v60, v21
	v_add_f32_e32 v20, v58, v20
	v_fma_f32 v21, v61, s101, v208
	v_add_f32_e32 v20, v59, v20
	v_exp_f32_e32 v61, v21
	v_add_f32_e32 v20, v52, v20
	v_fma_f32 v21, v62, s101, v208
	v_add_f32_e32 v20, v53, v20
	v_exp_f32_e32 v62, v21
	v_add_f32_e32 v20, v54, v20
	v_fma_f32 v21, v63, s101, v208
	v_add_f32_e32 v20, v55, v20
	v_exp_f32_e32 v63, v21
	v_add_f32_e32 v20, v60, v20
	v_add_f32_e32 v20, v61, v20
	v_add_f32_e32 v20, v62, v20
	v_add_f32_e32 v20, v63, v20
	ds_bpermute_b32 v21, v66, v20
	v_cvt_pk_bf16_f32 v28, v0, v1
	v_cvt_pk_bf16_f32 v29, v2, v3
	v_cvt_pk_bf16_f32 v30, v4, v5
	v_cvt_pk_bf16_f32 v31, v6, v7
	s_waitcnt lgkmcnt(0)
	v_add_f32_e32 v96, v20, v21
	ds_bpermute_b32 v119, v65, v96
	v_cvt_pk_bf16_f32 v24, v8, v9
	v_cvt_pk_bf16_f32 v25, v10, v11
	v_cvt_pk_bf16_f32 v26, v12, v13
	v_cvt_pk_bf16_f32 v27, v14, v15
	v_cvt_pk_bf16_f32 v20, v16, v17
	v_cvt_pk_bf16_f32 v21, v18, v19
	v_cvt_pk_bf16_f32 v22, v68, v67
	v_cvt_pk_bf16_f32 v23, v69, v23
	v_cvt_pk_bf16_f32 v16, v70, v71
	v_cvt_pk_bf16_f32 v17, v72, v73
	v_cvt_pk_bf16_f32 v18, v74, v75
	v_cvt_pk_bf16_f32 v19, v76, v77
	v_cvt_pk_bf16_f32 v12, v32, v33
	v_cvt_pk_bf16_f32 v13, v34, v35
	v_cvt_pk_bf16_f32 v14, v40, v41
	v_cvt_pk_bf16_f32 v15, v42, v43
	v_cvt_pk_bf16_f32 v8, v36, v37
	v_cvt_pk_bf16_f32 v9, v38, v39
	v_cvt_pk_bf16_f32 v10, v48, v49
	v_cvt_pk_bf16_f32 v11, v50, v51
	v_cvt_pk_bf16_f32 v4, v44, v45
	v_cvt_pk_bf16_f32 v5, v46, v47
	v_cvt_pk_bf16_f32 v6, v56, v57
	v_cvt_pk_bf16_f32 v7, v58, v59
	v_cvt_pk_bf16_f32 v0, v52, v53
	v_cvt_pk_bf16_f32 v1, v54, v55
	v_cvt_pk_bf16_f32 v2, v60, v61
	v_cvt_pk_bf16_f32 v3, v62, v63
	s_waitcnt lgkmcnt(0)
	s_barrier
	global_load_dwordx4 v[32:35], v[124:125], off offset:2048
	global_load_dwordx4 v[36:39], v[124:125], off offset:2304
	global_load_dwordx4 v[40:43], v[126:127], off offset:2048
	global_load_dwordx4 v[44:47], v[126:127], off offset:2304
	global_load_dwordx4 v[48:51], v[128:129], off offset:2048
	global_load_dwordx4 v[52:55], v[128:129], off offset:2304
	global_load_dwordx4 v[56:59], v[130:131], off offset:2048
	global_load_dwordx4 v[60:63], v[130:131], off offset:2304
	global_load_dwordx4 v[64:67], v[132:133], off offset:2048
	global_load_dwordx4 v[68:71], v[132:133], off offset:2304
	global_load_dwordx4 v[72:75], v[134:135], off offset:2048
	global_load_dwordx4 v[76:79], v[134:135], off offset:2304
	global_load_dwordx4 v[80:83], v[136:137], off offset:2048
	global_load_dwordx4 v[84:87], v[136:137], off offset:2304
	global_load_dwordx4 v[88:91], v[138:139], off offset:2048
	global_load_dwordx4 v[92:95], v[138:139], off offset:2304
	s_waitcnt vmcnt(15)
	ds_write_b128 v146, v[32:35]
	s_waitcnt vmcnt(14)
	ds_write_b128 v158, v[36:39]
	s_waitcnt vmcnt(13)
	ds_write_b128 v147, v[40:43]
	s_waitcnt vmcnt(12)
	ds_write_b128 v148, v[44:47]
	s_waitcnt vmcnt(11)
	ds_write_b128 v146, v[48:51] offset:17408
	s_waitcnt vmcnt(10)
	ds_write_b128 v149, v[52:55]
	s_waitcnt vmcnt(9)
	ds_write_b128 v150, v[56:59]
	s_waitcnt vmcnt(8)
	ds_write_b128 v151, v[60:63]
	s_waitcnt vmcnt(7)
	ds_write_b128 v146, v[64:67] offset:34816
	s_waitcnt vmcnt(6)
	ds_write_b128 v152, v[68:71]
	s_waitcnt vmcnt(5)
	ds_write_b128 v153, v[72:75]
	s_waitcnt vmcnt(4)
	ds_write_b128 v154, v[76:79]
	s_waitcnt vmcnt(3)
	ds_write_b128 v146, v[80:83] offset:52224
	s_waitcnt vmcnt(2)
	ds_write_b128 v155, v[84:87]
	s_waitcnt vmcnt(1)
	ds_write_b128 v156, v[88:91]
	s_waitcnt vmcnt(0)
	ds_write_b128 v157, v[92:95]
	v_add_f32_e32 v32, v96, v119
	v_div_scale_f32 v33, s[2:3], v32, v32, 1.0
	v_rcp_f32_e32 v34, v33
	v_mov_b32_e32 v119, v97
	s_waitcnt lgkmcnt(0)
	s_barrier
; __device__ __forceinline__ unsigned cvt_pk_bf16(float lo, float hi) { unsigned r; asm volatile("v_cvt_pk_bf16_f32 %0, %1, %2" : "=v"(r) : "v"(lo), "v"(hi)); return r; }
; __device__ __forceinline__ void attnC_item(const Frame& F, const Args& a, int item) {
;     ...
;     const float inv = 1.0f / sum;
;     bf16_t* orow = (bf16_t*)a.out + qrow * YP + 2048 + head * 256;
; #pragma unroll
;     for (int half = 0; half < 2; ++half) {
;         f32x4 o[8];
; #pragma unroll
;         for (int dt = 0; dt < 8; ++dt) o[dt] = (f32x4){0.f, 0.f, 0.f, 0.f};
;         pv_accum<8>(o, half ? R1 : R0, 0, pf, fr, fq);
; #pragma unroll
;         for (int dt = 0; dt < 8; ++dt) { u32x2 w; w.x = cvt_pk_bf16(o[dt][0] * inv, o[dt][1] * inv); w.y = cvt_pk_bf16(o[dt][2] * inv, o[dt][3] * inv); *(u32x2*)(orow + 128 * half + 16 * dt + 4 * fq) = w; }
	v_fma_f32 v35, -v33, v34, 1.0
	v_fmac_f32_e32 v34, v35, v34
	v_div_scale_f32 v35, vcc, 1.0, v32, 1.0
	v_mul_f32_e32 v36, v35, v34
	v_fma_f32 v37, -v33, v36, v35
	v_fmac_f32_e32 v36, v37, v34
	v_fma_f32 v33, -v33, v36, v35
	v_div_fmas_f32 v33, v33, v34, v36
	v_div_fixup_f32 v64, v33, v32, 1.0
	v_mov_b64_e32 v[32:33], s[20:21]
	v_mad_u64_u32 v[32:33], s[2:3], v122, s18, v[32:33]
	v_mad_i32_i24 v33, v123, s18, v33
	v_lshl_add_u64 v[32:33], v[32:33], 0, s[0:1]
	v_lshl_add_u64 v[62:63], v[32:33], 0, v[118:119]
	ds_read_b64_tr_b16 v[34:35], v143 offset:4352
	ds_read_b64_tr_b16 v[32:33], v143
	ds_read_b64_tr_b16 v[36:37], v143 offset:32
	ds_read_b64_tr_b16 v[38:39], v143 offset:4384
	ds_read_b64_tr_b16 v[40:41], v143 offset:64
	ds_read_b64_tr_b16 v[42:43], v143 offset:4416
	ds_read_b64_tr_b16 v[44:45], v143 offset:96
	ds_read_b64_tr_b16 v[46:47], v143 offset:4448
	ds_read_b64_tr_b16 v[48:49], v143 offset:128
	ds_read_b64_tr_b16 v[50:51], v143 offset:4480
	ds_read_b64_tr_b16 v[52:53], v143 offset:160
	ds_read_b64_tr_b16 v[54:55], v143 offset:4512
	ds_read_b64_tr_b16 v[56:57], v143 offset:192
	ds_read_b64_tr_b16 v[58:59], v143 offset:4544
	ds_read_b64_tr_b16 v[66:67], v143 offset:224
	ds_read_b64_tr_b16 v[68:69], v143 offset:4576
	s_waitcnt lgkmcnt(14)
	v_mfma_f32_16x16x32_bf16 v[32:35], v[32:35], v[28:31], 0
	ds_read_b64_tr_b16 v[72:73], v143 offset:13056
	ds_read_b64_tr_b16 v[70:71], v143 offset:8704
	ds_read_b64_tr_b16 v[74:75], v143 offset:8736
	ds_read_b64_tr_b16 v[76:77], v143 offset:13088
	v_lshl_add_u64 v[60:61], v[62:63], 0, s[8:9]
	s_waitcnt lgkmcnt(2)
	v_mfma_f32_16x16x32_bf16 v[32:35], v[70:73], v[24:27], v[32:35]
	ds_read_b64_tr_b16 v[70:71], v143 offset:8768
	ds_read_b64_tr_b16 v[72:73], v143 offset:13120
	v_add_co_u32_e32 v62, vcc, s19, v62
	v_mfma_f32_16x16x32_bf16 v[40:43], v[40:43], v[28:31], 0
	s_nop 0
	v_addc_co_u32_e32 v63, vcc, 0, v63, vcc
	s_waitcnt lgkmcnt(0)
	v_mfma_f32_16x16x32_bf16 v[40:43], v[70:73], v[24:27], v[40:43]
	ds_read_b64_tr_b16 v[70:71], v143 offset:8800
	ds_read_b64_tr_b16 v[72:73], v143 offset:13152
	v_mfma_f32_16x16x32_bf16 v[44:47], v[44:47], v[28:31], 0
	s_waitcnt lgkmcnt(0)
	v_mfma_f32_16x16x32_bf16 v[44:47], v[70:73], v[24:27], v[44:47]
	ds_read_b64_tr_b16 v[70:71], v143 offset:8832
	ds_read_b64_tr_b16 v[72:73], v143 offset:13184
	v_mfma_f32_16x16x32_bf16 v[48:51], v[48:51], v[28:31], 0
	s_waitcnt lgkmcnt(0)
	v_mfma_f32_16x16x32_bf16 v[48:51], v[70:73], v[24:27], v[48:51]
	ds_read_b64_tr_b16 v[70:71], v143 offset:8864
	ds_read_b64_tr_b16 v[72:73], v143 offset:13216
	v_mfma_f32_16x16x32_bf16 v[52:55], v[52:55], v[28:31], 0
	s_waitcnt lgkmcnt(0)
	v_mfma_f32_16x16x32_bf16 v[52:55], v[70:73], v[24:27], v[52:55]
	ds_read_b64_tr_b16 v[70:71], v143 offset:8896
	ds_read_b64_tr_b16 v[72:73], v143 offset:13248
	v_mfma_f32_16x16x32_bf16 v[56:59], v[56:59], v[28:31], 0
	s_waitcnt lgkmcnt(0)
	v_mfma_f32_16x16x32_bf16 v[56:59], v[70:73], v[24:27], v[56:59]
	ds_read_b64_tr_b16 v[70:71], v143 offset:8928
	ds_read_b64_tr_b16 v[72:73], v143 offset:13280
	v_mfma_f32_16x16x32_bf16 v[36:39], v[36:39], v[28:31], 0
	v_mfma_f32_16x16x32_bf16 v[66:69], v[66:69], v[28:31], 0
	v_mfma_f32_16x16x32_bf16 v[36:39], v[74:77], v[24:27], v[36:39]
	s_waitcnt lgkmcnt(0)
	v_mfma_f32_16x16x32_bf16 v[66:69], v[70:73], v[24:27], v[66:69]
	ds_read_b64_tr_b16 v[72:73], v143 offset:21760
	ds_read_b64_tr_b16 v[70:71], v143 offset:17408
	ds_read_b64_tr_b16 v[74:75], v143 offset:17440
	ds_read_b64_tr_b16 v[76:77], v143 offset:21792
	s_waitcnt lgkmcnt(2)
	v_mfma_f32_16x16x32_bf16 v[32:35], v[70:73], v[20:23], v[32:35]
	ds_read_b64_tr_b16 v[70:71], v143 offset:17472
	ds_read_b64_tr_b16 v[72:73], v143 offset:21824
	s_waitcnt lgkmcnt(0)
	v_mfma_f32_16x16x32_bf16 v[40:43], v[70:73], v[20:23], v[40:43]
	ds_read_b64_tr_b16 v[70:71], v143 offset:17504
	ds_read_b64_tr_b16 v[72:73], v143 offset:21856
	s_waitcnt lgkmcnt(0)
	v_mfma_f32_16x16x32_bf16 v[44:47], v[70:73], v[20:23], v[44:47]
	ds_read_b64_tr_b16 v[70:71], v143 offset:17536
	ds_read_b64_tr_b16 v[72:73], v143 offset:21888
	s_waitcnt lgkmcnt(0)
	v_mfma_f32_16x16x32_bf16 v[48:51], v[70:73], v[20:23], v[48:51]
	ds_read_b64_tr_b16 v[70:71], v143 offset:17568
	ds_read_b64_tr_b16 v[72:73], v143 offset:21920
	s_waitcnt lgkmcnt(0)
	v_mfma_f32_16x16x32_bf16 v[52:55], v[70:73], v[20:23], v[52:55]
	ds_read_b64_tr_b16 v[70:71], v143 offset:17600
	ds_read_b64_tr_b16 v[72:73], v143 offset:21952
	s_waitcnt lgkmcnt(0)
	v_mfma_f32_16x16x32_bf16 v[56:59], v[70:73], v[20:23], v[56:59]
	ds_read_b64_tr_b16 v[70:71], v143 offset:17632
	ds_read_b64_tr_b16 v[72:73], v143 offset:21984
	v_mfma_f32_16x16x32_bf16 v[36:39], v[74:77], v[20:23], v[36:39]
	s_waitcnt lgkmcnt(0)
	v_mfma_f32_16x16x32_bf16 v[66:69], v[70:73], v[20:23], v[66:69]
	ds_read_b64_tr_b16 v[72:73], v143 offset:30464
	ds_read_b64_tr_b16 v[70:71], v143 offset:26112
	ds_read_b64_tr_b16 v[74:75], v143 offset:26144
	ds_read_b64_tr_b16 v[76:77], v143 offset:30496
	s_waitcnt lgkmcnt(2)
	v_mfma_f32_16x16x32_bf16 v[32:35], v[70:73], v[16:19], v[32:35]
	ds_read_b64_tr_b16 v[70:71], v143 offset:26176
	ds_read_b64_tr_b16 v[72:73], v143 offset:30528
	s_waitcnt lgkmcnt(0)
	v_mfma_f32_16x16x32_bf16 v[40:43], v[70:73], v[16:19], v[40:43]
	ds_read_b64_tr_b16 v[70:71], v143 offset:26208
	ds_read_b64_tr_b16 v[72:73], v143 offset:30560
	s_waitcnt lgkmcnt(0)
	v_mfma_f32_16x16x32_bf16 v[44:47], v[70:73], v[16:19], v[44:47]
	ds_read_b64_tr_b16 v[70:71], v143 offset:26240
	ds_read_b64_tr_b16 v[72:73], v143 offset:30592
	s_waitcnt lgkmcnt(0)
	v_mfma_f32_16x16x32_bf16 v[48:51], v[70:73], v[16:19], v[48:51]
	ds_read_b64_tr_b16 v[70:71], v143 offset:26272
	ds_read_b64_tr_b16 v[72:73], v143 offset:30624
	s_waitcnt lgkmcnt(0)
; #define LAS __attribute__((address_space(3)))
; __device__ __forceinline__ unsigned cvt_pk_bf16(float lo, float hi) { unsigned r; asm volatile("v_cvt_pk_bf16_f32 %0, %1, %2" : "=v"(r) : "v"(lo), "v"(hi)); return r; }
; __device__ __forceinline__ s16x4 vtr(const LAS char* p) { return __builtin_bit_cast(s16x4, __builtin_amdgcn_ds_read_tr16_b64_v4i16((LAS s16x4*)p)); }
; template <int NKS>
; __device__ __forceinline__ void pv_accum(f32x4 (&o)[8], const LAS unsigned char* Vt, int key_row0, const bf16x8 (&pf)[NKS], int fr, int fq) {
; #pragma unroll
;     for (int ks = 0; ks < NKS; ++ks) {
;         const LAS char* p0 = (const LAS char*)Vt + (key_row0 + 32 * ks + 4 * fq + (fr >> 2)) * AT_PITCH + 8 * (fr & 3);
; #pragma unroll
;         for (int dt = 0; dt < 8; ++dt) { const s16x4 lo = vtr(p0 + 32 * dt), hi = vtr(p0 + 16 * AT_PITCH + 32 * dt);
;             const bf16x8 vf = {lo[0], lo[1], lo[2], lo[3], hi[0], hi[1], hi[2], hi[3]};
;             o[dt] = __builtin_amdgcn_mfma_f32_16x16x32_bf16(vf, pf[ks], o[dt], 0, 0, 0); }
;         asm volatile("" ::: "memory");
;     }
; }
; __device__ __forceinline__ void attnC_item(const Frame& F, const Args& a, int item) {
;     ...
;         for (int dt = 0; dt < 8; ++dt) { u32x2 w; w.x = cvt_pk_bf16(o[dt][0] * inv, o[dt][1] * inv); w.y = cvt_pk_bf16(o[dt][2] * inv, o[dt][3] * inv); *(u32x2*)(orow + 128 * half + 16 * dt + 4 * fq) = w; }
	v_mfma_f32_16x16x32_bf16 v[52:55], v[70:73], v[16:19], v[52:55]
	ds_read_b64_tr_b16 v[70:71], v143 offset:26304
	ds_read_b64_tr_b16 v[72:73], v143 offset:30656
	s_waitcnt lgkmcnt(0)
	v_mfma_f32_16x16x32_bf16 v[56:59], v[70:73], v[16:19], v[56:59]
	ds_read_b64_tr_b16 v[70:71], v143 offset:26336
	ds_read_b64_tr_b16 v[72:73], v143 offset:30688
	v_mfma_f32_16x16x32_bf16 v[36:39], v[74:77], v[16:19], v[36:39]
	s_waitcnt lgkmcnt(0)
	v_mfma_f32_16x16x32_bf16 v[66:69], v[70:73], v[16:19], v[66:69]
	ds_read_b64_tr_b16 v[72:73], v143 offset:39168
	ds_read_b64_tr_b16 v[70:71], v143 offset:34816
	ds_read_b64_tr_b16 v[74:75], v143 offset:34848
	ds_read_b64_tr_b16 v[76:77], v143 offset:39200
	s_waitcnt lgkmcnt(2)
	v_mfma_f32_16x16x32_bf16 v[32:35], v[70:73], v[12:15], v[32:35]
	ds_read_b64_tr_b16 v[70:71], v143 offset:34880
	ds_read_b64_tr_b16 v[72:73], v143 offset:39232
	s_waitcnt lgkmcnt(0)
	v_mfma_f32_16x16x32_bf16 v[40:43], v[70:73], v[12:15], v[40:43]
	ds_read_b64_tr_b16 v[70:71], v143 offset:34912
	ds_read_b64_tr_b16 v[72:73], v143 offset:39264
	s_waitcnt lgkmcnt(0)
	v_mfma_f32_16x16x32_bf16 v[44:47], v[70:73], v[12:15], v[44:47]
	ds_read_b64_tr_b16 v[70:71], v143 offset:34944
	ds_read_b64_tr_b16 v[72:73], v143 offset:39296
	s_waitcnt lgkmcnt(0)
	v_mfma_f32_16x16x32_bf16 v[48:51], v[70:73], v[12:15], v[48:51]
	ds_read_b64_tr_b16 v[70:71], v143 offset:34976
	ds_read_b64_tr_b16 v[72:73], v143 offset:39328
	s_waitcnt lgkmcnt(0)
	v_mfma_f32_16x16x32_bf16 v[52:55], v[70:73], v[12:15], v[52:55]
	ds_read_b64_tr_b16 v[70:71], v143 offset:35008
	ds_read_b64_tr_b16 v[72:73], v143 offset:39360
	s_waitcnt lgkmcnt(0)
	v_mfma_f32_16x16x32_bf16 v[56:59], v[70:73], v[12:15], v[56:59]
	ds_read_b64_tr_b16 v[70:71], v143 offset:35040
	ds_read_b64_tr_b16 v[72:73], v143 offset:39392
	v_mfma_f32_16x16x32_bf16 v[36:39], v[74:77], v[12:15], v[36:39]
	s_waitcnt lgkmcnt(0)
	v_mfma_f32_16x16x32_bf16 v[66:69], v[70:73], v[12:15], v[66:69]
	ds_read_b64_tr_b16 v[72:73], v143 offset:47872
	ds_read_b64_tr_b16 v[70:71], v143 offset:43520
	ds_read_b64_tr_b16 v[74:75], v143 offset:43552
	ds_read_b64_tr_b16 v[76:77], v143 offset:47904
	s_waitcnt lgkmcnt(2)
	v_mfma_f32_16x16x32_bf16 v[32:35], v[70:73], v[8:11], v[32:35]
	ds_read_b64_tr_b16 v[70:71], v143 offset:43584
	ds_read_b64_tr_b16 v[72:73], v143 offset:47936
	s_waitcnt lgkmcnt(0)
	v_mfma_f32_16x16x32_bf16 v[40:43], v[70:73], v[8:11], v[40:43]
	ds_read_b64_tr_b16 v[70:71], v143 offset:43616
	ds_read_b64_tr_b16 v[72:73], v143 offset:47968
	s_waitcnt lgkmcnt(0)
	v_mfma_f32_16x16x32_bf16 v[44:47], v[70:73], v[8:11], v[44:47]
	ds_read_b64_tr_b16 v[70:71], v143 offset:43648
	ds_read_b64_tr_b16 v[72:73], v143 offset:48000
	s_waitcnt lgkmcnt(0)
	v_mfma_f32_16x16x32_bf16 v[48:51], v[70:73], v[8:11], v[48:51]
	ds_read_b64_tr_b16 v[70:71], v143 offset:43680
	ds_read_b64_tr_b16 v[72:73], v143 offset:48032
	s_waitcnt lgkmcnt(0)
	v_mfma_f32_16x16x32_bf16 v[52:55], v[70:73], v[8:11], v[52:55]
	ds_read_b64_tr_b16 v[70:71], v143 offset:43712
	ds_read_b64_tr_b16 v[72:73], v143 offset:48064
	s_waitcnt lgkmcnt(0)
	v_mfma_f32_16x16x32_bf16 v[56:59], v[70:73], v[8:11], v[56:59]
	ds_read_b64_tr_b16 v[70:71], v143 offset:43744
	ds_read_b64_tr_b16 v[72:73], v143 offset:48096
	v_mfma_f32_16x16x32_bf16 v[36:39], v[74:77], v[8:11], v[36:39]
	s_waitcnt lgkmcnt(0)
	v_mfma_f32_16x16x32_bf16 v[66:69], v[70:73], v[8:11], v[66:69]
	ds_read_b64_tr_b16 v[72:73], v143 offset:56576
	ds_read_b64_tr_b16 v[70:71], v143 offset:52224
	ds_read_b64_tr_b16 v[74:75], v143 offset:52256
	ds_read_b64_tr_b16 v[76:77], v143 offset:56608
	s_waitcnt lgkmcnt(2)
	v_mfma_f32_16x16x32_bf16 v[32:35], v[70:73], v[4:7], v[32:35]
	ds_read_b64_tr_b16 v[70:71], v143 offset:52288
	ds_read_b64_tr_b16 v[72:73], v143 offset:56640
	s_waitcnt lgkmcnt(0)
	v_mfma_f32_16x16x32_bf16 v[40:43], v[70:73], v[4:7], v[40:43]
	ds_read_b64_tr_b16 v[70:71], v143 offset:52320
	ds_read_b64_tr_b16 v[72:73], v143 offset:56672
	s_waitcnt lgkmcnt(0)
	v_mfma_f32_16x16x32_bf16 v[44:47], v[70:73], v[4:7], v[44:47]
	ds_read_b64_tr_b16 v[70:71], v143 offset:52352
	ds_read_b64_tr_b16 v[72:73], v143 offset:56704
	s_waitcnt lgkmcnt(0)
	v_mfma_f32_16x16x32_bf16 v[70:73], v[70:73], v[4:7], v[48:51]
	s_nop 2
	ds_read_b64_tr_b16 v[48:49], v143 offset:52384
	ds_read_b64_tr_b16 v[50:51], v143 offset:56736
	v_mfma_f32_16x16x32_bf16 v[36:39], v[74:77], v[4:7], v[36:39]
	s_waitcnt lgkmcnt(0)
	v_mfma_f32_16x16x32_bf16 v[74:77], v[48:51], v[4:7], v[52:55]
	ds_read_b64_tr_b16 v[48:49], v143 offset:52416
	ds_read_b64_tr_b16 v[50:51], v143 offset:56768
	s_waitcnt lgkmcnt(0)
	v_mfma_f32_16x16x32_bf16 v[78:81], v[48:51], v[4:7], v[56:59]
	ds_read_b64_tr_b16 v[48:49], v143 offset:52448
	ds_read_b64_tr_b16 v[50:51], v143 offset:56800
	s_waitcnt lgkmcnt(0)
	v_mfma_f32_16x16x32_bf16 v[66:69], v[48:51], v[4:7], v[66:69]
	ds_read_b64_tr_b16 v[50:51], v143 offset:65280
	ds_read_b64_tr_b16 v[48:49], v143 offset:60928
	ds_read_b64_tr_b16 v[52:53], v143 offset:60960
	ds_read_b64_tr_b16 v[54:55], v143 offset:65312
	s_waitcnt lgkmcnt(2)
	v_mfma_f32_16x16x32_bf16 v[82:85], v[48:51], v[0:3], v[32:35]
	s_nop 2
	ds_read_b64_tr_b16 v[32:33], v143 offset:60992
	ds_read_b64_tr_b16 v[34:35], v143 offset:65344
	s_nop 2
	v_mul_f32_e32 v65, v64, v82
	s_waitcnt lgkmcnt(2)
	v_mfma_f32_16x16x32_bf16 v[56:59], v[52:55], v[0:3], v[36:39]
	s_waitcnt lgkmcnt(0)
	v_mfma_f32_16x16x32_bf16 v[52:55], v[32:35], v[0:3], v[40:43]
	ds_read_b64_tr_b16 v[32:33], v143 offset:61024
	ds_read_b64_tr_b16 v[34:35], v143 offset:65376
	s_nop 3
	v_mul_f32_e32 v56, v64, v56
	v_mul_f32_e32 v57, v64, v57
	s_waitcnt lgkmcnt(0)
; #define LAS __attribute__((address_space(3)))
; __device__ __forceinline__ unsigned cvt_pk_bf16(float lo, float hi) { unsigned r; asm volatile("v_cvt_pk_bf16_f32 %0, %1, %2" : "=v"(r) : "v"(lo), "v"(hi)); return r; }
; __device__ __forceinline__ s16x4 vtr(const LAS char* p) { return __builtin_bit_cast(s16x4, __builtin_amdgcn_ds_read_tr16_b64_v4i16((LAS s16x4*)p)); }
; template <int NKS>
; __device__ __forceinline__ void pv_accum(f32x4 (&o)[8], const LAS unsigned char* Vt, int key_row0, const bf16x8 (&pf)[NKS], int fr, int fq) {
; #pragma unroll
;     for (int ks = 0; ks < NKS; ++ks) {
;         const LAS char* p0 = (const LAS char*)Vt + (key_row0 + 32 * ks + 4 * fq + (fr >> 2)) * AT_PITCH + 8 * (fr & 3);
; #pragma unroll
;         for (int dt = 0; dt < 8; ++dt) { const s16x4 lo = vtr(p0 + 32 * dt), hi = vtr(p0 + 16 * AT_PITCH + 32 * dt);
;             const bf16x8 vf = {lo[0], lo[1], lo[2], lo[3], hi[0], hi[1], hi[2], hi[3]};
;             o[dt] = __builtin_amdgcn_mfma_f32_16x16x32_bf16(vf, pf[ks], o[dt], 0, 0, 0); }
;         asm volatile("" ::: "memory");
;     }
; }
; __device__ __forceinline__ void attnC_item(const Frame& F, const Args& a, int item) {
;     ...
;     for (int half = 0; half < 2; ++half) {
;         f32x4 o[8];
; #pragma unroll
;         for (int dt = 0; dt < 8; ++dt) o[dt] = (f32x4){0.f, 0.f, 0.f, 0.f};
;         pv_accum<8>(o, half ? R1 : R0, 0, pf, fr, fq);
; #pragma unroll
;         for (int dt = 0; dt < 8; ++dt) { u32x2 w; w.x = cvt_pk_bf16(o[dt][0] * inv, o[dt][1] * inv); w.y = cvt_pk_bf16(o[dt][2] * inv, o[dt][3] * inv); *(u32x2*)(orow + 128 * half + 16 * dt + 4 * fq) = w; }
	v_mfma_f32_16x16x32_bf16 v[48:51], v[32:35], v[0:3], v[44:47]
	ds_read_b64_tr_b16 v[32:33], v143 offset:61056
	ds_read_b64_tr_b16 v[34:35], v143 offset:65408
	v_mul_f32_e32 v52, v64, v52
	v_mul_f32_e32 v53, v64, v53
	s_waitcnt lgkmcnt(0)
	v_mfma_f32_16x16x32_bf16 v[44:47], v[32:35], v[0:3], v[70:73]
	ds_read_b64_tr_b16 v[32:33], v143 offset:61088
	ds_read_b64_tr_b16 v[34:35], v143 offset:65440
	v_mul_f32_e32 v48, v64, v48
	v_mul_f32_e32 v49, v64, v49
	s_waitcnt lgkmcnt(0)
	v_mfma_f32_16x16x32_bf16 v[40:43], v[32:35], v[0:3], v[74:77]
	ds_read_b64_tr_b16 v[32:33], v143 offset:61120
	ds_read_b64_tr_b16 v[34:35], v143 offset:65472
	v_mul_f32_e32 v44, v64, v44
	v_mul_f32_e32 v45, v64, v45
	s_waitcnt lgkmcnt(0)
	v_mfma_f32_16x16x32_bf16 v[36:39], v[32:35], v[0:3], v[78:81]
	ds_read_b64_tr_b16 v[32:33], v143 offset:61152
	ds_read_b64_tr_b16 v[34:35], v143 offset:65504
	v_mul_f32_e32 v40, v64, v40
	s_waitcnt lgkmcnt(0)
	v_mfma_f32_16x16x32_bf16 v[32:35], v[32:35], v[0:3], v[66:69]
	v_mul_f32_e32 v41, v64, v41
	s_nop 1
	v_mul_f32_e32 v66, v64, v83
	v_mul_f32_e32 v67, v64, v85
	v_cvt_pk_bf16_f32 v66, v65, v66
	v_mul_f32_e32 v65, v64, v84
	v_cvt_pk_bf16_f32 v67, v65, v67
	global_store_dwordx2 v[62:63], v[66:67], off
	v_cvt_pk_bf16_f32 v56, v56, v57
	v_mul_f32_e32 v57, v64, v58
	v_mul_f32_e32 v58, v64, v59
	v_cvt_pk_bf16_f32 v57, v57, v58
	global_store_dwordx2 v[60:61], v[56:57], off offset:32
	v_cvt_pk_bf16_f32 v52, v52, v53
	v_mul_f32_e32 v53, v64, v54
	v_mul_f32_e32 v54, v64, v55
	v_cvt_pk_bf16_f32 v53, v53, v54
	global_store_dwordx2 v[60:61], v[52:53], off offset:64
	v_cvt_pk_bf16_f32 v48, v48, v49
	v_mul_f32_e32 v49, v64, v50
	v_mul_f32_e32 v50, v64, v51
	v_cvt_pk_bf16_f32 v49, v49, v50
	global_store_dwordx2 v[60:61], v[48:49], off offset:96
	v_cvt_pk_bf16_f32 v44, v44, v45
	v_mul_f32_e32 v45, v64, v46
	v_mul_f32_e32 v46, v64, v47
	v_cvt_pk_bf16_f32 v45, v45, v46
	global_store_dwordx2 v[60:61], v[44:45], off offset:128
	v_cvt_pk_bf16_f32 v40, v40, v41
	v_mul_f32_e32 v41, v64, v42
	v_mul_f32_e32 v36, v64, v36
	v_mul_f32_e32 v37, v64, v37
	v_mul_f32_e32 v42, v64, v43
	v_cvt_pk_bf16_f32 v41, v41, v42
	global_store_dwordx2 v[60:61], v[40:41], off offset:160
	v_cvt_pk_bf16_f32 v36, v36, v37
	v_mul_f32_e32 v37, v64, v38
	v_mul_f32_e32 v32, v64, v32
	v_mul_f32_e32 v33, v64, v33
	v_mul_f32_e32 v38, v64, v39
	v_cvt_pk_bf16_f32 v37, v37, v38
	global_store_dwordx2 v[60:61], v[36:37], off offset:192
	v_cvt_pk_bf16_f32 v32, v32, v33
	v_mul_f32_e32 v33, v64, v34
	v_mul_f32_e32 v34, v64, v35
	v_cvt_pk_bf16_f32 v33, v33, v34
	global_store_dwordx2 v[60:61], v[32:33], off offset:224
	ds_read_b64_tr_b16 v[34:35], v145 offset:4352
	ds_read_b64_tr_b16 v[32:33], v145
	ds_read_b64_tr_b16 v[36:37], v145 offset:32
	ds_read_b64_tr_b16 v[38:39], v145 offset:4384
	ds_read_b64_tr_b16 v[40:41], v145 offset:64
	ds_read_b64_tr_b16 v[42:43], v145 offset:4416
	ds_read_b64_tr_b16 v[44:45], v145 offset:96
	ds_read_b64_tr_b16 v[46:47], v145 offset:4448
	ds_read_b64_tr_b16 v[48:49], v145 offset:128
	ds_read_b64_tr_b16 v[50:51], v145 offset:4480
	ds_read_b64_tr_b16 v[52:53], v145 offset:160
	ds_read_b64_tr_b16 v[54:55], v145 offset:4512
	ds_read_b64_tr_b16 v[56:57], v145 offset:192
	ds_read_b64_tr_b16 v[58:59], v145 offset:4544
	ds_read_b64_tr_b16 v[66:67], v145 offset:224
	ds_read_b64_tr_b16 v[68:69], v145 offset:4576
	s_waitcnt lgkmcnt(14)
	v_mfma_f32_16x16x32_bf16 v[32:35], v[32:35], v[28:31], 0
	s_waitcnt lgkmcnt(12)
	v_mfma_f32_16x16x32_bf16 v[36:39], v[36:39], v[28:31], 0
	s_waitcnt lgkmcnt(10)
	v_mfma_f32_16x16x32_bf16 v[40:43], v[40:43], v[28:31], 0
	s_waitcnt lgkmcnt(8)
	v_mfma_f32_16x16x32_bf16 v[44:47], v[44:47], v[28:31], 0
	s_waitcnt lgkmcnt(6)
	v_mfma_f32_16x16x32_bf16 v[48:51], v[48:51], v[28:31], 0
	s_waitcnt lgkmcnt(4)
	v_mfma_f32_16x16x32_bf16 v[52:55], v[52:55], v[28:31], 0
	s_waitcnt lgkmcnt(2)
	v_mfma_f32_16x16x32_bf16 v[56:59], v[56:59], v[28:31], 0
	s_waitcnt lgkmcnt(0)
	v_mfma_f32_16x16x32_bf16 v[28:31], v[66:69], v[28:31], 0
	ds_read_b64_tr_b16 v[68:69], v145 offset:13056
	ds_read_b64_tr_b16 v[66:67], v145 offset:8704
	ds_read_b64_tr_b16 v[70:71], v145 offset:8736
	ds_read_b64_tr_b16 v[72:73], v145 offset:13088
	s_waitcnt lgkmcnt(2)
	v_mfma_f32_16x16x32_bf16 v[32:35], v[66:69], v[24:27], v[32:35]
	ds_read_b64_tr_b16 v[66:67], v145 offset:8768
	ds_read_b64_tr_b16 v[68:69], v145 offset:13120
	s_waitcnt lgkmcnt(0)
	v_mfma_f32_16x16x32_bf16 v[40:43], v[66:69], v[24:27], v[40:43]
	ds_read_b64_tr_b16 v[66:67], v145 offset:8800
	ds_read_b64_tr_b16 v[68:69], v145 offset:13152
	s_waitcnt lgkmcnt(0)
	v_mfma_f32_16x16x32_bf16 v[44:47], v[66:69], v[24:27], v[44:47]
	ds_read_b64_tr_b16 v[66:67], v145 offset:8832
	ds_read_b64_tr_b16 v[68:69], v145 offset:13184
	s_waitcnt lgkmcnt(0)
	v_mfma_f32_16x16x32_bf16 v[48:51], v[66:69], v[24:27], v[48:51]
	ds_read_b64_tr_b16 v[66:67], v145 offset:8864
	ds_read_b64_tr_b16 v[68:69], v145 offset:13216
	s_waitcnt lgkmcnt(0)
	v_mfma_f32_16x16x32_bf16 v[52:55], v[66:69], v[24:27], v[52:55]
	ds_read_b64_tr_b16 v[66:67], v145 offset:8896
	ds_read_b64_tr_b16 v[68:69], v145 offset:13248
	s_waitcnt lgkmcnt(0)
	v_mfma_f32_16x16x32_bf16 v[56:59], v[66:69], v[24:27], v[56:59]
	ds_read_b64_tr_b16 v[66:67], v145 offset:8928
	ds_read_b64_tr_b16 v[68:69], v145 offset:13280
	v_mfma_f32_16x16x32_bf16 v[36:39], v[70:73], v[24:27], v[36:39]
	s_waitcnt lgkmcnt(0)
	v_mfma_f32_16x16x32_bf16 v[24:27], v[66:69], v[24:27], v[28:31]
	s_nop 2
	ds_read_b64_tr_b16 v[30:31], v145 offset:21760
	ds_read_b64_tr_b16 v[28:29], v145 offset:17408
	ds_read_b64_tr_b16 v[66:67], v145 offset:17440
	ds_read_b64_tr_b16 v[68:69], v145 offset:21792
	s_waitcnt lgkmcnt(2)
; #define LAS __attribute__((address_space(3)))
; __device__ __forceinline__ s16x4 vtr(const LAS char* p) { return __builtin_bit_cast(s16x4, __builtin_amdgcn_ds_read_tr16_b64_v4i16((LAS s16x4*)p)); }
; template <int NKS>
; __device__ __forceinline__ void pv_accum(f32x4 (&o)[8], const LAS unsigned char* Vt, int key_row0, const bf16x8 (&pf)[NKS], int fr, int fq) {
; #pragma unroll
;     for (int ks = 0; ks < NKS; ++ks) {
;         const LAS char* p0 = (const LAS char*)Vt + (key_row0 + 32 * ks + 4 * fq + (fr >> 2)) * AT_PITCH + 8 * (fr & 3);
; #pragma unroll
;         for (int dt = 0; dt < 8; ++dt) { const s16x4 lo = vtr(p0 + 32 * dt), hi = vtr(p0 + 16 * AT_PITCH + 32 * dt);
;             const bf16x8 vf = {lo[0], lo[1], lo[2], lo[3], hi[0], hi[1], hi[2], hi[3]};
;             o[dt] = __builtin_amdgcn_mfma_f32_16x16x32_bf16(vf, pf[ks], o[dt], 0, 0, 0); }
;         asm volatile("" ::: "memory");
;     }
; }
	v_mfma_f32_16x16x32_bf16 v[28:31], v[28:31], v[20:23], v[32:35]
	s_waitcnt lgkmcnt(0)
	v_mfma_f32_16x16x32_bf16 v[32:35], v[66:69], v[20:23], v[36:39]
	s_nop 2
	ds_read_b64_tr_b16 v[36:37], v145 offset:17472
	ds_read_b64_tr_b16 v[38:39], v145 offset:21824
	s_waitcnt lgkmcnt(0)
	v_mfma_f32_16x16x32_bf16 v[36:39], v[36:39], v[20:23], v[40:43]
	s_nop 2
	ds_read_b64_tr_b16 v[40:41], v145 offset:17504
	ds_read_b64_tr_b16 v[42:43], v145 offset:21856
	s_waitcnt lgkmcnt(0)
	v_mfma_f32_16x16x32_bf16 v[40:43], v[40:43], v[20:23], v[44:47]
	s_nop 2
	ds_read_b64_tr_b16 v[44:45], v145 offset:17536
	ds_read_b64_tr_b16 v[46:47], v145 offset:21888
	s_waitcnt lgkmcnt(0)
	v_mfma_f32_16x16x32_bf16 v[44:47], v[44:47], v[20:23], v[48:51]
	s_nop 2
	ds_read_b64_tr_b16 v[48:49], v145 offset:17568
	ds_read_b64_tr_b16 v[50:51], v145 offset:21920
	s_waitcnt lgkmcnt(0)
	v_mfma_f32_16x16x32_bf16 v[48:51], v[48:51], v[20:23], v[52:55]
	s_nop 2
	ds_read_b64_tr_b16 v[52:53], v145 offset:17600
	ds_read_b64_tr_b16 v[54:55], v145 offset:21952
	s_waitcnt lgkmcnt(0)
	v_mfma_f32_16x16x32_bf16 v[52:55], v[52:55], v[20:23], v[56:59]
	s_nop 2
	ds_read_b64_tr_b16 v[56:57], v145 offset:17632
	ds_read_b64_tr_b16 v[58:59], v145 offset:21984
	s_waitcnt lgkmcnt(0)
	v_mfma_f32_16x16x32_bf16 v[20:23], v[56:59], v[20:23], v[24:27]
	s_nop 2
	ds_read_b64_tr_b16 v[26:27], v145 offset:30464
	ds_read_b64_tr_b16 v[24:25], v145 offset:26112
	ds_read_b64_tr_b16 v[56:57], v145 offset:26144
	ds_read_b64_tr_b16 v[58:59], v145 offset:30496
	s_waitcnt lgkmcnt(2)
	v_mfma_f32_16x16x32_bf16 v[24:27], v[24:27], v[16:19], v[28:31]
	s_waitcnt lgkmcnt(0)
	v_mfma_f32_16x16x32_bf16 v[28:31], v[56:59], v[16:19], v[32:35]
	s_nop 2
	ds_read_b64_tr_b16 v[32:33], v145 offset:26176
	ds_read_b64_tr_b16 v[34:35], v145 offset:30528
	s_waitcnt lgkmcnt(0)
	v_mfma_f32_16x16x32_bf16 v[32:35], v[32:35], v[16:19], v[36:39]
	s_nop 2
	ds_read_b64_tr_b16 v[36:37], v145 offset:26208
	ds_read_b64_tr_b16 v[38:39], v145 offset:30560
	s_waitcnt lgkmcnt(0)
	v_mfma_f32_16x16x32_bf16 v[36:39], v[36:39], v[16:19], v[40:43]
	s_nop 2
	ds_read_b64_tr_b16 v[40:41], v145 offset:26240
	ds_read_b64_tr_b16 v[42:43], v145 offset:30592
	s_waitcnt lgkmcnt(0)
	v_mfma_f32_16x16x32_bf16 v[40:43], v[40:43], v[16:19], v[44:47]
	s_nop 2
	ds_read_b64_tr_b16 v[44:45], v145 offset:26272
	ds_read_b64_tr_b16 v[46:47], v145 offset:30624
	s_waitcnt lgkmcnt(0)
	v_mfma_f32_16x16x32_bf16 v[44:47], v[44:47], v[16:19], v[48:51]
	s_nop 2
	ds_read_b64_tr_b16 v[48:49], v145 offset:26304
	ds_read_b64_tr_b16 v[50:51], v145 offset:30656
	s_waitcnt lgkmcnt(0)
	v_mfma_f32_16x16x32_bf16 v[48:51], v[48:51], v[16:19], v[52:55]
	s_nop 2
	ds_read_b64_tr_b16 v[52:53], v145 offset:26336
	ds_read_b64_tr_b16 v[54:55], v145 offset:30688
	s_waitcnt lgkmcnt(0)
	v_mfma_f32_16x16x32_bf16 v[16:19], v[52:55], v[16:19], v[20:23]
	s_nop 2
	ds_read_b64_tr_b16 v[22:23], v145 offset:39168
	ds_read_b64_tr_b16 v[20:21], v145 offset:34816
	ds_read_b64_tr_b16 v[52:53], v145 offset:34848
	ds_read_b64_tr_b16 v[54:55], v145 offset:39200
	s_waitcnt lgkmcnt(2)
	v_mfma_f32_16x16x32_bf16 v[20:23], v[20:23], v[12:15], v[24:27]
	s_waitcnt lgkmcnt(0)
	v_mfma_f32_16x16x32_bf16 v[24:27], v[52:55], v[12:15], v[28:31]
	s_nop 2
	ds_read_b64_tr_b16 v[28:29], v145 offset:34880
	ds_read_b64_tr_b16 v[30:31], v145 offset:39232
	s_waitcnt lgkmcnt(0)
	v_mfma_f32_16x16x32_bf16 v[28:31], v[28:31], v[12:15], v[32:35]
	s_nop 2
	ds_read_b64_tr_b16 v[32:33], v145 offset:34912
	ds_read_b64_tr_b16 v[34:35], v145 offset:39264
	s_waitcnt lgkmcnt(0)
	v_mfma_f32_16x16x32_bf16 v[32:35], v[32:35], v[12:15], v[36:39]
	s_nop 2
	ds_read_b64_tr_b16 v[36:37], v145 offset:34944
	ds_read_b64_tr_b16 v[38:39], v145 offset:39296
	s_waitcnt lgkmcnt(0)
	v_mfma_f32_16x16x32_bf16 v[36:39], v[36:39], v[12:15], v[40:43]
	s_nop 2
	ds_read_b64_tr_b16 v[40:41], v145 offset:34976
	ds_read_b64_tr_b16 v[42:43], v145 offset:39328
	s_waitcnt lgkmcnt(0)
	v_mfma_f32_16x16x32_bf16 v[40:43], v[40:43], v[12:15], v[44:47]
	s_nop 2
	ds_read_b64_tr_b16 v[44:45], v145 offset:35008
	ds_read_b64_tr_b16 v[46:47], v145 offset:39360
	s_waitcnt lgkmcnt(0)
	v_mfma_f32_16x16x32_bf16 v[44:47], v[44:47], v[12:15], v[48:51]
	s_nop 2
	ds_read_b64_tr_b16 v[48:49], v145 offset:35040
	ds_read_b64_tr_b16 v[50:51], v145 offset:39392
	s_waitcnt lgkmcnt(0)
	v_mfma_f32_16x16x32_bf16 v[12:15], v[48:51], v[12:15], v[16:19]
	s_nop 2
	ds_read_b64_tr_b16 v[18:19], v145 offset:47872
	ds_read_b64_tr_b16 v[16:17], v145 offset:43520
	ds_read_b64_tr_b16 v[48:49], v145 offset:43552
	ds_read_b64_tr_b16 v[50:51], v145 offset:47904
	s_waitcnt lgkmcnt(2)
	v_mfma_f32_16x16x32_bf16 v[16:19], v[16:19], v[8:11], v[20:23]
	s_waitcnt lgkmcnt(0)
	v_mfma_f32_16x16x32_bf16 v[20:23], v[48:51], v[8:11], v[24:27]
	s_nop 2
	ds_read_b64_tr_b16 v[24:25], v145 offset:43584
	ds_read_b64_tr_b16 v[26:27], v145 offset:47936
	s_waitcnt lgkmcnt(0)
	v_mfma_f32_16x16x32_bf16 v[24:27], v[24:27], v[8:11], v[28:31]
	s_nop 2
	ds_read_b64_tr_b16 v[28:29], v145 offset:43616
	ds_read_b64_tr_b16 v[30:31], v145 offset:47968
	s_waitcnt lgkmcnt(0)
	v_mfma_f32_16x16x32_bf16 v[28:31], v[28:31], v[8:11], v[32:35]
	s_nop 2
	ds_read_b64_tr_b16 v[32:33], v145 offset:43648
	ds_read_b64_tr_b16 v[34:35], v145 offset:48000
	s_waitcnt lgkmcnt(0)
	v_mfma_f32_16x16x32_bf16 v[32:35], v[32:35], v[8:11], v[36:39]
	s_nop 2
	ds_read_b64_tr_b16 v[36:37], v145 offset:43680
	ds_read_b64_tr_b16 v[38:39], v145 offset:48032
	s_waitcnt lgkmcnt(0)
; __device__ __forceinline__ unsigned cvt_pk_bf16(float lo, float hi) { unsigned r; asm volatile("v_cvt_pk_bf16_f32 %0, %1, %2" : "=v"(r) : "v"(lo), "v"(hi)); return r; }
; __device__ __forceinline__ void attnC_item(const Frame& F, const Args& a, int item) {
;     ...
;     for (int half = 0; half < 2; ++half) {
;         f32x4 o[8];
; #pragma unroll
;         for (int dt = 0; dt < 8; ++dt) o[dt] = (f32x4){0.f, 0.f, 0.f, 0.f};
;         pv_accum<8>(o, half ? R1 : R0, 0, pf, fr, fq);
; #pragma unroll
;         for (int dt = 0; dt < 8; ++dt) { u32x2 w; w.x = cvt_pk_bf16(o[dt][0] * inv, o[dt][1] * inv); w.y = cvt_pk_bf16(o[dt][2] * inv, o[dt][3] * inv); *(u32x2*)(orow + 128 * half + 16 * dt + 4 * fq) = w; }
	v_mfma_f32_16x16x32_bf16 v[36:39], v[36:39], v[8:11], v[40:43]
	s_nop 2
	ds_read_b64_tr_b16 v[40:41], v145 offset:43712
	ds_read_b64_tr_b16 v[42:43], v145 offset:48064
	s_waitcnt lgkmcnt(0)
	v_mfma_f32_16x16x32_bf16 v[40:43], v[40:43], v[8:11], v[44:47]
	s_nop 2
	ds_read_b64_tr_b16 v[44:45], v145 offset:43744
	ds_read_b64_tr_b16 v[46:47], v145 offset:48096
	s_waitcnt lgkmcnt(0)
	v_mfma_f32_16x16x32_bf16 v[8:11], v[44:47], v[8:11], v[12:15]
	s_nop 2
	ds_read_b64_tr_b16 v[14:15], v145 offset:56576
	ds_read_b64_tr_b16 v[12:13], v145 offset:52224
	ds_read_b64_tr_b16 v[44:45], v145 offset:52256
	ds_read_b64_tr_b16 v[46:47], v145 offset:56608
	s_waitcnt lgkmcnt(2)
	v_mfma_f32_16x16x32_bf16 v[12:15], v[12:15], v[4:7], v[16:19]
	s_waitcnt lgkmcnt(0)
	v_mfma_f32_16x16x32_bf16 v[16:19], v[44:47], v[4:7], v[20:23]
	s_nop 2
	ds_read_b64_tr_b16 v[20:21], v145 offset:52288
	ds_read_b64_tr_b16 v[22:23], v145 offset:56640
	s_waitcnt lgkmcnt(0)
	v_mfma_f32_16x16x32_bf16 v[20:23], v[20:23], v[4:7], v[24:27]
	s_nop 2
	ds_read_b64_tr_b16 v[24:25], v145 offset:52320
	ds_read_b64_tr_b16 v[26:27], v145 offset:56672
	s_waitcnt lgkmcnt(0)
	v_mfma_f32_16x16x32_bf16 v[24:27], v[24:27], v[4:7], v[28:31]
	s_nop 2
	ds_read_b64_tr_b16 v[28:29], v145 offset:52352
	ds_read_b64_tr_b16 v[30:31], v145 offset:56704
	s_waitcnt lgkmcnt(0)
	v_mfma_f32_16x16x32_bf16 v[28:31], v[28:31], v[4:7], v[32:35]
	s_nop 2
	ds_read_b64_tr_b16 v[32:33], v145 offset:52384
	ds_read_b64_tr_b16 v[34:35], v145 offset:56736
	s_waitcnt lgkmcnt(0)
	v_mfma_f32_16x16x32_bf16 v[32:35], v[32:35], v[4:7], v[36:39]
	s_nop 2
	ds_read_b64_tr_b16 v[36:37], v145 offset:52416
	ds_read_b64_tr_b16 v[38:39], v145 offset:56768
	s_waitcnt lgkmcnt(0)
	v_mfma_f32_16x16x32_bf16 v[36:39], v[36:39], v[4:7], v[40:43]
	s_nop 2
	ds_read_b64_tr_b16 v[40:41], v145 offset:52448
	ds_read_b64_tr_b16 v[42:43], v145 offset:56800
	s_waitcnt lgkmcnt(0)
	v_mfma_f32_16x16x32_bf16 v[4:7], v[40:43], v[4:7], v[8:11]
	s_nop 2
	ds_read_b64_tr_b16 v[10:11], v145 offset:65280
	ds_read_b64_tr_b16 v[8:9], v145 offset:60928
	ds_read_b64_tr_b16 v[40:41], v145 offset:60960
	ds_read_b64_tr_b16 v[42:43], v145 offset:65312
	s_waitcnt lgkmcnt(2)
	v_mfma_f32_16x16x32_bf16 v[8:11], v[8:11], v[0:3], v[12:15]
	s_waitcnt lgkmcnt(0)
	v_mfma_f32_16x16x32_bf16 v[12:15], v[40:43], v[0:3], v[16:19]
	s_nop 2
	ds_read_b64_tr_b16 v[16:17], v145 offset:60992
	ds_read_b64_tr_b16 v[18:19], v145 offset:65344
	s_waitcnt lgkmcnt(0)
	v_mfma_f32_16x16x32_bf16 v[16:19], v[16:19], v[0:3], v[20:23]
	s_nop 2
	ds_read_b64_tr_b16 v[20:21], v145 offset:61024
	ds_read_b64_tr_b16 v[22:23], v145 offset:65376
	s_waitcnt lgkmcnt(0)
	v_mfma_f32_16x16x32_bf16 v[20:23], v[20:23], v[0:3], v[24:27]
	s_nop 2
	ds_read_b64_tr_b16 v[24:25], v145 offset:61056
	ds_read_b64_tr_b16 v[26:27], v145 offset:65408
	s_waitcnt lgkmcnt(0)
	v_mfma_f32_16x16x32_bf16 v[24:27], v[24:27], v[0:3], v[28:31]
	s_nop 2
	ds_read_b64_tr_b16 v[28:29], v145 offset:61088
	ds_read_b64_tr_b16 v[30:31], v145 offset:65440
	s_waitcnt lgkmcnt(0)
	v_mfma_f32_16x16x32_bf16 v[28:31], v[28:31], v[0:3], v[32:35]
	s_nop 2
	ds_read_b64_tr_b16 v[32:33], v145 offset:61120
	ds_read_b64_tr_b16 v[34:35], v145 offset:65472
	s_waitcnt lgkmcnt(0)
	v_mfma_f32_16x16x32_bf16 v[32:35], v[32:35], v[0:3], v[36:39]
	s_nop 2
	ds_read_b64_tr_b16 v[36:37], v145 offset:61152
	ds_read_b64_tr_b16 v[38:39], v145 offset:65504
	s_waitcnt lgkmcnt(0)
	v_mfma_f32_16x16x32_bf16 v[0:3], v[36:39], v[0:3], v[4:7]
	s_nop 2
	v_mul_f32_e32 v4, v64, v8
	v_mul_f32_e32 v5, v64, v9
	v_cvt_pk_bf16_f32 v4, v4, v5
	v_mul_f32_e32 v5, v64, v10
	v_mul_f32_e32 v6, v64, v11
	v_cvt_pk_bf16_f32 v5, v5, v6
	global_store_dwordx2 v[60:61], v[4:5], off offset:256
	v_mul_f32_e32 v4, v64, v12
	v_mul_f32_e32 v5, v64, v13
	v_cvt_pk_bf16_f32 v4, v4, v5
	v_mul_f32_e32 v5, v64, v14
	v_mul_f32_e32 v6, v64, v15
	v_cvt_pk_bf16_f32 v5, v5, v6
	global_store_dwordx2 v[60:61], v[4:5], off offset:288
	v_mul_f32_e32 v4, v64, v16
	v_mul_f32_e32 v5, v64, v17
	v_cvt_pk_bf16_f32 v4, v4, v5
	v_mul_f32_e32 v5, v64, v18
	v_mul_f32_e32 v6, v64, v19
	v_cvt_pk_bf16_f32 v5, v5, v6
	global_store_dwordx2 v[60:61], v[4:5], off offset:320
	v_mul_f32_e32 v4, v64, v20
	v_mul_f32_e32 v5, v64, v21
	v_cvt_pk_bf16_f32 v4, v4, v5
	v_mul_f32_e32 v5, v64, v22
	v_mul_f32_e32 v6, v64, v23
	v_cvt_pk_bf16_f32 v5, v5, v6
	global_store_dwordx2 v[60:61], v[4:5], off offset:352
	v_mul_f32_e32 v4, v64, v24
	v_mul_f32_e32 v5, v64, v25
	v_cvt_pk_bf16_f32 v4, v4, v5
	v_mul_f32_e32 v5, v64, v26
	v_mul_f32_e32 v6, v64, v27
	v_cvt_pk_bf16_f32 v5, v5, v6
	global_store_dwordx2 v[60:61], v[4:5], off offset:384
	v_mul_f32_e32 v4, v64, v28
	v_mul_f32_e32 v5, v64, v29
	v_cvt_pk_bf16_f32 v4, v4, v5
	v_mul_f32_e32 v5, v64, v30
	v_mul_f32_e32 v6, v64, v31
	v_cvt_pk_bf16_f32 v5, v5, v6
	global_store_dwordx2 v[60:61], v[4:5], off offset:416
	v_mul_f32_e32 v4, v64, v32
	v_mul_f32_e32 v5, v64, v33
	v_cvt_pk_bf16_f32 v4, v4, v5
	v_mul_f32_e32 v5, v64, v34
	v_mul_f32_e32 v0, v64, v0
	v_mul_f32_e32 v1, v64, v1
	v_mul_f32_e32 v6, v64, v35
	v_cvt_pk_bf16_f32 v5, v5, v6
	global_store_dwordx2 v[60:61], v[4:5], off offset:448
	v_cvt_pk_bf16_f32 v0, v0, v1
	v_mul_f32_e32 v1, v64, v2
	v_mul_f32_e32 v2, v64, v3
	v_cvt_pk_bf16_f32 v1, v1, v2
	global_store_dwordx2 v[60:61], v[0:1], off offset:480
	s_cbranch_scc0 .LBB0_396

; __device__ __forceinline__ unsigned cvt_pk_bf16(float lo, float hi) { unsigned r; asm volatile("v_cvt_pk_bf16_f32 %0, %1, %2" : "=v"(r) : "v"(lo), "v"(hi)); return r; }
; __device__ __forceinline__ void attnA_item(const Frame& F, const Args& a, int item) {
;     ...
;     mx = fmaxf(mx, __shfl_xor(mx, 16)); mx = fmaxf(mx, __shfl_xor(mx, 32));
;     float sum = 0.f;
; #pragma unroll
;     for (int ct = 0; ct < 12; ++ct)
; #pragma unroll
;         for (int j = 0; j < 4; ++j) { const float p = __expf(s[ct][j] - mx); s[ct][j] = p; sum += p; }
;     sum += __shfl_xor(sum, 16); sum += __shfl_xor(sum, 32);
;     bf16x8 pf[6];
; #pragma unroll
;     for (int ks = 0; ks < 6; ++ks) { u32x4 w; w.x = cvt_pk_bf16(s[2 * ks][0], s[2 * ks][1]); w.y = cvt_pk_bf16(s[2 * ks][2], s[2 * ks][3]);
;         w.z = cvt_pk_bf16(s[2 * ks + 1][0], s[2 * ks + 1][1]); w.w = cvt_pk_bf16(s[2 * ks + 1][2], s[2 * ks + 1][3]); pf[ks] = __builtin_bit_cast(bf16x8, w); }
.LBB0_564:
	s_or_b64 exec, exec, s[8:9]
	s_mov_b32 s3, 0xff61b1e6
	v_max3_f32 v2, v49, s3, v48
	v_max3_f32 v2, v2, v45, v44
	v_max3_f32 v2, v2, v47, v46
	v_max3_f32 v2, v2, v41, v40
	v_max3_f32 v2, v2, v43, v42
	v_max3_f32 v2, v2, v37, v36
	v_max3_f32 v2, v2, v39, v38
	v_max3_f32 v2, v2, v33, v32
	v_max3_f32 v2, v2, v50, v35
	v_max3_f32 v2, v2, v21, v20
	v_max3_f32 v2, v2, v23, v22
	v_max3_f32 v2, v2, v17, v16
	v_max3_f32 v2, v2, v19, v18
	v_max3_f32 v2, v2, v29, v28
	v_max3_f32 v2, v2, v31, v30
	v_max3_f32 v2, v2, v25, v24
	v_max3_f32 v2, v2, v27, v26
	v_max3_f32 v2, v2, v13, v12
	v_max3_f32 v2, v2, v15, v14
	v_max3_f32 v2, v2, v9, v8
	v_and_b32_e32 v34, 64, v197
	v_max3_f32 v2, v2, v11, v10
	v_xor_b32_e32 v3, 16, v197
	v_add_u32_e32 v34, 64, v34
	v_max3_f32 v2, v2, v5, v4
	v_cmp_lt_i32_e32 vcc, v3, v34
	v_max3_f32 v2, v2, v7, v6
	v_max3_f32 v2, v2, v1, v0
	v_cndmask_b32_e32 v3, v197, v3, vcc
	v_lshlrev_b32_e32 v3, 2, v3
	ds_bpermute_b32 v51, v3, v2
	s_mov_b64 s[8:9], -1
	s_cmpk_gt_u32 s6, 0x7f
	s_waitcnt lgkmcnt(0)
	v_max_f32_e32 v51, v51, v51
	v_max_f32_e32 v2, v2, v51
	v_xor_b32_e32 v51, 32, v197
	v_cmp_lt_i32_e32 vcc, v51, v34
	s_nop 1
	v_cndmask_b32_e32 v34, v197, v51, vcc
	v_lshlrev_b32_e32 v51, 2, v34
	ds_bpermute_b32 v34, v51, v2
	s_waitcnt lgkmcnt(0)
	v_max_f32_e32 v34, v34, v34
	v_max_f32_e32 v34, v2, v34
	s_mov_b32 s101, 0x3fb8aa3b
	v_mul_f32_e32 v208, 0xbfb8aa3b, v34
	v_fma_f32 v2, v49, s101, v208
	v_exp_f32_e32 v2, v2
	v_fma_f32 v48, v48, s101, v208
	v_exp_f32_e32 v48, v48
	v_fma_f32 v45, v45, s101, v208
	v_exp_f32_e32 v45, v45
	v_fma_f32 v44, v44, s101, v208
	v_exp_f32_e32 v44, v44
	v_fma_f32 v47, v47, s101, v208
	v_add_f32_e32 v49, 0, v2
	v_exp_f32_e32 v47, v47
	v_fma_f32 v46, v46, s101, v208
	v_add_f32_e32 v49, v48, v49
	v_exp_f32_e32 v46, v46
	v_fma_f32 v41, v41, s101, v208
	v_add_f32_e32 v49, v45, v49
	v_exp_f32_e32 v41, v41
	v_fma_f32 v40, v40, s101, v208
	v_add_f32_e32 v49, v44, v49
	v_exp_f32_e32 v40, v40
	v_fma_f32 v43, v43, s101, v208
	v_add_f32_e32 v49, v47, v49
	v_exp_f32_e32 v43, v43
	v_fma_f32 v42, v42, s101, v208
	v_add_f32_e32 v49, v46, v49
	v_exp_f32_e32 v42, v42
	v_fma_f32 v37, v37, s101, v208
	v_add_f32_e32 v49, v41, v49
	v_exp_f32_e32 v37, v37
	v_fma_f32 v36, v36, s101, v208
	v_add_f32_e32 v49, v40, v49
	v_exp_f32_e32 v52, v36
	v_add_f32_e32 v49, v43, v49
	v_fma_f32 v39, v39, s101, v208
	v_add_f32_e32 v49, v42, v49
	v_exp_f32_e32 v39, v39
	v_fma_f32 v38, v38, s101, v208
	v_add_f32_e32 v49, v37, v49
	v_exp_f32_e32 v38, v38
	v_fma_f32 v33, v33, s101, v208
	v_add_f32_e32 v36, v52, v49
	v_exp_f32_e32 v33, v33
	v_fma_f32 v32, v32, s101, v208
	v_exp_f32_e32 v32, v32
	v_fma_f32 v49, v50, s101, v208
	v_add_f32_e32 v36, v39, v36
	v_exp_f32_e32 v49, v49
	v_fma_f32 v35, v35, s101, v208
	v_add_f32_e32 v36, v38, v36
	v_exp_f32_e32 v50, v35
	v_fma_f32 v21, v21, s101, v208
	v_add_f32_e32 v36, v33, v36
	v_exp_f32_e32 v53, v21
	v_fma_f32 v20, v20, s101, v208
	v_add_f32_e32 v36, v32, v36
	v_exp_f32_e32 v54, v20
	v_add_f32_e32 v36, v49, v36
	v_add_f32_e32 v35, v50, v36
	v_add_f32_e32 v21, v53, v35
	v_add_f32_e32 v20, v54, v21
	v_fma_f32 v21, v23, s101, v208
	v_exp_f32_e32 v55, v21
	v_fma_f32 v21, v22, s101, v208
	v_exp_f32_e32 v56, v21
	v_fma_f32 v17, v17, s101, v208
	v_exp_f32_e32 v57, v17
	v_fma_f32 v16, v16, s101, v208
	v_exp_f32_e32 v58, v16
	v_add_f32_e32 v20, v55, v20
	v_add_f32_e32 v20, v56, v20
	v_add_f32_e32 v17, v57, v20
	v_add_f32_e32 v16, v58, v17
	v_fma_f32 v17, v19, s101, v208
	v_exp_f32_e32 v59, v17
	v_fma_f32 v17, v18, s101, v208
	v_exp_f32_e32 v62, v17
	v_fma_f32 v17, v29, s101, v208
	v_exp_f32_e32 v29, v17
	v_fma_f32 v17, v28, s101, v208
	v_exp_f32_e32 v28, v17
	v_fma_f32 v17, v31, s101, v208
	v_exp_f32_e32 v31, v17
	v_fma_f32 v17, v30, s101, v208
	v_exp_f32_e32 v30, v17
	v_fma_f32 v17, v25, s101, v208
	v_exp_f32_e32 v25, v17
	v_add_f32_e32 v16, v59, v16
	v_fma_f32 v17, v24, s101, v208
	v_add_f32_e32 v16, v62, v16
	v_exp_f32_e32 v24, v17
	v_add_f32_e32 v16, v29, v16
	v_fma_f32 v17, v27, s101, v208
	v_add_f32_e32 v16, v28, v16
	v_exp_f32_e32 v27, v17
	v_add_f32_e32 v16, v31, v16
	v_fma_f32 v17, v26, s101, v208
	v_add_f32_e32 v16, v30, v16
	v_exp_f32_e32 v26, v17
	v_fma_f32 v13, v13, s101, v208
	v_add_f32_e32 v16, v25, v16
	v_exp_f32_e32 v63, v13
	v_fma_f32 v12, v12, s101, v208
	v_add_f32_e32 v16, v24, v16
	v_exp_f32_e32 v66, v12
	v_add_f32_e32 v16, v27, v16
	v_add_f32_e32 v16, v26, v16
	v_add_f32_e32 v13, v63, v16
	v_add_f32_e32 v12, v66, v13
	v_fma_f32 v13, v15, s101, v208
	v_exp_f32_e32 v71, v13
	v_fma_f32 v13, v14, s101, v208
	v_exp_f32_e32 v73, v13
	v_fma_f32 v9, v9, s101, v208
	v_exp_f32_e32 v74, v9
	v_fma_f32 v8, v8, s101, v208
	v_exp_f32_e32 v75, v8
	v_add_f32_e32 v12, v71, v12
	v_add_f32_e32 v12, v73, v12
	v_add_f32_e32 v9, v74, v12
	v_add_f32_e32 v8, v75, v9
	v_fma_f32 v9, v11, s101, v208
	v_exp_f32_e32 v199, v9
	v_fma_f32 v9, v10, s101, v208
	v_exp_f32_e32 v200, v9
	v_fma_f32 v5, v5, s101, v208
	v_exp_f32_e32 v201, v5
	v_fma_f32 v4, v4, s101, v208
	v_exp_f32_e32 v202, v4
	v_add_f32_e32 v8, v199, v8
	v_add_f32_e32 v8, v200, v8
	v_add_f32_e32 v5, v201, v8
	v_add_f32_e32 v4, v202, v5
	v_fma_f32 v5, v7, s101, v208
	v_exp_f32_e32 v203, v5
	v_fma_f32 v5, v6, s101, v208
	v_exp_f32_e32 v204, v5
	v_fma_f32 v1, v1, s101, v208
	v_exp_f32_e32 v205, v1
	v_fma_f32 v0, v0, s101, v208
	v_exp_f32_e32 v206, v0
	v_add_f32_e32 v4, v203, v4
	v_add_f32_e32 v4, v204, v4
	v_add_f32_e32 v1, v205, v4
	v_add_f32_e32 v0, v206, v1
	ds_bpermute_b32 v1, v3, v0
	v_cvt_pk_bf16_f32 v20, v2, v48
	v_cvt_pk_bf16_f32 v21, v45, v44
	v_cvt_pk_bf16_f32 v22, v47, v46
	v_cvt_pk_bf16_f32 v23, v41, v40
	s_waitcnt lgkmcnt(0)
; #define LAS __attribute__((address_space(3)))
; __device__ __forceinline__ unsigned cvt_pk_bf16(float lo, float hi) { unsigned r; asm volatile("v_cvt_pk_bf16_f32 %0, %1, %2" : "=v"(r) : "v"(lo), "v"(hi)); return r; }
; __device__ __forceinline__ s16x4 vtr(const LAS char* p) { return __builtin_bit_cast(s16x4, __builtin_amdgcn_ds_read_tr16_b64_v4i16((LAS s16x4*)p)); }
; template <int NKS>
; __device__ __forceinline__ void pv_accum(f32x4 (&o)[8], const LAS unsigned char* Vt, int key_row0, const bf16x8 (&pf)[NKS], int fr, int fq) {
; #pragma unroll
;     for (int ks = 0; ks < NKS; ++ks) {
;         const LAS char* p0 = (const LAS char*)Vt + (key_row0 + 32 * ks + 4 * fq + (fr >> 2)) * AT_PITCH + 8 * (fr & 3);
; #pragma unroll
;         for (int dt = 0; dt < 8; ++dt) { const s16x4 lo = vtr(p0 + 32 * dt), hi = vtr(p0 + 16 * AT_PITCH + 32 * dt);
;             const bf16x8 vf = {lo[0], lo[1], lo[2], lo[3], hi[0], hi[1], hi[2], hi[3]};
;             o[dt] = __builtin_amdgcn_mfma_f32_16x16x32_bf16(vf, pf[ks], o[dt], 0, 0, 0); }
;         asm volatile("" ::: "memory");
;     }
; }
; __device__ __forceinline__ void attnA_item(const Frame& F, const Args& a, int item) {
;     ...
;     sum += __shfl_xor(sum, 16); sum += __shfl_xor(sum, 32);
;     bf16x8 pf[6];
; #pragma unroll
;     for (int ks = 0; ks < 6; ++ks) { u32x4 w; w.x = cvt_pk_bf16(s[2 * ks][0], s[2 * ks][1]); w.y = cvt_pk_bf16(s[2 * ks][2], s[2 * ks][3]);
;         w.z = cvt_pk_bf16(s[2 * ks + 1][0], s[2 * ks + 1][1]); w.w = cvt_pk_bf16(s[2 * ks + 1][2], s[2 * ks + 1][3]); pf[ks] = __builtin_bit_cast(bf16x8, w); }
;     f32x4 o[8];
; #pragma unroll
;     for (int dt = 0; dt < 8; ++dt) o[dt] = (f32x4){0.f, 0.f, 0.f, 0.f};
;     pv_accum<6>(o, R1, 64 * hb, pf, fr, fq);
	v_add_f32_e32 v35, v0, v1
	v_cvt_pk_bf16_f32 v16, v43, v42
	v_cvt_pk_bf16_f32 v17, v37, v52
	v_cvt_pk_bf16_f32 v18, v39, v38
	v_cvt_pk_bf16_f32 v19, v33, v32
	v_cvt_pk_bf16_f32 v12, v49, v50
	v_cvt_pk_bf16_f32 v13, v53, v54
	v_cvt_pk_bf16_f32 v14, v55, v56
	v_cvt_pk_bf16_f32 v15, v57, v58
	v_cvt_pk_bf16_f32 v8, v59, v62
	v_cvt_pk_bf16_f32 v9, v29, v28
	v_cvt_pk_bf16_f32 v10, v31, v30
	v_cvt_pk_bf16_f32 v11, v25, v24
	v_cvt_pk_bf16_f32 v4, v27, v26
	v_cvt_pk_bf16_f32 v5, v63, v66
	v_cvt_pk_bf16_f32 v6, v71, v73
	v_cvt_pk_bf16_f32 v7, v74, v75
	v_cvt_pk_bf16_f32 v0, v199, v200
	v_cvt_pk_bf16_f32 v1, v201, v202
	v_cvt_pk_bf16_f32 v2, v203, v204
	v_cvt_pk_bf16_f32 v3, v205, v206
	ds_read_b64_tr_b16 v[26:27], v182 offset:4352
	ds_read_b64_tr_b16 v[24:25], v182
	ds_read_b64_tr_b16 v[28:29], v182 offset:32
	ds_read_b64_tr_b16 v[30:31], v182 offset:4384
	ds_bpermute_b32 v36, v51, v35
	ds_read_b64_tr_b16 v[38:39], v182 offset:64
	ds_read_b64_tr_b16 v[40:41], v182 offset:4416
	ds_read_b64_tr_b16 v[42:43], v182 offset:96
	ds_read_b64_tr_b16 v[44:45], v182 offset:4448
	ds_read_b64_tr_b16 v[46:47], v182 offset:128
	ds_read_b64_tr_b16 v[48:49], v182 offset:4480
	ds_read_b64_tr_b16 v[50:51], v182 offset:160
	ds_read_b64_tr_b16 v[52:53], v182 offset:4512
	ds_read_b64_tr_b16 v[54:55], v182 offset:192
	ds_read_b64_tr_b16 v[56:57], v182 offset:4544
	ds_read_b64_tr_b16 v[200:201], v182 offset:224
	ds_read_b64_tr_b16 v[202:203], v182 offset:4576
	s_waitcnt lgkmcnt(14)
	v_mfma_f32_16x16x32_bf16 v[24:27], v[24:27], v[20:23], 0
	s_waitcnt lgkmcnt(13)
	v_mfma_f32_16x16x32_bf16 v[28:31], v[28:31], v[20:23], 0
	s_waitcnt lgkmcnt(10)
	v_mfma_f32_16x16x32_bf16 v[38:41], v[38:41], v[20:23], 0
	s_waitcnt lgkmcnt(8)
	v_mfma_f32_16x16x32_bf16 v[42:45], v[42:45], v[20:23], 0
	s_waitcnt lgkmcnt(6)
	v_mfma_f32_16x16x32_bf16 v[46:49], v[46:49], v[20:23], 0
	s_waitcnt lgkmcnt(4)
	v_mfma_f32_16x16x32_bf16 v[50:53], v[50:53], v[20:23], 0
	s_waitcnt lgkmcnt(2)
	v_mfma_f32_16x16x32_bf16 v[54:57], v[54:57], v[20:23], 0
	s_waitcnt lgkmcnt(0)
	v_mfma_f32_16x16x32_bf16 v[20:23], v[200:203], v[20:23], 0
	ds_read_b64_tr_b16 v[202:203], v182 offset:13056
	ds_read_b64_tr_b16 v[200:201], v182 offset:8704
	ds_read_b64_tr_b16 v[204:205], v182 offset:8736
	ds_read_b64_tr_b16 v[206:207], v182 offset:13088
	s_waitcnt lgkmcnt(2)
	v_mfma_f32_16x16x32_bf16 v[24:27], v[200:203], v[16:19], v[24:27]
	ds_read_b64_tr_b16 v[200:201], v182 offset:8768
	ds_read_b64_tr_b16 v[202:203], v182 offset:13120
	s_waitcnt lgkmcnt(0)
	v_mfma_f32_16x16x32_bf16 v[38:41], v[200:203], v[16:19], v[38:41]
	ds_read_b64_tr_b16 v[200:201], v182 offset:8800
	ds_read_b64_tr_b16 v[202:203], v182 offset:13152
	s_waitcnt lgkmcnt(0)
	v_mfma_f32_16x16x32_bf16 v[42:45], v[200:203], v[16:19], v[42:45]
	ds_read_b64_tr_b16 v[200:201], v182 offset:8832
	ds_read_b64_tr_b16 v[202:203], v182 offset:13184
	s_waitcnt lgkmcnt(0)
	v_mfma_f32_16x16x32_bf16 v[46:49], v[200:203], v[16:19], v[46:49]
	ds_read_b64_tr_b16 v[200:201], v182 offset:8864
	ds_read_b64_tr_b16 v[202:203], v182 offset:13216
	s_waitcnt lgkmcnt(0)
	v_mfma_f32_16x16x32_bf16 v[50:53], v[200:203], v[16:19], v[50:53]
	ds_read_b64_tr_b16 v[200:201], v182 offset:8896
	ds_read_b64_tr_b16 v[202:203], v182 offset:13248
	s_waitcnt lgkmcnt(0)
	v_mfma_f32_16x16x32_bf16 v[54:57], v[200:203], v[16:19], v[54:57]
	ds_read_b64_tr_b16 v[200:201], v182 offset:8928
	ds_read_b64_tr_b16 v[202:203], v182 offset:13280
	v_mfma_f32_16x16x32_bf16 v[28:31], v[204:207], v[16:19], v[28:31]
	s_waitcnt lgkmcnt(0)
	v_mfma_f32_16x16x32_bf16 v[16:19], v[200:203], v[16:19], v[20:23]
	s_nop 2
	ds_read_b64_tr_b16 v[22:23], v182 offset:21760
	ds_read_b64_tr_b16 v[20:21], v182 offset:17408
	ds_read_b64_tr_b16 v[200:201], v182 offset:17440
	ds_read_b64_tr_b16 v[202:203], v182 offset:21792
	s_waitcnt lgkmcnt(2)
	v_mfma_f32_16x16x32_bf16 v[20:23], v[20:23], v[12:15], v[24:27]
	s_waitcnt lgkmcnt(0)
	v_mfma_f32_16x16x32_bf16 v[24:27], v[200:203], v[12:15], v[28:31]
	s_nop 2
	ds_read_b64_tr_b16 v[28:29], v182 offset:17472
	ds_read_b64_tr_b16 v[30:31], v182 offset:21824
	s_waitcnt lgkmcnt(0)
	v_mfma_f32_16x16x32_bf16 v[28:31], v[28:31], v[12:15], v[38:41]
	s_nop 2
	ds_read_b64_tr_b16 v[38:39], v182 offset:17504
	ds_read_b64_tr_b16 v[40:41], v182 offset:21856
	s_waitcnt lgkmcnt(0)
	v_mfma_f32_16x16x32_bf16 v[38:41], v[38:41], v[12:15], v[42:45]
	s_nop 2
	ds_read_b64_tr_b16 v[42:43], v182 offset:17536
	ds_read_b64_tr_b16 v[44:45], v182 offset:21888
	s_waitcnt lgkmcnt(0)
	v_mfma_f32_16x16x32_bf16 v[42:45], v[42:45], v[12:15], v[46:49]
	s_nop 2
	ds_read_b64_tr_b16 v[46:47], v182 offset:17568
	ds_read_b64_tr_b16 v[48:49], v182 offset:21920
	s_waitcnt lgkmcnt(0)
	v_mfma_f32_16x16x32_bf16 v[46:49], v[46:49], v[12:15], v[50:53]
	s_nop 2
	ds_read_b64_tr_b16 v[50:51], v182 offset:17600
	ds_read_b64_tr_b16 v[52:53], v182 offset:21952
	s_waitcnt lgkmcnt(0)
	v_mfma_f32_16x16x32_bf16 v[50:53], v[50:53], v[12:15], v[54:57]
	s_nop 2
	ds_read_b64_tr_b16 v[54:55], v182 offset:17632
	ds_read_b64_tr_b16 v[56:57], v182 offset:21984
	s_waitcnt lgkmcnt(0)
; #define LAS __attribute__((address_space(3)))
; __device__ __forceinline__ s16x4 vtr(const LAS char* p) { return __builtin_bit_cast(s16x4, __builtin_amdgcn_ds_read_tr16_b64_v4i16((LAS s16x4*)p)); }
; template <int NKS>
; __device__ __forceinline__ void pv_accum(f32x4 (&o)[8], const LAS unsigned char* Vt, int key_row0, const bf16x8 (&pf)[NKS], int fr, int fq) {
; #pragma unroll
;     for (int ks = 0; ks < NKS; ++ks) {
;         const LAS char* p0 = (const LAS char*)Vt + (key_row0 + 32 * ks + 4 * fq + (fr >> 2)) * AT_PITCH + 8 * (fr & 3);
; #pragma unroll
;         for (int dt = 0; dt < 8; ++dt) { const s16x4 lo = vtr(p0 + 32 * dt), hi = vtr(p0 + 16 * AT_PITCH + 32 * dt);
;             const bf16x8 vf = {lo[0], lo[1], lo[2], lo[3], hi[0], hi[1], hi[2], hi[3]};
;             o[dt] = __builtin_amdgcn_mfma_f32_16x16x32_bf16(vf, pf[ks], o[dt], 0, 0, 0); }
;         asm volatile("" ::: "memory");
;     }
; }
; __device__ __forceinline__ void attnA_item(const Frame& F, const Args& a, int item) {
;     ...
;     pv_accum<6>(o, R1, 64 * hb, pf, fr, fq);
;     const float inv = 1.0f / sum;
;     bf16_t* orow = (g == 0) ? (bf16_t*)a.out + qrow * YP + hh * 128 : (bf16_t*)((unsigned char*)a.out + DO_O12) + qrow * 1024 + (g - 1) * 512 + hh * 128;
	v_mfma_f32_16x16x32_bf16 v[12:15], v[54:57], v[12:15], v[16:19]
	s_nop 2
	ds_read_b64_tr_b16 v[18:19], v182 offset:30464
	ds_read_b64_tr_b16 v[16:17], v182 offset:26112
	ds_read_b64_tr_b16 v[54:55], v182 offset:26144
	ds_read_b64_tr_b16 v[56:57], v182 offset:30496
	s_waitcnt lgkmcnt(2)
	v_mfma_f32_16x16x32_bf16 v[16:19], v[16:19], v[8:11], v[20:23]
	s_waitcnt lgkmcnt(0)
	v_mfma_f32_16x16x32_bf16 v[20:23], v[54:57], v[8:11], v[24:27]
	s_nop 2
	ds_read_b64_tr_b16 v[24:25], v182 offset:26176
	ds_read_b64_tr_b16 v[26:27], v182 offset:30528
	s_waitcnt lgkmcnt(0)
	v_mfma_f32_16x16x32_bf16 v[24:27], v[24:27], v[8:11], v[28:31]
	s_nop 2
	ds_read_b64_tr_b16 v[28:29], v182 offset:26208
	ds_read_b64_tr_b16 v[30:31], v182 offset:30560
	s_waitcnt lgkmcnt(0)
	v_mfma_f32_16x16x32_bf16 v[28:31], v[28:31], v[8:11], v[38:41]
	s_nop 2
	ds_read_b64_tr_b16 v[38:39], v182 offset:26240
	ds_read_b64_tr_b16 v[40:41], v182 offset:30592
	s_waitcnt lgkmcnt(0)
	v_mfma_f32_16x16x32_bf16 v[38:41], v[38:41], v[8:11], v[42:45]
	s_nop 2
	ds_read_b64_tr_b16 v[42:43], v182 offset:26272
	ds_read_b64_tr_b16 v[44:45], v182 offset:30624
	s_waitcnt lgkmcnt(0)
	v_mfma_f32_16x16x32_bf16 v[42:45], v[42:45], v[8:11], v[46:49]
	s_nop 2
	ds_read_b64_tr_b16 v[46:47], v182 offset:26304
	ds_read_b64_tr_b16 v[48:49], v182 offset:30656
	s_waitcnt lgkmcnt(0)
	v_mfma_f32_16x16x32_bf16 v[46:49], v[46:49], v[8:11], v[50:53]
	s_nop 2
	ds_read_b64_tr_b16 v[50:51], v182 offset:26336
	ds_read_b64_tr_b16 v[52:53], v182 offset:30688
	s_waitcnt lgkmcnt(0)
	v_mfma_f32_16x16x32_bf16 v[8:11], v[50:53], v[8:11], v[12:15]
	s_nop 2
	ds_read_b64_tr_b16 v[14:15], v182 offset:39168
	ds_read_b64_tr_b16 v[12:13], v182 offset:34816
	ds_read_b64_tr_b16 v[50:51], v182 offset:34848
	ds_read_b64_tr_b16 v[52:53], v182 offset:39200
	s_waitcnt lgkmcnt(2)
	v_mfma_f32_16x16x32_bf16 v[12:15], v[12:15], v[4:7], v[16:19]
	s_waitcnt lgkmcnt(0)
	v_mfma_f32_16x16x32_bf16 v[16:19], v[50:53], v[4:7], v[20:23]
	s_nop 2
	ds_read_b64_tr_b16 v[20:21], v182 offset:34880
	ds_read_b64_tr_b16 v[22:23], v182 offset:39232
	s_waitcnt lgkmcnt(0)
	v_mfma_f32_16x16x32_bf16 v[20:23], v[20:23], v[4:7], v[24:27]
	s_nop 2
	ds_read_b64_tr_b16 v[24:25], v182 offset:34912
	ds_read_b64_tr_b16 v[26:27], v182 offset:39264
	s_waitcnt lgkmcnt(0)
	v_mfma_f32_16x16x32_bf16 v[24:27], v[24:27], v[4:7], v[28:31]
	s_nop 2
	ds_read_b64_tr_b16 v[28:29], v182 offset:34944
	ds_read_b64_tr_b16 v[30:31], v182 offset:39296
	s_waitcnt lgkmcnt(0)
	v_mfma_f32_16x16x32_bf16 v[28:31], v[28:31], v[4:7], v[38:41]
	s_nop 2
	ds_read_b64_tr_b16 v[38:39], v182 offset:34976
	ds_read_b64_tr_b16 v[40:41], v182 offset:39328
	s_waitcnt lgkmcnt(0)
	v_mfma_f32_16x16x32_bf16 v[38:41], v[38:41], v[4:7], v[42:45]
	s_nop 2
	ds_read_b64_tr_b16 v[42:43], v182 offset:35008
	ds_read_b64_tr_b16 v[44:45], v182 offset:39360
	s_waitcnt lgkmcnt(0)
	v_mfma_f32_16x16x32_bf16 v[42:45], v[42:45], v[4:7], v[46:49]
	s_nop 2
	ds_read_b64_tr_b16 v[46:47], v182 offset:35040
	ds_read_b64_tr_b16 v[48:49], v182 offset:39392
	s_waitcnt lgkmcnt(0)
	v_mfma_f32_16x16x32_bf16 v[46:49], v[46:49], v[4:7], v[8:11]
	ds_read_b64_tr_b16 v[6:7], v182 offset:47872
	ds_read_b64_tr_b16 v[4:5], v182 offset:43520
	s_nop 0
	ds_read_b64_tr_b16 v[8:9], v182 offset:43552
	ds_read_b64_tr_b16 v[10:11], v182 offset:47904
	s_waitcnt lgkmcnt(2)
	v_mfma_f32_16x16x32_bf16 v[4:7], v[4:7], v[0:3], v[12:15]
	s_nop 2
	ds_read_b64_tr_b16 v[12:13], v182 offset:43584
	ds_read_b64_tr_b16 v[14:15], v182 offset:47936
	s_waitcnt lgkmcnt(2)
	v_mfma_f32_16x16x32_bf16 v[8:11], v[8:11], v[0:3], v[16:19]
	s_nop 2
	ds_read_b64_tr_b16 v[16:17], v182 offset:43616
	ds_read_b64_tr_b16 v[18:19], v182 offset:47968
	s_waitcnt lgkmcnt(2)
	v_mfma_f32_16x16x32_bf16 v[12:15], v[12:15], v[0:3], v[20:23]
	s_nop 2
	ds_read_b64_tr_b16 v[20:21], v182 offset:43648
	ds_read_b64_tr_b16 v[22:23], v182 offset:48000
	s_waitcnt lgkmcnt(2)
	v_mfma_f32_16x16x32_bf16 v[16:19], v[16:19], v[0:3], v[24:27]
	s_nop 2
	ds_read_b64_tr_b16 v[24:25], v182 offset:43680
	ds_read_b64_tr_b16 v[26:27], v182 offset:48032
	s_waitcnt lgkmcnt(2)
	v_mfma_f32_16x16x32_bf16 v[20:23], v[20:23], v[0:3], v[28:31]
	s_nop 2
	ds_read_b64_tr_b16 v[28:29], v182 offset:43712
	ds_read_b64_tr_b16 v[30:31], v182 offset:48064
	s_waitcnt lgkmcnt(2)
	v_mfma_f32_16x16x32_bf16 v[24:27], v[24:27], v[0:3], v[38:41]
	s_nop 2
	ds_read_b64_tr_b16 v[38:39], v182 offset:43744
	ds_read_b64_tr_b16 v[40:41], v182 offset:48096
	s_waitcnt lgkmcnt(2)
	v_mfma_f32_16x16x32_bf16 v[28:31], v[28:31], v[0:3], v[42:45]
	s_waitcnt lgkmcnt(0)
	v_mfma_f32_16x16x32_bf16 v[0:3], v[38:41], v[0:3], v[46:49]
	s_cbranch_scc0 .LBB0_566
	v_lshlrev_b64 v[32:33], 11, v[60:61]
	s_lshl_b32 s8, s5, 9
	v_lshl_add_u64 v[32:33], s[20:21], 0, v[32:33]
	s_ashr_i32 s9, s8, 31
	v_lshl_add_u64 v[32:33], s[8:9], 1, v[32:33]
	s_mov_b64 s[8:9], 0x5fffc00
	v_lshl_add_u64 v[32:33], v[32:33], 0, s[8:9]
	s_and_b32 s6, s2, 0x180
	s_mov_b64 s[8:9], 0

; __device__ __forceinline__ float sigmoidf_(float x) { return 1.0f / (1.0f + __expf(-x)); }
;     __device__ __forceinline__ void operator()(const f32x4 (&acc)[2][2][4][2], const Unit& u, int wr, int wc, int fr, int fq) const {
;         const int row0 = u.pm * BM + wr * 64 + fr; const int col0 = u.pn * BM + wc * 32 + 8 * fq;
;         f32x4 bv[2][2];
; #pragma unroll
;         for (int bj = 0; bj < 2; ++bj)
; #pragma unroll
;             for (int n = 0; n < 2; ++n) bv[bj][n] = *(const f32x4*)(bias + col0 + bj * HALF + 4 * n);
; #pragma unroll
;         for (int ai = 0; ai < 2; ++ai)
; #pragma unroll
;             for (int m = 0; m < 4; ++m) { unsigned char* rowp = O + (size_t)(row0 + ai * HALF + m * 16) * GP8 + col0;
; #pragma unroll
;                 for (int bj = 0; bj < 2; ++bj) { const f32x4 v0 = acc[ai][bj][m][0] + bv[bj][0], v1 = acc[ai][bj][m][1] + bv[bj][1];
;                     unsigned q[8];
; #pragma unroll
;                     for (int j = 0; j < 4; ++j) { q[j] = (unsigned)fmaxf(__builtin_rintf(sigmoidf_(v0[j]) * 255.f), 1.f); q[4 + j] = (unsigned)fmaxf(__builtin_rintf(sigmoidf_(v1[j]) * 255.f), 1.f); }
;                     u32x2 w; w.x = q[0] | (q[1] << 8) | (q[2] << 16) | (q[3] << 24); w.y = q[4] | (q[5] << 8) | (q[6] << 16) | (q[7] << 24);
;                     *(u32x2*)(rowp + bj * HALF) = w; } }
.LBB0_793:
	v_lshl_or_b32 v162, s9, 8, v169
	v_ashrrev_i32_e32 v163, 31, v162
	v_lshl_add_u64 v[36:37], v[162:163], 2, s[78:79]
	global_load_dwordx4 v[52:55], v[36:37], off
	global_load_dwordx4 v[48:51], v[36:37], off offset:16
	v_lshl_add_u32 v173, s8, 8, v145
	v_mov_b64_e32 v[164:165], s[12:13]
	v_mad_i64_i32 v[32:33], s[2:3], v173, s55, v[164:165]
	v_lshl_add_u64 v[166:167], v[32:33], 0, v[162:163]
	global_load_dwordx4 v[32:35], v[36:37], off offset:528
	s_nop 0
	global_load_dwordx4 v[36:39], v[36:37], off offset:512
	s_waitcnt vmcnt(0)
	s_mov_b32 s100, 0xbfb8aa3b
	v_mul_f32_e32 v32, 0xbfb8aa3b, v32
	v_mul_f32_e32 v33, 0xbfb8aa3b, v33
	v_mul_f32_e32 v34, 0xbfb8aa3b, v34
	v_mul_f32_e32 v35, 0xbfb8aa3b, v35
	v_mul_f32_e32 v36, 0xbfb8aa3b, v36
	v_mul_f32_e32 v37, 0xbfb8aa3b, v37
	v_mul_f32_e32 v38, 0xbfb8aa3b, v38
	v_mul_f32_e32 v39, 0xbfb8aa3b, v39
	v_mul_f32_e32 v48, 0xbfb8aa3b, v48
	v_mul_f32_e32 v49, 0xbfb8aa3b, v49
	v_mul_f32_e32 v50, 0xbfb8aa3b, v50
	v_mul_f32_e32 v51, 0xbfb8aa3b, v51
	v_mul_f32_e32 v52, 0xbfb8aa3b, v52
	v_mul_f32_e32 v53, 0xbfb8aa3b, v53
	v_mul_f32_e32 v54, 0xbfb8aa3b, v54
	v_mul_f32_e32 v55, 0xbfb8aa3b, v55
	v_fma_f32 v140, v140, s100, v52
	v_fma_f32 v136, v136, s100, v48
	v_exp_f32_e32 v140, v140
	v_fma_f32 v141, v141, s100, v53
	v_fma_f32 v142, v142, s100, v54
	v_exp_f32_e32 v136, v136
	v_exp_f32_e32 v141, v141
	v_exp_f32_e32 v142, v142
	v_fma_f32 v137, v137, s100, v49
	v_add_f32_e32 v140, 1.0, v140
	v_exp_f32_e32 v137, v137
	v_add_f32_e32 v136, 1.0, v136
	v_add_f32_e32 v141, 1.0, v141
	v_add_f32_e32 v142, 1.0, v142
	v_add_f32_e32 v137, 1.0, v137
	v_rcp_f32_e32 v140, v140
	v_rcp_f32_e32 v136, v136
	s_nop 0
	v_mul_f32_e32 v136, 0x437f0000, v136
	v_rcp_f32_e32 v141, v141
	v_rndne_f32_e32 v136, v136
	v_mul_f32_e32 v141, 0x437f0000, v141
	v_max_f32_e32 v136, 1.0, v136
	v_rndne_f32_e32 v141, v141
	v_rcp_f32_e32 v137, v137
	v_cvt_u32_f32_e32 v174, v136
	v_max_f32_e32 v136, 1.0, v141
	v_fma_f32 v138, v138, s100, v50
	v_exp_f32_e32 v138, v138
	s_nop 0
	v_add_f32_e32 v138, 1.0, v138
	v_rcp_f32_e32 v141, v142
	v_fma_f32 v143, v143, s100, v55
	v_exp_f32_e32 v143, v143
	v_rcp_f32_e32 v138, v138
	v_add_f32_e32 v142, 1.0, v143
	v_fma_f32 v139, v139, s100, v51
	v_exp_f32_e32 v139, v139
	s_nop 0
	v_add_f32_e32 v139, 1.0, v139
	v_rcp_f32_e32 v142, v142
	v_mul_f32_e32 v140, 0x437f0000, v140
	v_rndne_f32_e32 v140, v140
	v_mul_f32_e32 v141, 0x437f0000, v141
	v_mul_f32_e32 v142, 0x437f0000, v142
	v_fma_f32 v132, v132, s100, v36
	v_max_f32_e32 v140, 1.0, v140
	v_rndne_f32_e32 v141, v141
	v_rndne_f32_e32 v142, v142
	v_exp_f32_e32 v132, v132
	v_cvt_u32_f32_e32 v140, v140
	v_mul_f32_e32 v137, 0x437f0000, v137
	v_cvt_u32_f32_e32 v136, v136
	v_max_f32_e32 v141, 1.0, v141
	v_max_f32_e32 v142, 1.0, v142
	v_rcp_f32_e32 v139, v139
	v_rndne_f32_e32 v137, v137
	v_cvt_u32_f32_sdwa v141, v141 dst_sel:WORD_1 dst_unused:UNUSED_PAD src0_sel:DWORD
	v_mul_f32_e32 v138, 0x437f0000, v138
	v_cvt_u32_f32_sdwa v142, v142 dst_sel:BYTE_3 dst_unused:UNUSED_PAD src0_sel:DWORD
	v_mul_f32_e32 v139, 0x437f0000, v139
	v_max_f32_e32 v137, 1.0, v137
	v_rndne_f32_e32 v138, v138
	v_rndne_f32_e32 v139, v139
	v_cvt_u32_f32_e32 v137, v137
	v_max_f32_e32 v138, 1.0, v138
	v_max_f32_e32 v139, 1.0, v139
	v_add_f32_e32 v132, 1.0, v132
	v_cvt_u32_f32_sdwa v138, v138 dst_sel:WORD_1 dst_unused:UNUSED_PAD src0_sel:DWORD
	v_cvt_u32_f32_sdwa v139, v139 dst_sel:BYTE_3 dst_unused:UNUSED_PAD src0_sel:DWORD
	v_lshl_or_b32 v136, v136, 8, v140
	v_or3_b32 v136, v136, v141, v142
	v_lshl_or_b32 v137, v137, 8, v174
	v_or3_b32 v137, v137, v138, v139
	global_store_dwordx2 v[166:167], v[136:137], off
	v_fma_f32 v128, v128, s100, v32
	v_exp_f32_e32 v128, v128
	s_nop 0
	v_add_f32_e32 v128, 1.0, v128
	v_rcp_f32_e32 v132, v132
	v_fma_f32 v133, v133, s100, v37
	v_exp_f32_e32 v133, v133
	s_nop 0
	v_add_f32_e32 v133, 1.0, v133
	v_rcp_f32_e32 v128, v128
	s_nop 0
	v_mul_f32_e32 v128, 0x437f0000, v128
	v_rndne_f32_e32 v128, v128
	v_max_f32_e32 v128, 1.0, v128
	v_cvt_u32_f32_e32 v138, v128
	v_fma_f32 v129, v129, s100, v33
	v_exp_f32_e32 v129, v129
	s_nop 0
	v_add_f32_e32 v129, 1.0, v129
	v_rcp_f32_e32 v128, v133
	v_fma_f32 v134, v134, s100, v38
	v_exp_f32_e32 v134, v134
	v_rcp_f32_e32 v129, v129
	v_add_f32_e32 v133, 1.0, v134
	v_fma_f32 v130, v130, s100, v34
	v_exp_f32_e32 v130, v130
	s_nop 0
	v_add_f32_e32 v130, 1.0, v130
	v_rcp_f32_e32 v133, v133
	v_fma_f32 v135, v135, s100, v39
	v_exp_f32_e32 v135, v135
	v_rcp_f32_e32 v130, v130
	v_add_f32_e32 v134, 1.0, v135
	v_fma_f32 v131, v131, s100, v35
	v_exp_f32_e32 v131, v131
	s_nop 0
	v_add_f32_e32 v131, 1.0, v131
	v_rcp_f32_e32 v134, v134
	v_mul_f32_e32 v129, 0x437f0000, v129
	v_rndne_f32_e32 v129, v129
	v_mul_f32_e32 v130, 0x437f0000, v130
	v_rcp_f32_e32 v131, v131
	s_nop 0
	v_mul_f32_e32 v131, 0x437f0000, v131
	v_max_f32_e32 v129, 1.0, v129
	v_rndne_f32_e32 v130, v130
	v_rndne_f32_e32 v131, v131
	v_fma_f32 v124, v124, s100, v52
	v_cvt_u32_f32_e32 v129, v129
	v_max_f32_e32 v130, 1.0, v130
	v_max_f32_e32 v131, 1.0, v131
	v_exp_f32_e32 v124, v124
	v_cvt_u32_f32_sdwa v130, v130 dst_sel:WORD_1 dst_unused:UNUSED_PAD src0_sel:DWORD
	v_cvt_u32_f32_sdwa v131, v131 dst_sel:BYTE_3 dst_unused:UNUSED_PAD src0_sel:DWORD
	v_mul_f32_e32 v132, 0x437f0000, v132
	v_mul_f32_e32 v128, 0x437f0000, v128
	v_rndne_f32_e32 v132, v132
	v_rndne_f32_e32 v128, v128
	v_lshl_or_b32 v129, v129, 8, v138
	v_add_f32_e32 v124, 1.0, v124
	v_max_f32_e32 v132, 1.0, v132
	v_max_f32_e32 v128, 1.0, v128
	v_mul_f32_e32 v133, 0x437f0000, v133
	v_mul_f32_e32 v134, 0x437f0000, v134
	v_or3_b32 v129, v129, v130, v131
	v_cvt_u32_f32_e32 v132, v132
	v_cvt_u32_f32_e32 v128, v128
	v_rndne_f32_e32 v133, v133
; __device__ __forceinline__ float sigmoidf_(float x) { return 1.0f / (1.0f + __expf(-x)); }
;     __device__ __forceinline__ void operator()(const f32x4 (&acc)[2][2][4][2], const Unit& u, int wr, int wc, int fr, int fq) const {
;     ...
;             for (int m = 0; m < 4; ++m) { unsigned char* rowp = O + (size_t)(row0 + ai * HALF + m * 16) * GP8 + col0;
; #pragma unroll
;                 for (int bj = 0; bj < 2; ++bj) { const f32x4 v0 = acc[ai][bj][m][0] + bv[bj][0], v1 = acc[ai][bj][m][1] + bv[bj][1];
;                     unsigned q[8];
; #pragma unroll
;                     for (int j = 0; j < 4; ++j) { q[j] = (unsigned)fmaxf(__builtin_rintf(sigmoidf_(v0[j]) * 255.f), 1.f); q[4 + j] = (unsigned)fmaxf(__builtin_rintf(sigmoidf_(v1[j]) * 255.f), 1.f); }
;                     u32x2 w; w.x = q[0] | (q[1] << 8) | (q[2] << 16) | (q[3] << 24); w.y = q[4] | (q[5] << 8) | (q[6] << 16) | (q[7] << 24);
;                     *(u32x2*)(rowp + bj * HALF) = w; } }
	v_rndne_f32_e32 v134, v134
	v_max_f32_e32 v133, 1.0, v133
	v_max_f32_e32 v134, 1.0, v134
	v_cvt_u32_f32_sdwa v133, v133 dst_sel:WORD_1 dst_unused:UNUSED_PAD src0_sel:DWORD
	v_cvt_u32_f32_sdwa v134, v134 dst_sel:BYTE_3 dst_unused:UNUSED_PAD src0_sel:DWORD
	v_lshl_or_b32 v128, v128, 8, v132
	v_fma_f32 v120, v120, s100, v48
	v_or3_b32 v128, v128, v133, v134
	v_exp_f32_e32 v120, v120
	s_nop 0
	v_add_f32_e32 v120, 1.0, v120
	v_rcp_f32_e32 v124, v124
	v_fma_f32 v125, v125, s100, v53
	v_exp_f32_e32 v125, v125
	s_nop 0
	v_add_f32_e32 v125, 1.0, v125
	v_rcp_f32_e32 v120, v120
	s_nop 0
	v_mul_f32_e32 v120, 0x437f0000, v120
	v_rndne_f32_e32 v120, v120
	v_max_f32_e32 v120, 1.0, v120
	v_cvt_u32_f32_e32 v132, v120
	v_fma_f32 v121, v121, s100, v49
	v_exp_f32_e32 v121, v121
	s_nop 0
	v_add_f32_e32 v121, 1.0, v121
	v_rcp_f32_e32 v120, v125
	v_fma_f32 v126, v126, s100, v54
	v_exp_f32_e32 v126, v126
	v_rcp_f32_e32 v121, v121
	v_add_f32_e32 v125, 1.0, v126
	v_fma_f32 v122, v122, s100, v50
	v_exp_f32_e32 v122, v122
	s_nop 0
	v_add_f32_e32 v122, 1.0, v122
	v_rcp_f32_e32 v125, v125
	v_fma_f32 v127, v127, s100, v55
	v_exp_f32_e32 v127, v127
	v_rcp_f32_e32 v122, v122
	v_add_f32_e32 v126, 1.0, v127
	v_fma_f32 v123, v123, s100, v51
	v_exp_f32_e32 v123, v123
	s_nop 0
	v_add_f32_e32 v123, 1.0, v123
	v_rcp_f32_e32 v126, v126
	v_mul_f32_e32 v124, 0x437f0000, v124
	v_mul_f32_e32 v120, 0x437f0000, v120
	v_rndne_f32_e32 v124, v124
	v_rndne_f32_e32 v120, v120
	v_mul_f32_e32 v125, 0x437f0000, v125
	v_mul_f32_e32 v126, 0x437f0000, v126
	v_fma_f32 v116, v116, s100, v36
	v_max_f32_e32 v124, 1.0, v124
	v_max_f32_e32 v120, 1.0, v120
	v_rndne_f32_e32 v125, v125
	v_rndne_f32_e32 v126, v126
	v_exp_f32_e32 v116, v116
	v_cvt_u32_f32_e32 v124, v124
	v_cvt_u32_f32_e32 v120, v120
	v_mul_f32_e32 v121, 0x437f0000, v121
	v_max_f32_e32 v125, 1.0, v125
	v_max_f32_e32 v126, 1.0, v126
	v_rcp_f32_e32 v123, v123
	v_rndne_f32_e32 v121, v121
	v_cvt_u32_f32_sdwa v125, v125 dst_sel:WORD_1 dst_unused:UNUSED_PAD src0_sel:DWORD
	v_mul_f32_e32 v122, 0x437f0000, v122
	v_cvt_u32_f32_sdwa v126, v126 dst_sel:BYTE_3 dst_unused:UNUSED_PAD src0_sel:DWORD
	v_mul_f32_e32 v123, 0x437f0000, v123
	v_max_f32_e32 v121, 1.0, v121
	v_rndne_f32_e32 v122, v122
	v_rndne_f32_e32 v123, v123
	v_cvt_u32_f32_e32 v121, v121
	v_max_f32_e32 v122, 1.0, v122
	v_max_f32_e32 v123, 1.0, v123
	v_add_f32_e32 v116, 1.0, v116
	v_cvt_u32_f32_sdwa v122, v122 dst_sel:WORD_1 dst_unused:UNUSED_PAD src0_sel:DWORD
	v_cvt_u32_f32_sdwa v123, v123 dst_sel:BYTE_3 dst_unused:UNUSED_PAD src0_sel:DWORD
	v_lshl_or_b32 v120, v120, 8, v124
	v_or3_b32 v120, v120, v125, v126
	global_store_dwordx2 v[166:167], v[128:129], off offset:128
	v_or_b32_e32 v128, 16, v173
	v_mad_i64_i32 v[128:129], s[2:3], v128, s55, v[164:165]
	v_lshl_or_b32 v121, v121, 8, v132
	v_lshl_add_u64 v[128:129], v[128:129], 0, v[162:163]
	v_or3_b32 v121, v121, v122, v123
	global_store_dwordx2 v[128:129], v[120:121], off
	v_fma_f32 v112, v112, s100, v32
	v_exp_f32_e32 v112, v112
	s_nop 0
	v_add_f32_e32 v112, 1.0, v112
	v_rcp_f32_e32 v116, v116
	v_fma_f32 v117, v117, s100, v37
	v_exp_f32_e32 v117, v117
	s_nop 0
	v_add_f32_e32 v117, 1.0, v117
	v_rcp_f32_e32 v112, v112
	s_nop 0
	v_mul_f32_e32 v112, 0x437f0000, v112
	v_rndne_f32_e32 v112, v112
	v_max_f32_e32 v112, 1.0, v112
	v_cvt_u32_f32_e32 v122, v112
	v_fma_f32 v113, v113, s100, v33
	v_exp_f32_e32 v113, v113
	s_nop 0
	v_add_f32_e32 v113, 1.0, v113
	v_rcp_f32_e32 v112, v117
	v_fma_f32 v118, v118, s100, v38
	v_exp_f32_e32 v118, v118
	v_rcp_f32_e32 v113, v113
	v_add_f32_e32 v117, 1.0, v118
	v_fma_f32 v114, v114, s100, v34
	v_exp_f32_e32 v114, v114
	s_nop 0
	v_add_f32_e32 v114, 1.0, v114
	v_rcp_f32_e32 v117, v117
	v_fma_f32 v119, v119, s100, v39
	v_exp_f32_e32 v119, v119
	v_rcp_f32_e32 v114, v114
	v_add_f32_e32 v118, 1.0, v119
	v_fma_f32 v115, v115, s100, v35
	v_exp_f32_e32 v115, v115
	s_nop 0
	v_add_f32_e32 v115, 1.0, v115
	v_rcp_f32_e32 v118, v118
	v_mul_f32_e32 v113, 0x437f0000, v113
	v_rndne_f32_e32 v113, v113
	v_mul_f32_e32 v114, 0x437f0000, v114
	v_rcp_f32_e32 v115, v115
	s_nop 0
	v_mul_f32_e32 v115, 0x437f0000, v115
	v_max_f32_e32 v113, 1.0, v113
	v_rndne_f32_e32 v114, v114
	v_rndne_f32_e32 v115, v115
	v_fma_f32 v108, v108, s100, v52
	v_cvt_u32_f32_e32 v113, v113
	v_max_f32_e32 v114, 1.0, v114
	v_max_f32_e32 v115, 1.0, v115
	v_exp_f32_e32 v108, v108
	v_cvt_u32_f32_sdwa v114, v114 dst_sel:WORD_1 dst_unused:UNUSED_PAD src0_sel:DWORD
	v_cvt_u32_f32_sdwa v115, v115 dst_sel:BYTE_3 dst_unused:UNUSED_PAD src0_sel:DWORD
	v_mul_f32_e32 v116, 0x437f0000, v116
	v_mul_f32_e32 v112, 0x437f0000, v112
	v_rndne_f32_e32 v116, v116
	v_rndne_f32_e32 v112, v112
	v_lshl_or_b32 v113, v113, 8, v122
	v_add_f32_e32 v108, 1.0, v108
	v_max_f32_e32 v116, 1.0, v116
	v_max_f32_e32 v112, 1.0, v112
	v_mul_f32_e32 v117, 0x437f0000, v117
	v_mul_f32_e32 v118, 0x437f0000, v118
	v_or3_b32 v113, v113, v114, v115
	v_cvt_u32_f32_e32 v116, v116
	v_cvt_u32_f32_e32 v112, v112
	v_rndne_f32_e32 v117, v117
	v_rndne_f32_e32 v118, v118
	v_max_f32_e32 v117, 1.0, v117
	v_max_f32_e32 v118, 1.0, v118
	v_cvt_u32_f32_sdwa v117, v117 dst_sel:WORD_1 dst_unused:UNUSED_PAD src0_sel:DWORD
	v_cvt_u32_f32_sdwa v118, v118 dst_sel:BYTE_3 dst_unused:UNUSED_PAD src0_sel:DWORD
	v_lshl_or_b32 v112, v112, 8, v116
	v_fma_f32 v104, v104, s100, v48
	v_or3_b32 v112, v112, v117, v118
	v_exp_f32_e32 v104, v104
	s_nop 0
	v_add_f32_e32 v104, 1.0, v104
	v_rcp_f32_e32 v108, v108
	v_fma_f32 v109, v109, s100, v53
	v_exp_f32_e32 v109, v109
	s_nop 0
	v_add_f32_e32 v109, 1.0, v109
	v_rcp_f32_e32 v104, v104
	s_nop 0
	v_mul_f32_e32 v104, 0x437f0000, v104
	v_rndne_f32_e32 v104, v104
	v_max_f32_e32 v104, 1.0, v104
; __device__ __forceinline__ float sigmoidf_(float x) { return 1.0f / (1.0f + __expf(-x)); }
;     __device__ __forceinline__ void operator()(const f32x4 (&acc)[2][2][4][2], const Unit& u, int wr, int wc, int fr, int fq) const {
;     ...
;             for (int m = 0; m < 4; ++m) { unsigned char* rowp = O + (size_t)(row0 + ai * HALF + m * 16) * GP8 + col0;
; #pragma unroll
;                 for (int bj = 0; bj < 2; ++bj) { const f32x4 v0 = acc[ai][bj][m][0] + bv[bj][0], v1 = acc[ai][bj][m][1] + bv[bj][1];
;                     unsigned q[8];
; #pragma unroll
;                     for (int j = 0; j < 4; ++j) { q[j] = (unsigned)fmaxf(__builtin_rintf(sigmoidf_(v0[j]) * 255.f), 1.f); q[4 + j] = (unsigned)fmaxf(__builtin_rintf(sigmoidf_(v1[j]) * 255.f), 1.f); }
;                     u32x2 w; w.x = q[0] | (q[1] << 8) | (q[2] << 16) | (q[3] << 24); w.y = q[4] | (q[5] << 8) | (q[6] << 16) | (q[7] << 24);
;                     *(u32x2*)(rowp + bj * HALF) = w; } }
	v_cvt_u32_f32_e32 v116, v104
	v_fma_f32 v105, v105, s100, v49
	v_exp_f32_e32 v105, v105
	s_nop 0
	v_add_f32_e32 v105, 1.0, v105
	v_rcp_f32_e32 v104, v109
	v_fma_f32 v110, v110, s100, v54
	v_exp_f32_e32 v110, v110
	v_rcp_f32_e32 v105, v105
	v_add_f32_e32 v109, 1.0, v110
	v_fma_f32 v106, v106, s100, v50
	v_exp_f32_e32 v106, v106
	s_nop 0
	v_add_f32_e32 v106, 1.0, v106
	v_rcp_f32_e32 v109, v109
	v_fma_f32 v111, v111, s100, v55
	v_exp_f32_e32 v111, v111
	v_rcp_f32_e32 v106, v106
	v_add_f32_e32 v110, 1.0, v111
	v_fma_f32 v107, v107, s100, v51
	v_exp_f32_e32 v107, v107
	s_nop 0
	v_add_f32_e32 v107, 1.0, v107
	v_rcp_f32_e32 v110, v110
	v_mul_f32_e32 v108, 0x437f0000, v108
	v_mul_f32_e32 v104, 0x437f0000, v104
	v_rndne_f32_e32 v108, v108
	v_rndne_f32_e32 v104, v104
	v_mul_f32_e32 v109, 0x437f0000, v109
	v_mul_f32_e32 v110, 0x437f0000, v110
	v_fma_f32 v100, v100, s100, v36
	v_max_f32_e32 v108, 1.0, v108
	v_max_f32_e32 v104, 1.0, v104
	v_rndne_f32_e32 v109, v109
	v_rndne_f32_e32 v110, v110
	v_exp_f32_e32 v100, v100
	v_cvt_u32_f32_e32 v108, v108
	v_cvt_u32_f32_e32 v104, v104
	v_mul_f32_e32 v105, 0x437f0000, v105
	v_max_f32_e32 v109, 1.0, v109
	v_max_f32_e32 v110, 1.0, v110
	v_rcp_f32_e32 v107, v107
	v_rndne_f32_e32 v105, v105
	v_cvt_u32_f32_sdwa v109, v109 dst_sel:WORD_1 dst_unused:UNUSED_PAD src0_sel:DWORD
	v_mul_f32_e32 v106, 0x437f0000, v106
	v_cvt_u32_f32_sdwa v110, v110 dst_sel:BYTE_3 dst_unused:UNUSED_PAD src0_sel:DWORD
	v_mul_f32_e32 v107, 0x437f0000, v107
	v_max_f32_e32 v105, 1.0, v105
	v_rndne_f32_e32 v106, v106
	v_rndne_f32_e32 v107, v107
	v_cvt_u32_f32_e32 v105, v105
	v_max_f32_e32 v106, 1.0, v106
	v_max_f32_e32 v107, 1.0, v107
	v_add_f32_e32 v100, 1.0, v100
	v_cvt_u32_f32_sdwa v106, v106 dst_sel:WORD_1 dst_unused:UNUSED_PAD src0_sel:DWORD
	v_cvt_u32_f32_sdwa v107, v107 dst_sel:BYTE_3 dst_unused:UNUSED_PAD src0_sel:DWORD
	v_lshl_or_b32 v104, v104, 8, v108
	v_or3_b32 v104, v104, v109, v110
	global_store_dwordx2 v[128:129], v[112:113], off offset:128
	v_or_b32_e32 v112, 32, v173
	v_mad_i64_i32 v[112:113], s[2:3], v112, s55, v[164:165]
	v_lshl_or_b32 v105, v105, 8, v116
	v_lshl_add_u64 v[112:113], v[112:113], 0, v[162:163]
	v_or3_b32 v105, v105, v106, v107
	global_store_dwordx2 v[112:113], v[104:105], off
	v_fma_f32 v96, v96, s100, v32
	v_exp_f32_e32 v96, v96
	s_nop 0
	v_add_f32_e32 v96, 1.0, v96
	v_rcp_f32_e32 v100, v100
	v_fma_f32 v101, v101, s100, v37
	v_exp_f32_e32 v101, v101
	s_nop 0
	v_add_f32_e32 v101, 1.0, v101
	v_rcp_f32_e32 v96, v96
	s_nop 0
	v_mul_f32_e32 v96, 0x437f0000, v96
	v_rndne_f32_e32 v96, v96
	v_max_f32_e32 v96, 1.0, v96
	v_cvt_u32_f32_e32 v106, v96
	v_fma_f32 v97, v97, s100, v33
	v_exp_f32_e32 v97, v97
	s_nop 0
	v_add_f32_e32 v97, 1.0, v97
	v_rcp_f32_e32 v96, v101
	v_fma_f32 v102, v102, s100, v38
	v_exp_f32_e32 v102, v102
	v_rcp_f32_e32 v97, v97
	v_add_f32_e32 v101, 1.0, v102
	v_fma_f32 v98, v98, s100, v34
	v_exp_f32_e32 v98, v98
	s_nop 0
	v_add_f32_e32 v98, 1.0, v98
	v_rcp_f32_e32 v101, v101
	v_fma_f32 v103, v103, s100, v39
	v_exp_f32_e32 v103, v103
	v_rcp_f32_e32 v98, v98
	v_add_f32_e32 v102, 1.0, v103
	v_fma_f32 v99, v99, s100, v35
	v_exp_f32_e32 v99, v99
	s_nop 0
	v_add_f32_e32 v99, 1.0, v99
	v_rcp_f32_e32 v102, v102
	v_mul_f32_e32 v97, 0x437f0000, v97
	v_rndne_f32_e32 v97, v97
	v_mul_f32_e32 v98, 0x437f0000, v98
	v_rcp_f32_e32 v99, v99
	s_nop 0
	v_mul_f32_e32 v99, 0x437f0000, v99
	v_max_f32_e32 v97, 1.0, v97
	v_rndne_f32_e32 v98, v98
	v_rndne_f32_e32 v99, v99
	v_fma_f32 v92, v92, s100, v52
	v_cvt_u32_f32_e32 v97, v97
	v_max_f32_e32 v98, 1.0, v98
	v_max_f32_e32 v99, 1.0, v99
	v_exp_f32_e32 v92, v92
	v_cvt_u32_f32_sdwa v98, v98 dst_sel:WORD_1 dst_unused:UNUSED_PAD src0_sel:DWORD
	v_cvt_u32_f32_sdwa v99, v99 dst_sel:BYTE_3 dst_unused:UNUSED_PAD src0_sel:DWORD
	v_mul_f32_e32 v100, 0x437f0000, v100
	v_mul_f32_e32 v96, 0x437f0000, v96
	v_rndne_f32_e32 v100, v100
	v_rndne_f32_e32 v96, v96
	v_lshl_or_b32 v97, v97, 8, v106
	v_add_f32_e32 v92, 1.0, v92
	v_max_f32_e32 v100, 1.0, v100
	v_max_f32_e32 v96, 1.0, v96
	v_mul_f32_e32 v101, 0x437f0000, v101
	v_mul_f32_e32 v102, 0x437f0000, v102
	v_or3_b32 v97, v97, v98, v99
	v_cvt_u32_f32_e32 v100, v100
	v_cvt_u32_f32_e32 v96, v96
	v_rndne_f32_e32 v101, v101
	v_rndne_f32_e32 v102, v102
	v_max_f32_e32 v101, 1.0, v101
	v_max_f32_e32 v102, 1.0, v102
	v_cvt_u32_f32_sdwa v101, v101 dst_sel:WORD_1 dst_unused:UNUSED_PAD src0_sel:DWORD
	v_cvt_u32_f32_sdwa v102, v102 dst_sel:BYTE_3 dst_unused:UNUSED_PAD src0_sel:DWORD
	v_lshl_or_b32 v96, v96, 8, v100
	v_fma_f32 v88, v88, s100, v48
	v_or3_b32 v96, v96, v101, v102
	v_exp_f32_e32 v88, v88
	s_nop 0
	v_add_f32_e32 v88, 1.0, v88
	v_rcp_f32_e32 v92, v92
	v_fma_f32 v93, v93, s100, v53
	v_exp_f32_e32 v93, v93
	s_nop 0
	v_add_f32_e32 v93, 1.0, v93
	v_rcp_f32_e32 v88, v88
	s_nop 0
	v_mul_f32_e32 v88, 0x437f0000, v88
	v_rndne_f32_e32 v88, v88
	v_max_f32_e32 v88, 1.0, v88
	v_cvt_u32_f32_e32 v100, v88
	v_fma_f32 v89, v89, s100, v49
	v_exp_f32_e32 v89, v89
	s_nop 0
	v_add_f32_e32 v89, 1.0, v89
	v_rcp_f32_e32 v88, v93
	v_fma_f32 v94, v94, s100, v54
	v_exp_f32_e32 v94, v94
	v_rcp_f32_e32 v89, v89
	v_add_f32_e32 v93, 1.0, v94
	v_fma_f32 v90, v90, s100, v50
	v_exp_f32_e32 v90, v90
	s_nop 0
	v_add_f32_e32 v90, 1.0, v90
	v_rcp_f32_e32 v93, v93
	v_fma_f32 v95, v95, s100, v55
	v_exp_f32_e32 v95, v95
	v_rcp_f32_e32 v90, v90
	v_add_f32_e32 v94, 1.0, v95
	v_fma_f32 v91, v91, s100, v51
	v_exp_f32_e32 v91, v91
	s_nop 0
	v_add_f32_e32 v91, 1.0, v91
	v_rcp_f32_e32 v94, v94
	v_mul_f32_e32 v92, 0x437f0000, v92
	v_mul_f32_e32 v88, 0x437f0000, v88
	v_rndne_f32_e32 v92, v92
	v_rndne_f32_e32 v88, v88
	v_mul_f32_e32 v93, 0x437f0000, v93
	v_mul_f32_e32 v94, 0x437f0000, v94
; __device__ __forceinline__ float sigmoidf_(float x) { return 1.0f / (1.0f + __expf(-x)); }
;     __device__ __forceinline__ void operator()(const f32x4 (&acc)[2][2][4][2], const Unit& u, int wr, int wc, int fr, int fq) const {
;     ...
;             for (int m = 0; m < 4; ++m) { unsigned char* rowp = O + (size_t)(row0 + ai * HALF + m * 16) * GP8 + col0;
; #pragma unroll
;                 for (int bj = 0; bj < 2; ++bj) { const f32x4 v0 = acc[ai][bj][m][0] + bv[bj][0], v1 = acc[ai][bj][m][1] + bv[bj][1];
;                     unsigned q[8];
; #pragma unroll
;                     for (int j = 0; j < 4; ++j) { q[j] = (unsigned)fmaxf(__builtin_rintf(sigmoidf_(v0[j]) * 255.f), 1.f); q[4 + j] = (unsigned)fmaxf(__builtin_rintf(sigmoidf_(v1[j]) * 255.f), 1.f); }
;                     u32x2 w; w.x = q[0] | (q[1] << 8) | (q[2] << 16) | (q[3] << 24); w.y = q[4] | (q[5] << 8) | (q[6] << 16) | (q[7] << 24);
;                     *(u32x2*)(rowp + bj * HALF) = w; } }
	v_fma_f32 v84, v84, s100, v36
	v_max_f32_e32 v92, 1.0, v92
	v_max_f32_e32 v88, 1.0, v88
	v_rndne_f32_e32 v93, v93
	v_rndne_f32_e32 v94, v94
	v_exp_f32_e32 v84, v84
	v_cvt_u32_f32_e32 v92, v92
	v_cvt_u32_f32_e32 v88, v88
	v_mul_f32_e32 v89, 0x437f0000, v89
	v_max_f32_e32 v93, 1.0, v93
	v_max_f32_e32 v94, 1.0, v94
	v_rcp_f32_e32 v91, v91
	v_rndne_f32_e32 v89, v89
	v_cvt_u32_f32_sdwa v93, v93 dst_sel:WORD_1 dst_unused:UNUSED_PAD src0_sel:DWORD
	v_mul_f32_e32 v90, 0x437f0000, v90
	v_cvt_u32_f32_sdwa v94, v94 dst_sel:BYTE_3 dst_unused:UNUSED_PAD src0_sel:DWORD
	v_mul_f32_e32 v91, 0x437f0000, v91
	v_max_f32_e32 v89, 1.0, v89
	v_rndne_f32_e32 v90, v90
	v_rndne_f32_e32 v91, v91
	v_cvt_u32_f32_e32 v89, v89
	v_max_f32_e32 v90, 1.0, v90
	v_max_f32_e32 v91, 1.0, v91
	v_add_f32_e32 v84, 1.0, v84
	v_cvt_u32_f32_sdwa v90, v90 dst_sel:WORD_1 dst_unused:UNUSED_PAD src0_sel:DWORD
	v_cvt_u32_f32_sdwa v91, v91 dst_sel:BYTE_3 dst_unused:UNUSED_PAD src0_sel:DWORD
	v_lshl_or_b32 v88, v88, 8, v92
	v_or3_b32 v88, v88, v93, v94
	global_store_dwordx2 v[112:113], v[96:97], off offset:128
	v_or_b32_e32 v96, 48, v173
	v_mad_i64_i32 v[96:97], s[2:3], v96, s55, v[164:165]
	v_lshl_or_b32 v89, v89, 8, v100
	v_lshl_add_u64 v[96:97], v[96:97], 0, v[162:163]
	v_or3_b32 v89, v89, v90, v91
	global_store_dwordx2 v[96:97], v[88:89], off
	v_fma_f32 v80, v80, s100, v32
	v_exp_f32_e32 v80, v80
	s_nop 0
	v_add_f32_e32 v80, 1.0, v80
	v_rcp_f32_e32 v84, v84
	v_fma_f32 v85, v85, s100, v37
	v_exp_f32_e32 v85, v85
	s_nop 0
	v_add_f32_e32 v85, 1.0, v85
	v_rcp_f32_e32 v80, v80
	s_nop 0
	v_mul_f32_e32 v80, 0x437f0000, v80
	v_rndne_f32_e32 v80, v80
	v_max_f32_e32 v80, 1.0, v80
	v_cvt_u32_f32_e32 v90, v80
	v_fma_f32 v81, v81, s100, v33
	v_exp_f32_e32 v81, v81
	s_nop 0
	v_add_f32_e32 v81, 1.0, v81
	v_rcp_f32_e32 v80, v85
	v_fma_f32 v86, v86, s100, v38
	v_exp_f32_e32 v86, v86
	v_rcp_f32_e32 v81, v81
	v_add_f32_e32 v85, 1.0, v86
	v_fma_f32 v82, v82, s100, v34
	v_exp_f32_e32 v82, v82
	s_nop 0
	v_add_f32_e32 v82, 1.0, v82
	v_rcp_f32_e32 v85, v85
	v_fma_f32 v87, v87, s100, v39
	v_exp_f32_e32 v87, v87
	v_rcp_f32_e32 v82, v82
	v_add_f32_e32 v86, 1.0, v87
	v_fma_f32 v83, v83, s100, v35
	v_exp_f32_e32 v83, v83
	s_nop 0
	v_add_f32_e32 v83, 1.0, v83
	v_rcp_f32_e32 v86, v86
	v_mul_f32_e32 v81, 0x437f0000, v81
	v_rndne_f32_e32 v81, v81
	v_mul_f32_e32 v82, 0x437f0000, v82
	v_rcp_f32_e32 v83, v83
	s_nop 0
	v_mul_f32_e32 v83, 0x437f0000, v83
	v_max_f32_e32 v81, 1.0, v81
	v_rndne_f32_e32 v82, v82
	v_rndne_f32_e32 v83, v83
	v_fma_f32 v76, v76, s100, v52
	v_cvt_u32_f32_e32 v81, v81
	v_max_f32_e32 v82, 1.0, v82
	v_max_f32_e32 v83, 1.0, v83
	v_exp_f32_e32 v76, v76
	v_cvt_u32_f32_sdwa v82, v82 dst_sel:WORD_1 dst_unused:UNUSED_PAD src0_sel:DWORD
	v_cvt_u32_f32_sdwa v83, v83 dst_sel:BYTE_3 dst_unused:UNUSED_PAD src0_sel:DWORD
	v_mul_f32_e32 v84, 0x437f0000, v84
	v_mul_f32_e32 v80, 0x437f0000, v80
	v_rndne_f32_e32 v84, v84
	v_rndne_f32_e32 v80, v80
	v_lshl_or_b32 v81, v81, 8, v90
	v_add_f32_e32 v76, 1.0, v76
	v_max_f32_e32 v84, 1.0, v84
	v_max_f32_e32 v80, 1.0, v80
	v_mul_f32_e32 v85, 0x437f0000, v85
	v_mul_f32_e32 v86, 0x437f0000, v86
	v_or3_b32 v81, v81, v82, v83
	v_cvt_u32_f32_e32 v84, v84
	v_cvt_u32_f32_e32 v80, v80
	v_rndne_f32_e32 v85, v85
	v_rndne_f32_e32 v86, v86
	v_max_f32_e32 v85, 1.0, v85
	v_max_f32_e32 v86, 1.0, v86
	v_cvt_u32_f32_sdwa v85, v85 dst_sel:WORD_1 dst_unused:UNUSED_PAD src0_sel:DWORD
	v_cvt_u32_f32_sdwa v86, v86 dst_sel:BYTE_3 dst_unused:UNUSED_PAD src0_sel:DWORD
	v_lshl_or_b32 v80, v80, 8, v84
	v_fma_f32 v72, v72, s100, v48
	v_or3_b32 v80, v80, v85, v86
	v_exp_f32_e32 v72, v72
	s_nop 0
	v_add_f32_e32 v72, 1.0, v72
	v_rcp_f32_e32 v76, v76
	v_fma_f32 v77, v77, s100, v53
	v_exp_f32_e32 v77, v77
	s_nop 0
	v_add_f32_e32 v77, 1.0, v77
	v_rcp_f32_e32 v72, v72
	s_nop 0
	v_mul_f32_e32 v72, 0x437f0000, v72
	v_rndne_f32_e32 v72, v72
	v_max_f32_e32 v72, 1.0, v72
	v_cvt_u32_f32_e32 v84, v72
	v_fma_f32 v73, v73, s100, v49
	v_exp_f32_e32 v73, v73
	s_nop 0
	v_add_f32_e32 v73, 1.0, v73
	v_rcp_f32_e32 v72, v77
	v_fma_f32 v78, v78, s100, v54
	v_exp_f32_e32 v78, v78
	v_rcp_f32_e32 v73, v73
	v_add_f32_e32 v77, 1.0, v78
	v_fma_f32 v74, v74, s100, v50
	v_exp_f32_e32 v74, v74
	s_nop 0
	v_add_f32_e32 v74, 1.0, v74
	v_rcp_f32_e32 v77, v77
	v_fma_f32 v79, v79, s100, v55
	v_exp_f32_e32 v79, v79
	v_rcp_f32_e32 v74, v74
	v_add_f32_e32 v78, 1.0, v79
	v_fma_f32 v75, v75, s100, v51
	v_exp_f32_e32 v75, v75
	s_nop 0
	v_add_f32_e32 v75, 1.0, v75
	v_rcp_f32_e32 v78, v78
	v_mul_f32_e32 v76, 0x437f0000, v76
	v_mul_f32_e32 v72, 0x437f0000, v72
	v_rndne_f32_e32 v76, v76
	v_rndne_f32_e32 v72, v72
	v_mul_f32_e32 v77, 0x437f0000, v77
	v_mul_f32_e32 v78, 0x437f0000, v78
	v_fma_f32 v68, v68, s100, v36
	v_max_f32_e32 v76, 1.0, v76
	v_max_f32_e32 v72, 1.0, v72
	v_rndne_f32_e32 v77, v77
	v_rndne_f32_e32 v78, v78
	v_exp_f32_e32 v68, v68
	v_cvt_u32_f32_e32 v76, v76
	v_cvt_u32_f32_e32 v72, v72
	v_mul_f32_e32 v73, 0x437f0000, v73
	v_max_f32_e32 v77, 1.0, v77
	v_max_f32_e32 v78, 1.0, v78
	v_rcp_f32_e32 v75, v75
	v_rndne_f32_e32 v73, v73
	v_cvt_u32_f32_sdwa v77, v77 dst_sel:WORD_1 dst_unused:UNUSED_PAD src0_sel:DWORD
	v_mul_f32_e32 v74, 0x437f0000, v74
	v_cvt_u32_f32_sdwa v78, v78 dst_sel:BYTE_3 dst_unused:UNUSED_PAD src0_sel:DWORD
	v_mul_f32_e32 v75, 0x437f0000, v75
	v_max_f32_e32 v73, 1.0, v73
	v_rndne_f32_e32 v74, v74
	v_rndne_f32_e32 v75, v75
	v_cvt_u32_f32_e32 v73, v73
	v_max_f32_e32 v74, 1.0, v74
	v_max_f32_e32 v75, 1.0, v75
	v_add_f32_e32 v68, 1.0, v68
	v_cvt_u32_f32_sdwa v74, v74 dst_sel:WORD_1 dst_unused:UNUSED_PAD src0_sel:DWORD
	v_cvt_u32_f32_sdwa v75, v75 dst_sel:BYTE_3 dst_unused:UNUSED_PAD src0_sel:DWORD
	v_lshl_or_b32 v72, v72, 8, v76
; __device__ __forceinline__ float sigmoidf_(float x) { return 1.0f / (1.0f + __expf(-x)); }
;     __device__ __forceinline__ void operator()(const f32x4 (&acc)[2][2][4][2], const Unit& u, int wr, int wc, int fr, int fq) const {
;     ...
;             for (int m = 0; m < 4; ++m) { unsigned char* rowp = O + (size_t)(row0 + ai * HALF + m * 16) * GP8 + col0;
; #pragma unroll
;                 for (int bj = 0; bj < 2; ++bj) { const f32x4 v0 = acc[ai][bj][m][0] + bv[bj][0], v1 = acc[ai][bj][m][1] + bv[bj][1];
;                     unsigned q[8];
; #pragma unroll
;                     for (int j = 0; j < 4; ++j) { q[j] = (unsigned)fmaxf(__builtin_rintf(sigmoidf_(v0[j]) * 255.f), 1.f); q[4 + j] = (unsigned)fmaxf(__builtin_rintf(sigmoidf_(v1[j]) * 255.f), 1.f); }
;                     u32x2 w; w.x = q[0] | (q[1] << 8) | (q[2] << 16) | (q[3] << 24); w.y = q[4] | (q[5] << 8) | (q[6] << 16) | (q[7] << 24);
;                     *(u32x2*)(rowp + bj * HALF) = w; } }
	v_or3_b32 v72, v72, v77, v78
	global_store_dwordx2 v[96:97], v[80:81], off offset:128
	v_add_u32_e32 v80, 0x80, v173
	v_mad_i64_i32 v[80:81], s[2:3], v80, s55, v[164:165]
	v_lshl_or_b32 v73, v73, 8, v84
	v_lshl_add_u64 v[80:81], v[80:81], 0, v[162:163]
	v_or3_b32 v73, v73, v74, v75
	global_store_dwordx2 v[80:81], v[72:73], off
	v_fma_f32 v64, v64, s100, v32
	v_exp_f32_e32 v64, v64
	s_nop 0
	v_add_f32_e32 v64, 1.0, v64
	v_rcp_f32_e32 v68, v68
	v_fma_f32 v69, v69, s100, v37
	v_exp_f32_e32 v69, v69
	s_nop 0
	v_add_f32_e32 v69, 1.0, v69
	v_rcp_f32_e32 v64, v64
	s_nop 0
	v_mul_f32_e32 v64, 0x437f0000, v64
	v_rndne_f32_e32 v64, v64
	v_max_f32_e32 v64, 1.0, v64
	v_cvt_u32_f32_e32 v74, v64
	v_fma_f32 v65, v65, s100, v33
	v_exp_f32_e32 v65, v65
	s_nop 0
	v_add_f32_e32 v65, 1.0, v65
	v_rcp_f32_e32 v64, v69
	v_fma_f32 v70, v70, s100, v38
	v_exp_f32_e32 v70, v70
	v_rcp_f32_e32 v65, v65
	v_add_f32_e32 v69, 1.0, v70
	v_fma_f32 v66, v66, s100, v34
	v_exp_f32_e32 v66, v66
	s_nop 0
	v_add_f32_e32 v66, 1.0, v66
	v_rcp_f32_e32 v69, v69
	v_fma_f32 v71, v71, s100, v39
	v_exp_f32_e32 v71, v71
	v_rcp_f32_e32 v66, v66
	v_add_f32_e32 v70, 1.0, v71
	v_fma_f32 v67, v67, s100, v35
	v_exp_f32_e32 v67, v67
	s_nop 0
	v_add_f32_e32 v67, 1.0, v67
	v_rcp_f32_e32 v70, v70
	v_mul_f32_e32 v65, 0x437f0000, v65
	v_rndne_f32_e32 v65, v65
	v_mul_f32_e32 v66, 0x437f0000, v66
	v_rcp_f32_e32 v67, v67
	s_nop 0
	v_mul_f32_e32 v67, 0x437f0000, v67
	v_max_f32_e32 v65, 1.0, v65
	v_rndne_f32_e32 v66, v66
	v_rndne_f32_e32 v67, v67
	v_fma_f32 v60, v60, s100, v52
	v_cvt_u32_f32_e32 v65, v65
	v_max_f32_e32 v66, 1.0, v66
	v_max_f32_e32 v67, 1.0, v67
	v_exp_f32_e32 v60, v60
	v_cvt_u32_f32_sdwa v66, v66 dst_sel:WORD_1 dst_unused:UNUSED_PAD src0_sel:DWORD
	v_cvt_u32_f32_sdwa v67, v67 dst_sel:BYTE_3 dst_unused:UNUSED_PAD src0_sel:DWORD
	v_mul_f32_e32 v68, 0x437f0000, v68
	v_mul_f32_e32 v64, 0x437f0000, v64
	v_rndne_f32_e32 v68, v68
	v_rndne_f32_e32 v64, v64
	v_lshl_or_b32 v65, v65, 8, v74
	v_add_f32_e32 v60, 1.0, v60
	v_max_f32_e32 v68, 1.0, v68
	v_max_f32_e32 v64, 1.0, v64
	v_mul_f32_e32 v69, 0x437f0000, v69
	v_mul_f32_e32 v70, 0x437f0000, v70
	v_or3_b32 v65, v65, v66, v67
	v_cvt_u32_f32_e32 v68, v68
	v_cvt_u32_f32_e32 v64, v64
	v_rndne_f32_e32 v69, v69
	v_rndne_f32_e32 v70, v70
	v_max_f32_e32 v69, 1.0, v69
	v_max_f32_e32 v70, 1.0, v70
	v_cvt_u32_f32_sdwa v69, v69 dst_sel:WORD_1 dst_unused:UNUSED_PAD src0_sel:DWORD
	v_cvt_u32_f32_sdwa v70, v70 dst_sel:BYTE_3 dst_unused:UNUSED_PAD src0_sel:DWORD
	v_lshl_or_b32 v64, v64, 8, v68
	v_fma_f32 v56, v56, s100, v48
	v_or3_b32 v64, v64, v69, v70
	v_exp_f32_e32 v56, v56
	s_nop 0
	v_add_f32_e32 v56, 1.0, v56
	v_rcp_f32_e32 v60, v60
	v_fma_f32 v61, v61, s100, v53
	v_exp_f32_e32 v61, v61
	s_nop 0
	v_add_f32_e32 v61, 1.0, v61
	v_rcp_f32_e32 v56, v56
	s_nop 0
	v_mul_f32_e32 v56, 0x437f0000, v56
	v_rndne_f32_e32 v56, v56
	v_max_f32_e32 v56, 1.0, v56
	v_cvt_u32_f32_e32 v68, v56
	v_fma_f32 v57, v57, s100, v49
	v_exp_f32_e32 v57, v57
	s_nop 0
	v_add_f32_e32 v57, 1.0, v57
	v_rcp_f32_e32 v56, v61
	v_fma_f32 v62, v62, s100, v54
	v_exp_f32_e32 v62, v62
	v_rcp_f32_e32 v57, v57
	v_add_f32_e32 v61, 1.0, v62
	v_fma_f32 v58, v58, s100, v50
	v_exp_f32_e32 v58, v58
	s_nop 0
	v_add_f32_e32 v58, 1.0, v58
	v_rcp_f32_e32 v61, v61
	v_fma_f32 v63, v63, s100, v55
	v_exp_f32_e32 v63, v63
	v_rcp_f32_e32 v58, v58
	v_add_f32_e32 v62, 1.0, v63
	v_fma_f32 v59, v59, s100, v51
	v_exp_f32_e32 v59, v59
	s_nop 0
	v_add_f32_e32 v59, 1.0, v59
	v_rcp_f32_e32 v62, v62
	v_mul_f32_e32 v60, 0x437f0000, v60
	v_mul_f32_e32 v56, 0x437f0000, v56
	v_rndne_f32_e32 v60, v60
	v_rndne_f32_e32 v56, v56
	v_mul_f32_e32 v61, 0x437f0000, v61
	v_mul_f32_e32 v62, 0x437f0000, v62
	v_fma_f32 v44, v44, s100, v36
	v_max_f32_e32 v60, 1.0, v60
	v_max_f32_e32 v56, 1.0, v56
	v_rndne_f32_e32 v61, v61
	v_rndne_f32_e32 v62, v62
	v_exp_f32_e32 v44, v44
	v_cvt_u32_f32_e32 v60, v60
	v_cvt_u32_f32_e32 v56, v56
	v_mul_f32_e32 v57, 0x437f0000, v57
	v_max_f32_e32 v61, 1.0, v61
	v_max_f32_e32 v62, 1.0, v62
	v_rcp_f32_e32 v59, v59
	v_rndne_f32_e32 v57, v57
	v_cvt_u32_f32_sdwa v61, v61 dst_sel:WORD_1 dst_unused:UNUSED_PAD src0_sel:DWORD
	v_mul_f32_e32 v58, 0x437f0000, v58
	v_cvt_u32_f32_sdwa v62, v62 dst_sel:BYTE_3 dst_unused:UNUSED_PAD src0_sel:DWORD
	v_mul_f32_e32 v59, 0x437f0000, v59
	v_max_f32_e32 v57, 1.0, v57
	v_rndne_f32_e32 v58, v58
	v_rndne_f32_e32 v59, v59
	v_cvt_u32_f32_e32 v57, v57
	v_max_f32_e32 v58, 1.0, v58
	v_max_f32_e32 v59, 1.0, v59
	v_add_f32_e32 v44, 1.0, v44
	v_cvt_u32_f32_sdwa v58, v58 dst_sel:WORD_1 dst_unused:UNUSED_PAD src0_sel:DWORD
	v_cvt_u32_f32_sdwa v59, v59 dst_sel:BYTE_3 dst_unused:UNUSED_PAD src0_sel:DWORD
	v_lshl_or_b32 v56, v56, 8, v60
	v_or3_b32 v56, v56, v61, v62
	global_store_dwordx2 v[80:81], v[64:65], off offset:128
	v_add_u32_e32 v64, 0x90, v173
	v_mad_i64_i32 v[64:65], s[2:3], v64, s55, v[164:165]
	v_lshl_or_b32 v57, v57, 8, v68
	v_lshl_add_u64 v[64:65], v[64:65], 0, v[162:163]
	v_or3_b32 v57, v57, v58, v59
	global_store_dwordx2 v[64:65], v[56:57], off
	v_fma_f32 v40, v40, s100, v32
	v_exp_f32_e32 v40, v40
	s_nop 0
	v_add_f32_e32 v40, 1.0, v40
	v_rcp_f32_e32 v44, v44
	v_fma_f32 v45, v45, s100, v37
	v_exp_f32_e32 v45, v45
	s_nop 0
	v_add_f32_e32 v45, 1.0, v45
	v_rcp_f32_e32 v40, v40
	s_nop 0
	v_mul_f32_e32 v40, 0x437f0000, v40
	v_rndne_f32_e32 v40, v40
	v_max_f32_e32 v40, 1.0, v40
	v_cvt_u32_f32_e32 v58, v40
	v_fma_f32 v41, v41, s100, v33
	v_exp_f32_e32 v41, v41
	s_nop 0
	v_add_f32_e32 v41, 1.0, v41
	v_rcp_f32_e32 v40, v45
	v_fma_f32 v46, v46, s100, v38
	v_exp_f32_e32 v46, v46
	v_rcp_f32_e32 v41, v41
	v_add_f32_e32 v45, 1.0, v46
	v_fma_f32 v42, v42, s100, v34
	v_exp_f32_e32 v42, v42
	s_nop 0
; __device__ __forceinline__ float sigmoidf_(float x) { return 1.0f / (1.0f + __expf(-x)); }
;     __device__ __forceinline__ void operator()(const f32x4 (&acc)[2][2][4][2], const Unit& u, int wr, int wc, int fr, int fq) const {
;     ...
;             for (int m = 0; m < 4; ++m) { unsigned char* rowp = O + (size_t)(row0 + ai * HALF + m * 16) * GP8 + col0;
; #pragma unroll
;                 for (int bj = 0; bj < 2; ++bj) { const f32x4 v0 = acc[ai][bj][m][0] + bv[bj][0], v1 = acc[ai][bj][m][1] + bv[bj][1];
;                     unsigned q[8];
; #pragma unroll
;                     for (int j = 0; j < 4; ++j) { q[j] = (unsigned)fmaxf(__builtin_rintf(sigmoidf_(v0[j]) * 255.f), 1.f); q[4 + j] = (unsigned)fmaxf(__builtin_rintf(sigmoidf_(v1[j]) * 255.f), 1.f); }
;                     u32x2 w; w.x = q[0] | (q[1] << 8) | (q[2] << 16) | (q[3] << 24); w.y = q[4] | (q[5] << 8) | (q[6] << 16) | (q[7] << 24);
;                     *(u32x2*)(rowp + bj * HALF) = w; } }
	v_add_f32_e32 v42, 1.0, v42
	v_rcp_f32_e32 v45, v45
	v_fma_f32 v47, v47, s100, v39
	v_exp_f32_e32 v47, v47
	v_rcp_f32_e32 v42, v42
	v_add_f32_e32 v46, 1.0, v47
	v_fma_f32 v43, v43, s100, v35
	v_exp_f32_e32 v43, v43
	s_nop 0
	v_add_f32_e32 v43, 1.0, v43
	v_rcp_f32_e32 v46, v46
	v_mul_f32_e32 v41, 0x437f0000, v41
	v_rndne_f32_e32 v41, v41
	v_mul_f32_e32 v42, 0x437f0000, v42
	v_rcp_f32_e32 v43, v43
	s_nop 0
	v_mul_f32_e32 v43, 0x437f0000, v43
	v_max_f32_e32 v41, 1.0, v41
	v_rndne_f32_e32 v42, v42
	v_rndne_f32_e32 v43, v43
	v_fma_f32 v28, v28, s100, v52
	v_cvt_u32_f32_e32 v41, v41
	v_max_f32_e32 v42, 1.0, v42
	v_max_f32_e32 v43, 1.0, v43
	v_exp_f32_e32 v28, v28
	v_cvt_u32_f32_sdwa v42, v42 dst_sel:WORD_1 dst_unused:UNUSED_PAD src0_sel:DWORD
	v_cvt_u32_f32_sdwa v43, v43 dst_sel:BYTE_3 dst_unused:UNUSED_PAD src0_sel:DWORD
	v_mul_f32_e32 v44, 0x437f0000, v44
	v_mul_f32_e32 v40, 0x437f0000, v40
	v_rndne_f32_e32 v44, v44
	v_rndne_f32_e32 v40, v40
	v_lshl_or_b32 v41, v41, 8, v58
	v_add_f32_e32 v28, 1.0, v28
	v_max_f32_e32 v44, 1.0, v44
	v_max_f32_e32 v40, 1.0, v40
	v_mul_f32_e32 v45, 0x437f0000, v45
	v_mul_f32_e32 v46, 0x437f0000, v46
	v_or3_b32 v41, v41, v42, v43
	v_cvt_u32_f32_e32 v44, v44
	v_cvt_u32_f32_e32 v40, v40
	v_rndne_f32_e32 v45, v45
	v_rndne_f32_e32 v46, v46
	v_max_f32_e32 v45, 1.0, v45
	v_max_f32_e32 v46, 1.0, v46
	v_cvt_u32_f32_sdwa v45, v45 dst_sel:WORD_1 dst_unused:UNUSED_PAD src0_sel:DWORD
	v_cvt_u32_f32_sdwa v46, v46 dst_sel:BYTE_3 dst_unused:UNUSED_PAD src0_sel:DWORD
	v_lshl_or_b32 v40, v40, 8, v44
	v_fma_f32 v24, v24, s100, v48
	v_or3_b32 v40, v40, v45, v46
	v_exp_f32_e32 v24, v24
	s_nop 0
	v_add_f32_e32 v24, 1.0, v24
	v_rcp_f32_e32 v28, v28
	v_fma_f32 v29, v29, s100, v53
	v_exp_f32_e32 v29, v29
	s_nop 0
	v_add_f32_e32 v29, 1.0, v29
	v_rcp_f32_e32 v24, v24
	s_nop 0
	v_mul_f32_e32 v24, 0x437f0000, v24
	v_rndne_f32_e32 v24, v24
	v_max_f32_e32 v24, 1.0, v24
	v_cvt_u32_f32_e32 v44, v24
	v_fma_f32 v25, v25, s100, v49
	v_exp_f32_e32 v25, v25
	s_nop 0
	v_add_f32_e32 v25, 1.0, v25
	v_rcp_f32_e32 v24, v29
	v_fma_f32 v30, v30, s100, v54
	v_exp_f32_e32 v30, v30
	v_rcp_f32_e32 v25, v25
	v_add_f32_e32 v29, 1.0, v30
	v_fma_f32 v26, v26, s100, v50
	v_exp_f32_e32 v26, v26
	s_nop 0
	v_add_f32_e32 v26, 1.0, v26
	v_rcp_f32_e32 v29, v29
	v_fma_f32 v31, v31, s100, v55
	v_exp_f32_e32 v31, v31
	v_rcp_f32_e32 v26, v26
	v_add_f32_e32 v30, 1.0, v31
	v_fma_f32 v27, v27, s100, v51
	v_exp_f32_e32 v27, v27
	s_nop 0
	v_add_f32_e32 v27, 1.0, v27
	v_rcp_f32_e32 v30, v30
	v_mul_f32_e32 v28, 0x437f0000, v28
	v_mul_f32_e32 v24, 0x437f0000, v24
	v_rndne_f32_e32 v28, v28
	v_rndne_f32_e32 v24, v24
	v_mul_f32_e32 v29, 0x437f0000, v29
	v_mul_f32_e32 v30, 0x437f0000, v30
	v_fma_f32 v20, v20, s100, v36
	v_max_f32_e32 v28, 1.0, v28
	v_max_f32_e32 v24, 1.0, v24
	v_rndne_f32_e32 v29, v29
	v_rndne_f32_e32 v30, v30
	v_exp_f32_e32 v20, v20
	v_cvt_u32_f32_e32 v28, v28
	v_cvt_u32_f32_e32 v24, v24
	v_mul_f32_e32 v25, 0x437f0000, v25
	v_max_f32_e32 v29, 1.0, v29
	v_max_f32_e32 v30, 1.0, v30
	v_rcp_f32_e32 v27, v27
	v_rndne_f32_e32 v25, v25
	v_cvt_u32_f32_sdwa v29, v29 dst_sel:WORD_1 dst_unused:UNUSED_PAD src0_sel:DWORD
	v_mul_f32_e32 v26, 0x437f0000, v26
	v_cvt_u32_f32_sdwa v30, v30 dst_sel:BYTE_3 dst_unused:UNUSED_PAD src0_sel:DWORD
	v_mul_f32_e32 v27, 0x437f0000, v27
	v_max_f32_e32 v25, 1.0, v25
	v_rndne_f32_e32 v26, v26
	v_rndne_f32_e32 v27, v27
	v_cvt_u32_f32_e32 v25, v25
	v_max_f32_e32 v26, 1.0, v26
	v_max_f32_e32 v27, 1.0, v27
	v_add_f32_e32 v20, 1.0, v20
	v_cvt_u32_f32_sdwa v26, v26 dst_sel:WORD_1 dst_unused:UNUSED_PAD src0_sel:DWORD
	v_cvt_u32_f32_sdwa v27, v27 dst_sel:BYTE_3 dst_unused:UNUSED_PAD src0_sel:DWORD
	v_lshl_or_b32 v24, v24, 8, v28
	v_or3_b32 v24, v24, v29, v30
	global_store_dwordx2 v[64:65], v[40:41], off offset:128
	v_add_u32_e32 v40, 0xa0, v173
	v_mad_i64_i32 v[40:41], s[2:3], v40, s55, v[164:165]
	v_lshl_or_b32 v25, v25, 8, v44
	v_lshl_add_u64 v[40:41], v[40:41], 0, v[162:163]
	v_or3_b32 v25, v25, v26, v27
	global_store_dwordx2 v[40:41], v[24:25], off
	v_fma_f32 v16, v16, s100, v32
	v_exp_f32_e32 v16, v16
	s_nop 0
	v_add_f32_e32 v16, 1.0, v16
	v_rcp_f32_e32 v20, v20
	v_fma_f32 v21, v21, s100, v37
	v_exp_f32_e32 v21, v21
	s_nop 0
	v_add_f32_e32 v21, 1.0, v21
	v_rcp_f32_e32 v16, v16
	s_nop 0
	v_mul_f32_e32 v16, 0x437f0000, v16
	v_rndne_f32_e32 v16, v16
	v_max_f32_e32 v16, 1.0, v16
	v_cvt_u32_f32_e32 v26, v16
	v_fma_f32 v17, v17, s100, v33
	v_exp_f32_e32 v17, v17
	s_nop 0
	v_add_f32_e32 v17, 1.0, v17
	v_rcp_f32_e32 v16, v21
	v_fma_f32 v22, v22, s100, v38
	v_exp_f32_e32 v22, v22
	v_rcp_f32_e32 v17, v17
	v_add_f32_e32 v21, 1.0, v22
	v_fma_f32 v18, v18, s100, v34
	v_exp_f32_e32 v18, v18
	s_nop 0
	v_add_f32_e32 v18, 1.0, v18
	v_rcp_f32_e32 v21, v21
	v_fma_f32 v23, v23, s100, v39
	v_exp_f32_e32 v23, v23
	v_rcp_f32_e32 v18, v18
	v_add_f32_e32 v22, 1.0, v23
	v_fma_f32 v19, v19, s100, v35
	v_exp_f32_e32 v19, v19
	s_nop 0
	v_add_f32_e32 v19, 1.0, v19
	v_rcp_f32_e32 v22, v22
	v_mul_f32_e32 v17, 0x437f0000, v17
	v_rndne_f32_e32 v17, v17
	v_mul_f32_e32 v18, 0x437f0000, v18
	v_rcp_f32_e32 v19, v19
	s_nop 0
	v_mul_f32_e32 v19, 0x437f0000, v19
	v_max_f32_e32 v17, 1.0, v17
	v_rndne_f32_e32 v18, v18
	v_rndne_f32_e32 v19, v19
	v_fma_f32 v12, v12, s100, v52
	v_cvt_u32_f32_e32 v17, v17
	v_max_f32_e32 v18, 1.0, v18
	v_max_f32_e32 v19, 1.0, v19
	v_exp_f32_e32 v12, v12
	v_cvt_u32_f32_sdwa v18, v18 dst_sel:WORD_1 dst_unused:UNUSED_PAD src0_sel:DWORD
; __device__ __forceinline__ float sigmoidf_(float x) { return 1.0f / (1.0f + __expf(-x)); }
; #define PG8_BAR __builtin_amdgcn_s_barrier()
;     __device__ __forceinline__ void operator()(const f32x4 (&acc)[2][2][4][2], const Unit& u, int wr, int wc, int fr, int fq) const {
;     ...
;             for (int m = 0; m < 4; ++m) { unsigned char* rowp = O + (size_t)(row0 + ai * HALF + m * 16) * GP8 + col0;
; #pragma unroll
;                 for (int bj = 0; bj < 2; ++bj) { const f32x4 v0 = acc[ai][bj][m][0] + bv[bj][0], v1 = acc[ai][bj][m][1] + bv[bj][1];
;                     unsigned q[8];
; #pragma unroll
;                     for (int j = 0; j < 4; ++j) { q[j] = (unsigned)fmaxf(__builtin_rintf(sigmoidf_(v0[j]) * 255.f), 1.f); q[4 + j] = (unsigned)fmaxf(__builtin_rintf(sigmoidf_(v1[j]) * 255.f), 1.f); }
;                     u32x2 w; w.x = q[0] | (q[1] << 8) | (q[2] << 16) | (q[3] << 24); w.y = q[4] | (q[5] << 8) | (q[6] << 16) | (q[7] << 24);
;                     *(u32x2*)(rowp + bj * HALF) = w; } }
; template <class Epi, class Sched, bool ALIGN_EPI = true>
; __device__ __forceinline__ void gemm_phase(LAS unsigned char* lds, const Gemm g, const Sched& S, const Epi& E) {
;     ...
;         if (!has_next) break;
; #pragma unroll
;         for (int a = 0; a < 2; ++a)
; #pragma unroll
;             for (int b = 0; b < 2; ++b)
; #pragma unroll
;                 for (int m = 0; m < 4; ++m)
; #pragma unroll
;                     for (int n = 0; n < 2; ++n) acc[a][b][m][n] = (f32x4){0.f, 0.f, 0.f, 0.f};
;         cur = nxt; cA = nA; cB = nB; ++ui;
;         if constexpr (ALIGN_EPI) { if (wr == 1) PG8_BAR; }
	v_cvt_u32_f32_sdwa v19, v19 dst_sel:BYTE_3 dst_unused:UNUSED_PAD src0_sel:DWORD
	v_mul_f32_e32 v20, 0x437f0000, v20
	v_mul_f32_e32 v16, 0x437f0000, v16
	v_rndne_f32_e32 v20, v20
	v_rndne_f32_e32 v16, v16
	v_lshl_or_b32 v17, v17, 8, v26
	v_add_f32_e32 v12, 1.0, v12
	v_max_f32_e32 v20, 1.0, v20
	v_max_f32_e32 v16, 1.0, v16
	v_mul_f32_e32 v21, 0x437f0000, v21
	v_mul_f32_e32 v22, 0x437f0000, v22
	v_or3_b32 v17, v17, v18, v19
	v_cvt_u32_f32_e32 v20, v20
	v_cvt_u32_f32_e32 v16, v16
	v_rndne_f32_e32 v21, v21
	v_rndne_f32_e32 v22, v22
	v_max_f32_e32 v21, 1.0, v21
	v_max_f32_e32 v22, 1.0, v22
	v_cvt_u32_f32_sdwa v21, v21 dst_sel:WORD_1 dst_unused:UNUSED_PAD src0_sel:DWORD
	v_cvt_u32_f32_sdwa v22, v22 dst_sel:BYTE_3 dst_unused:UNUSED_PAD src0_sel:DWORD
	v_lshl_or_b32 v16, v16, 8, v20
	v_fma_f32 v8, v8, s100, v48
	v_or3_b32 v16, v16, v21, v22
	v_exp_f32_e32 v8, v8
	s_nop 0
	v_add_f32_e32 v8, 1.0, v8
	v_rcp_f32_e32 v12, v12
	v_fma_f32 v13, v13, s100, v53
	v_exp_f32_e32 v13, v13
	s_nop 0
	v_add_f32_e32 v13, 1.0, v13
	v_rcp_f32_e32 v8, v8
	s_nop 0
	v_mul_f32_e32 v8, 0x437f0000, v8
	v_rndne_f32_e32 v8, v8
	v_max_f32_e32 v8, 1.0, v8
	v_cvt_u32_f32_e32 v20, v8
	v_fma_f32 v9, v9, s100, v49
	v_exp_f32_e32 v9, v9
	s_nop 0
	v_add_f32_e32 v9, 1.0, v9
	v_rcp_f32_e32 v8, v13
	v_fma_f32 v14, v14, s100, v54
	v_exp_f32_e32 v14, v14
	v_rcp_f32_e32 v9, v9
	v_add_f32_e32 v13, 1.0, v14
	v_fma_f32 v10, v10, s100, v50
	v_exp_f32_e32 v10, v10
	s_nop 0
	v_add_f32_e32 v10, 1.0, v10
	v_rcp_f32_e32 v13, v13
	v_fma_f32 v15, v15, s100, v55
	v_exp_f32_e32 v15, v15
	v_rcp_f32_e32 v10, v10
	v_add_f32_e32 v14, 1.0, v15
	v_fma_f32 v11, v11, s100, v51
	v_exp_f32_e32 v11, v11
	s_nop 0
	v_add_f32_e32 v11, 1.0, v11
	v_rcp_f32_e32 v14, v14
	v_mul_f32_e32 v12, 0x437f0000, v12
	v_mul_f32_e32 v8, 0x437f0000, v8
	v_rndne_f32_e32 v12, v12
	v_rndne_f32_e32 v8, v8
	v_mul_f32_e32 v13, 0x437f0000, v13
	v_mul_f32_e32 v14, 0x437f0000, v14
	v_fma_f32 v4, v4, s100, v36
	v_max_f32_e32 v12, 1.0, v12
	v_max_f32_e32 v8, 1.0, v8
	v_rndne_f32_e32 v13, v13
	v_rndne_f32_e32 v14, v14
	v_exp_f32_e32 v4, v4
	v_cvt_u32_f32_e32 v12, v12
	v_cvt_u32_f32_e32 v8, v8
	v_mul_f32_e32 v9, 0x437f0000, v9
	v_max_f32_e32 v13, 1.0, v13
	v_max_f32_e32 v14, 1.0, v14
	v_rcp_f32_e32 v11, v11
	v_rndne_f32_e32 v9, v9
	v_cvt_u32_f32_sdwa v13, v13 dst_sel:WORD_1 dst_unused:UNUSED_PAD src0_sel:DWORD
	v_mul_f32_e32 v10, 0x437f0000, v10
	v_cvt_u32_f32_sdwa v14, v14 dst_sel:BYTE_3 dst_unused:UNUSED_PAD src0_sel:DWORD
	v_mul_f32_e32 v11, 0x437f0000, v11
	v_max_f32_e32 v9, 1.0, v9
	v_rndne_f32_e32 v10, v10
	v_rndne_f32_e32 v11, v11
	v_cvt_u32_f32_e32 v9, v9
	v_max_f32_e32 v10, 1.0, v10
	v_max_f32_e32 v11, 1.0, v11
	v_add_f32_e32 v4, 1.0, v4
	v_cvt_u32_f32_sdwa v10, v10 dst_sel:WORD_1 dst_unused:UNUSED_PAD src0_sel:DWORD
	v_cvt_u32_f32_sdwa v11, v11 dst_sel:BYTE_3 dst_unused:UNUSED_PAD src0_sel:DWORD
	v_lshl_or_b32 v8, v8, 8, v12
	v_or3_b32 v8, v8, v13, v14
	global_store_dwordx2 v[40:41], v[16:17], off offset:128
	v_add_u32_e32 v16, 0xb0, v173
	v_mad_i64_i32 v[16:17], s[2:3], v16, s55, v[164:165]
	v_lshl_or_b32 v9, v9, 8, v20
	v_lshl_add_u64 v[16:17], v[16:17], 0, v[162:163]
	v_or3_b32 v9, v9, v10, v11
	global_store_dwordx2 v[16:17], v[8:9], off
	v_fma_f32 v0, v0, s100, v32
	v_exp_f32_e32 v0, v0
	s_nop 0
	v_add_f32_e32 v0, 1.0, v0
	v_rcp_f32_e32 v4, v4
	v_fma_f32 v5, v5, s100, v37
	v_exp_f32_e32 v5, v5
	s_nop 0
	v_add_f32_e32 v5, 1.0, v5
	v_rcp_f32_e32 v0, v0
	s_nop 0
	v_mul_f32_e32 v0, 0x437f0000, v0
	v_rndne_f32_e32 v0, v0
	v_max_f32_e32 v0, 1.0, v0
	v_cvt_u32_f32_e32 v10, v0
	v_fma_f32 v1, v1, s100, v33
	v_exp_f32_e32 v1, v1
	s_nop 0
	v_add_f32_e32 v1, 1.0, v1
	v_rcp_f32_e32 v0, v5
	v_fma_f32 v6, v6, s100, v38
	v_exp_f32_e32 v6, v6
	v_rcp_f32_e32 v1, v1
	v_add_f32_e32 v5, 1.0, v6
	v_fma_f32 v2, v2, s100, v34
	v_exp_f32_e32 v2, v2
	s_nop 0
	v_add_f32_e32 v2, 1.0, v2
	v_rcp_f32_e32 v5, v5
	v_fma_f32 v7, v7, s100, v39
	v_exp_f32_e32 v7, v7
	v_rcp_f32_e32 v2, v2
	v_add_f32_e32 v6, 1.0, v7
	v_fma_f32 v3, v3, s100, v35
	v_exp_f32_e32 v3, v3
	s_nop 0
	v_add_f32_e32 v3, 1.0, v3
	v_rcp_f32_e32 v6, v6
	v_mul_f32_e32 v4, 0x437f0000, v4
	v_mul_f32_e32 v0, 0x437f0000, v0
	v_mul_f32_e32 v1, 0x437f0000, v1
	v_rcp_f32_e32 v3, v3
	v_rndne_f32_e32 v4, v4
	v_rndne_f32_e32 v0, v0
	v_rndne_f32_e32 v1, v1
	v_mul_f32_e32 v5, 0x437f0000, v5
	v_mul_f32_e32 v2, 0x437f0000, v2
	v_mul_f32_e32 v6, 0x437f0000, v6
	v_mul_f32_e32 v3, 0x437f0000, v3
	v_max_f32_e32 v4, 1.0, v4
	v_max_f32_e32 v0, 1.0, v0
	v_max_f32_e32 v1, 1.0, v1
	v_rndne_f32_e32 v5, v5
	v_rndne_f32_e32 v2, v2
	v_rndne_f32_e32 v6, v6
	v_rndne_f32_e32 v3, v3
	v_cvt_u32_f32_e32 v4, v4
	v_cvt_u32_f32_e32 v0, v0
	v_cvt_u32_f32_e32 v1, v1
	v_max_f32_e32 v5, 1.0, v5
	v_max_f32_e32 v2, 1.0, v2
	v_max_f32_e32 v6, 1.0, v6
	v_max_f32_e32 v3, 1.0, v3
	v_cvt_u32_f32_sdwa v5, v5 dst_sel:WORD_1 dst_unused:UNUSED_PAD src0_sel:DWORD
	v_cvt_u32_f32_sdwa v2, v2 dst_sel:WORD_1 dst_unused:UNUSED_PAD src0_sel:DWORD
	v_cvt_u32_f32_sdwa v6, v6 dst_sel:BYTE_3 dst_unused:UNUSED_PAD src0_sel:DWORD
	v_cvt_u32_f32_sdwa v3, v3 dst_sel:BYTE_3 dst_unused:UNUSED_PAD src0_sel:DWORD
	v_lshl_or_b32 v0, v0, 8, v4
	v_lshl_or_b32 v1, v1, 8, v10
	v_or3_b32 v0, v0, v5, v6
	v_or3_b32 v1, v1, v2, v3
	s_andn2_b64 vcc, exec, s[0:1]
	s_mov_b64 s[0:1], -1
	global_store_dwordx2 v[16:17], v[0:1], off offset:128
	s_cbranch_vccnz .LBB0_786
	s_andn2_b64 vcc, exec, s[10:11]
	s_cbranch_vccnz .LBB0_785
	s_barrier
	s_branch .LBB0_785

; __device__ __forceinline__ float sigmoidf_(float x) { return 1.0f / (1.0f + __expf(-x)); }
;     __device__ __forceinline__ void operator()(const f32x4 (&acc)[2][2][4][2], const Unit& u, int wr, int wc, int fr, int fq) const {
;         const int row0 = u.pm * BM + wr * 64 + fr; const int col0 = u.pn * BM + wc * 32 + 8 * fq;
;         f32x4 bv[2][2];
; #pragma unroll
;         for (int bj = 0; bj < 2; ++bj)
; #pragma unroll
;             for (int n = 0; n < 2; ++n) bv[bj][n] = *(const f32x4*)(bias + col0 + bj * HALF + 4 * n);
; #pragma unroll
;         for (int ai = 0; ai < 2; ++ai)
; #pragma unroll
;             for (int m = 0; m < 4; ++m) { unsigned char* rowp = O + (size_t)(row0 + ai * HALF + m * 16) * GP8 + col0;
; #pragma unroll
;                 for (int bj = 0; bj < 2; ++bj) { const f32x4 v0 = acc[ai][bj][m][0] + bv[bj][0], v1 = acc[ai][bj][m][1] + bv[bj][1];
;                     unsigned q[8];
; #pragma unroll
;                     for (int j = 0; j < 4; ++j) { q[j] = (unsigned)fmaxf(__builtin_rintf(sigmoidf_(v0[j]) * 255.f), 1.f); q[4 + j] = (unsigned)fmaxf(__builtin_rintf(sigmoidf_(v1[j]) * 255.f), 1.f); }
;                     u32x2 w; w.x = q[0] | (q[1] << 8) | (q[2] << 16) | (q[3] << 24); w.y = q[4] | (q[5] << 8) | (q[6] << 16) | (q[7] << 24);
;                     *(u32x2*)(rowp + bj * HALF) = w; } }
.LBB0_811:
	v_lshl_or_b32 v162, s9, 8, v170
	v_ashrrev_i32_e32 v163, 31, v162
	v_lshl_add_u64 v[36:37], v[162:163], 2, s[78:79]
	global_load_dwordx4 v[52:55], v[36:37], off
	global_load_dwordx4 v[48:51], v[36:37], off offset:16
	v_lshl_add_u32 v174, s8, 8, v168
	v_mov_b64_e32 v[164:165], s[34:35]
	v_mad_i64_i32 v[32:33], s[2:3], v174, s55, v[164:165]
	v_lshl_add_u64 v[166:167], v[32:33], 0, v[162:163]
	global_load_dwordx4 v[32:35], v[36:37], off offset:528
	s_nop 0
	global_load_dwordx4 v[36:39], v[36:37], off offset:512
	s_waitcnt vmcnt(0)
	s_mov_b32 s100, 0xbfb8aa3b
	v_mul_f32_e32 v32, 0xbfb8aa3b, v32
	v_mul_f32_e32 v33, 0xbfb8aa3b, v33
	v_mul_f32_e32 v34, 0xbfb8aa3b, v34
	v_mul_f32_e32 v35, 0xbfb8aa3b, v35
	v_mul_f32_e32 v36, 0xbfb8aa3b, v36
	v_mul_f32_e32 v37, 0xbfb8aa3b, v37
	v_mul_f32_e32 v38, 0xbfb8aa3b, v38
	v_mul_f32_e32 v39, 0xbfb8aa3b, v39
	v_mul_f32_e32 v48, 0xbfb8aa3b, v48
	v_mul_f32_e32 v49, 0xbfb8aa3b, v49
	v_mul_f32_e32 v50, 0xbfb8aa3b, v50
	v_mul_f32_e32 v51, 0xbfb8aa3b, v51
	v_mul_f32_e32 v52, 0xbfb8aa3b, v52
	v_mul_f32_e32 v53, 0xbfb8aa3b, v53
	v_mul_f32_e32 v54, 0xbfb8aa3b, v54
	v_mul_f32_e32 v55, 0xbfb8aa3b, v55
	v_fma_f32 v140, v140, s100, v52
	v_fma_f32 v136, v136, s100, v48
	v_exp_f32_e32 v140, v140
	v_fma_f32 v141, v141, s100, v53
	v_fma_f32 v142, v142, s100, v54
	v_exp_f32_e32 v136, v136
	v_exp_f32_e32 v141, v141
	v_exp_f32_e32 v142, v142
	v_fma_f32 v137, v137, s100, v49
	v_add_f32_e32 v140, 1.0, v140
	v_exp_f32_e32 v137, v137
	v_add_f32_e32 v136, 1.0, v136
	v_add_f32_e32 v141, 1.0, v141
	v_add_f32_e32 v142, 1.0, v142
	v_add_f32_e32 v137, 1.0, v137
	v_rcp_f32_e32 v140, v140
	v_rcp_f32_e32 v136, v136
	s_nop 0
	v_mul_f32_e32 v136, 0x437f0000, v136
	v_rcp_f32_e32 v141, v141
	v_rndne_f32_e32 v136, v136
	v_mul_f32_e32 v141, 0x437f0000, v141
	v_max_f32_e32 v136, 1.0, v136
	v_rndne_f32_e32 v141, v141
	v_rcp_f32_e32 v137, v137
	v_cvt_u32_f32_e32 v175, v136
	v_max_f32_e32 v136, 1.0, v141
	v_fma_f32 v138, v138, s100, v50
	v_exp_f32_e32 v138, v138
	s_nop 0
	v_add_f32_e32 v138, 1.0, v138
	v_rcp_f32_e32 v141, v142
	v_fma_f32 v143, v143, s100, v55
	v_exp_f32_e32 v143, v143
	v_rcp_f32_e32 v138, v138
	v_add_f32_e32 v142, 1.0, v143
	v_fma_f32 v139, v139, s100, v51
	v_exp_f32_e32 v139, v139
	s_nop 0
	v_add_f32_e32 v139, 1.0, v139
	v_rcp_f32_e32 v142, v142
	v_mul_f32_e32 v140, 0x437f0000, v140
	v_rndne_f32_e32 v140, v140
	v_mul_f32_e32 v141, 0x437f0000, v141
	v_mul_f32_e32 v142, 0x437f0000, v142
	v_fma_f32 v132, v132, s100, v36
	v_max_f32_e32 v140, 1.0, v140
	v_rndne_f32_e32 v141, v141
	v_rndne_f32_e32 v142, v142
	v_exp_f32_e32 v132, v132
	v_cvt_u32_f32_e32 v140, v140
	v_mul_f32_e32 v137, 0x437f0000, v137
	v_cvt_u32_f32_e32 v136, v136
	v_max_f32_e32 v141, 1.0, v141
	v_max_f32_e32 v142, 1.0, v142
	v_rcp_f32_e32 v139, v139
	v_rndne_f32_e32 v137, v137
	v_cvt_u32_f32_sdwa v141, v141 dst_sel:WORD_1 dst_unused:UNUSED_PAD src0_sel:DWORD
	v_mul_f32_e32 v138, 0x437f0000, v138
	v_cvt_u32_f32_sdwa v142, v142 dst_sel:BYTE_3 dst_unused:UNUSED_PAD src0_sel:DWORD
	v_mul_f32_e32 v139, 0x437f0000, v139
	v_max_f32_e32 v137, 1.0, v137
	v_rndne_f32_e32 v138, v138
	v_rndne_f32_e32 v139, v139
	v_cvt_u32_f32_e32 v137, v137
	v_max_f32_e32 v138, 1.0, v138
	v_max_f32_e32 v139, 1.0, v139
	v_add_f32_e32 v132, 1.0, v132
	v_cvt_u32_f32_sdwa v138, v138 dst_sel:WORD_1 dst_unused:UNUSED_PAD src0_sel:DWORD
	v_cvt_u32_f32_sdwa v139, v139 dst_sel:BYTE_3 dst_unused:UNUSED_PAD src0_sel:DWORD
	v_lshl_or_b32 v136, v136, 8, v140
	v_or3_b32 v136, v136, v141, v142
	v_lshl_or_b32 v137, v137, 8, v175
	v_or3_b32 v137, v137, v138, v139
	global_store_dwordx2 v[166:167], v[136:137], off
	v_fma_f32 v128, v128, s100, v32
	v_exp_f32_e32 v128, v128
	s_nop 0
	v_add_f32_e32 v128, 1.0, v128
	v_rcp_f32_e32 v132, v132
	v_fma_f32 v133, v133, s100, v37
	v_exp_f32_e32 v133, v133
	s_nop 0
	v_add_f32_e32 v133, 1.0, v133
	v_rcp_f32_e32 v128, v128
	s_nop 0
	v_mul_f32_e32 v128, 0x437f0000, v128
	v_rndne_f32_e32 v128, v128
	v_max_f32_e32 v128, 1.0, v128
	v_cvt_u32_f32_e32 v138, v128
	v_fma_f32 v129, v129, s100, v33
	v_exp_f32_e32 v129, v129
	s_nop 0
	v_add_f32_e32 v129, 1.0, v129
	v_rcp_f32_e32 v128, v133
	v_fma_f32 v134, v134, s100, v38
	v_exp_f32_e32 v134, v134
	v_rcp_f32_e32 v129, v129
	v_add_f32_e32 v133, 1.0, v134
	v_fma_f32 v130, v130, s100, v34
	v_exp_f32_e32 v130, v130
	s_nop 0
	v_add_f32_e32 v130, 1.0, v130
	v_rcp_f32_e32 v133, v133
	v_fma_f32 v135, v135, s100, v39
	v_exp_f32_e32 v135, v135
	v_rcp_f32_e32 v130, v130
	v_add_f32_e32 v134, 1.0, v135
	v_fma_f32 v131, v131, s100, v35
	v_exp_f32_e32 v131, v131
	s_nop 0
	v_add_f32_e32 v131, 1.0, v131
	v_rcp_f32_e32 v134, v134
	v_mul_f32_e32 v129, 0x437f0000, v129
	v_rndne_f32_e32 v129, v129
	v_mul_f32_e32 v130, 0x437f0000, v130
	v_rcp_f32_e32 v131, v131
	s_nop 0
	v_mul_f32_e32 v131, 0x437f0000, v131
	v_max_f32_e32 v129, 1.0, v129
	v_rndne_f32_e32 v130, v130
	v_rndne_f32_e32 v131, v131
	v_fma_f32 v124, v124, s100, v52
	v_cvt_u32_f32_e32 v129, v129
	v_max_f32_e32 v130, 1.0, v130
	v_max_f32_e32 v131, 1.0, v131
	v_exp_f32_e32 v124, v124
	v_cvt_u32_f32_sdwa v130, v130 dst_sel:WORD_1 dst_unused:UNUSED_PAD src0_sel:DWORD
	v_cvt_u32_f32_sdwa v131, v131 dst_sel:BYTE_3 dst_unused:UNUSED_PAD src0_sel:DWORD
	v_mul_f32_e32 v132, 0x437f0000, v132
	v_mul_f32_e32 v128, 0x437f0000, v128
	v_rndne_f32_e32 v132, v132
	v_rndne_f32_e32 v128, v128
	v_lshl_or_b32 v129, v129, 8, v138
	v_add_f32_e32 v124, 1.0, v124
	v_max_f32_e32 v132, 1.0, v132
	v_max_f32_e32 v128, 1.0, v128
	v_mul_f32_e32 v133, 0x437f0000, v133
	v_mul_f32_e32 v134, 0x437f0000, v134
	v_or3_b32 v129, v129, v130, v131
	v_cvt_u32_f32_e32 v132, v132
	v_cvt_u32_f32_e32 v128, v128
	v_rndne_f32_e32 v133, v133
; __device__ __forceinline__ float sigmoidf_(float x) { return 1.0f / (1.0f + __expf(-x)); }
;     __device__ __forceinline__ void operator()(const f32x4 (&acc)[2][2][4][2], const Unit& u, int wr, int wc, int fr, int fq) const {
;     ...
;             for (int m = 0; m < 4; ++m) { unsigned char* rowp = O + (size_t)(row0 + ai * HALF + m * 16) * GP8 + col0;
; #pragma unroll
;                 for (int bj = 0; bj < 2; ++bj) { const f32x4 v0 = acc[ai][bj][m][0] + bv[bj][0], v1 = acc[ai][bj][m][1] + bv[bj][1];
;                     unsigned q[8];
; #pragma unroll
;                     for (int j = 0; j < 4; ++j) { q[j] = (unsigned)fmaxf(__builtin_rintf(sigmoidf_(v0[j]) * 255.f), 1.f); q[4 + j] = (unsigned)fmaxf(__builtin_rintf(sigmoidf_(v1[j]) * 255.f), 1.f); }
;                     u32x2 w; w.x = q[0] | (q[1] << 8) | (q[2] << 16) | (q[3] << 24); w.y = q[4] | (q[5] << 8) | (q[6] << 16) | (q[7] << 24);
;                     *(u32x2*)(rowp + bj * HALF) = w; } }
	v_rndne_f32_e32 v134, v134
	v_max_f32_e32 v133, 1.0, v133
	v_max_f32_e32 v134, 1.0, v134
	v_cvt_u32_f32_sdwa v133, v133 dst_sel:WORD_1 dst_unused:UNUSED_PAD src0_sel:DWORD
	v_cvt_u32_f32_sdwa v134, v134 dst_sel:BYTE_3 dst_unused:UNUSED_PAD src0_sel:DWORD
	v_lshl_or_b32 v128, v128, 8, v132
	v_fma_f32 v120, v120, s100, v48
	v_or3_b32 v128, v128, v133, v134
	v_exp_f32_e32 v120, v120
	s_nop 0
	v_add_f32_e32 v120, 1.0, v120
	v_rcp_f32_e32 v124, v124
	v_fma_f32 v125, v125, s100, v53
	v_exp_f32_e32 v125, v125
	s_nop 0
	v_add_f32_e32 v125, 1.0, v125
	v_rcp_f32_e32 v120, v120
	s_nop 0
	v_mul_f32_e32 v120, 0x437f0000, v120
	v_rndne_f32_e32 v120, v120
	v_max_f32_e32 v120, 1.0, v120
	v_cvt_u32_f32_e32 v132, v120
	v_fma_f32 v121, v121, s100, v49
	v_exp_f32_e32 v121, v121
	s_nop 0
	v_add_f32_e32 v121, 1.0, v121
	v_rcp_f32_e32 v120, v125
	v_fma_f32 v126, v126, s100, v54
	v_exp_f32_e32 v126, v126
	v_rcp_f32_e32 v121, v121
	v_add_f32_e32 v125, 1.0, v126
	v_fma_f32 v122, v122, s100, v50
	v_exp_f32_e32 v122, v122
	s_nop 0
	v_add_f32_e32 v122, 1.0, v122
	v_rcp_f32_e32 v125, v125
	v_fma_f32 v127, v127, s100, v55
	v_exp_f32_e32 v127, v127
	v_rcp_f32_e32 v122, v122
	v_add_f32_e32 v126, 1.0, v127
	v_fma_f32 v123, v123, s100, v51
	v_exp_f32_e32 v123, v123
	s_nop 0
	v_add_f32_e32 v123, 1.0, v123
	v_rcp_f32_e32 v126, v126
	v_mul_f32_e32 v124, 0x437f0000, v124
	v_mul_f32_e32 v120, 0x437f0000, v120
	v_rndne_f32_e32 v124, v124
	v_rndne_f32_e32 v120, v120
	v_mul_f32_e32 v125, 0x437f0000, v125
	v_mul_f32_e32 v126, 0x437f0000, v126
	v_fma_f32 v116, v116, s100, v36
	v_max_f32_e32 v124, 1.0, v124
	v_max_f32_e32 v120, 1.0, v120
	v_rndne_f32_e32 v125, v125
	v_rndne_f32_e32 v126, v126
	v_exp_f32_e32 v116, v116
	v_cvt_u32_f32_e32 v124, v124
	v_cvt_u32_f32_e32 v120, v120
	v_mul_f32_e32 v121, 0x437f0000, v121
	v_max_f32_e32 v125, 1.0, v125
	v_max_f32_e32 v126, 1.0, v126
	v_rcp_f32_e32 v123, v123
	v_rndne_f32_e32 v121, v121
	v_cvt_u32_f32_sdwa v125, v125 dst_sel:WORD_1 dst_unused:UNUSED_PAD src0_sel:DWORD
	v_mul_f32_e32 v122, 0x437f0000, v122
	v_cvt_u32_f32_sdwa v126, v126 dst_sel:BYTE_3 dst_unused:UNUSED_PAD src0_sel:DWORD
	v_mul_f32_e32 v123, 0x437f0000, v123
	v_max_f32_e32 v121, 1.0, v121
	v_rndne_f32_e32 v122, v122
	v_rndne_f32_e32 v123, v123
	v_cvt_u32_f32_e32 v121, v121
	v_max_f32_e32 v122, 1.0, v122
	v_max_f32_e32 v123, 1.0, v123
	v_add_f32_e32 v116, 1.0, v116
	v_cvt_u32_f32_sdwa v122, v122 dst_sel:WORD_1 dst_unused:UNUSED_PAD src0_sel:DWORD
	v_cvt_u32_f32_sdwa v123, v123 dst_sel:BYTE_3 dst_unused:UNUSED_PAD src0_sel:DWORD
	v_lshl_or_b32 v120, v120, 8, v124
	v_or3_b32 v120, v120, v125, v126
	global_store_dwordx2 v[166:167], v[128:129], off offset:128
	v_or_b32_e32 v128, 16, v174
	v_mad_i64_i32 v[128:129], s[2:3], v128, s55, v[164:165]
	v_lshl_or_b32 v121, v121, 8, v132
	v_lshl_add_u64 v[128:129], v[128:129], 0, v[162:163]
	v_or3_b32 v121, v121, v122, v123
	global_store_dwordx2 v[128:129], v[120:121], off
	v_fma_f32 v112, v112, s100, v32
	v_exp_f32_e32 v112, v112
	s_nop 0
	v_add_f32_e32 v112, 1.0, v112
	v_rcp_f32_e32 v116, v116
	v_fma_f32 v117, v117, s100, v37
	v_exp_f32_e32 v117, v117
	s_nop 0
	v_add_f32_e32 v117, 1.0, v117
	v_rcp_f32_e32 v112, v112
	s_nop 0
	v_mul_f32_e32 v112, 0x437f0000, v112
	v_rndne_f32_e32 v112, v112
	v_max_f32_e32 v112, 1.0, v112
	v_cvt_u32_f32_e32 v122, v112
	v_fma_f32 v113, v113, s100, v33
	v_exp_f32_e32 v113, v113
	s_nop 0
	v_add_f32_e32 v113, 1.0, v113
	v_rcp_f32_e32 v112, v117
	v_fma_f32 v118, v118, s100, v38
	v_exp_f32_e32 v118, v118
	v_rcp_f32_e32 v113, v113
	v_add_f32_e32 v117, 1.0, v118
	v_fma_f32 v114, v114, s100, v34
	v_exp_f32_e32 v114, v114
	s_nop 0
	v_add_f32_e32 v114, 1.0, v114
	v_rcp_f32_e32 v117, v117
	v_fma_f32 v119, v119, s100, v39
	v_exp_f32_e32 v119, v119
	v_rcp_f32_e32 v114, v114
	v_add_f32_e32 v118, 1.0, v119
	v_fma_f32 v115, v115, s100, v35
	v_exp_f32_e32 v115, v115
	s_nop 0
	v_add_f32_e32 v115, 1.0, v115
	v_rcp_f32_e32 v118, v118
	v_mul_f32_e32 v113, 0x437f0000, v113
	v_rndne_f32_e32 v113, v113
	v_mul_f32_e32 v114, 0x437f0000, v114
	v_rcp_f32_e32 v115, v115
	s_nop 0
	v_mul_f32_e32 v115, 0x437f0000, v115
	v_max_f32_e32 v113, 1.0, v113
	v_rndne_f32_e32 v114, v114
	v_rndne_f32_e32 v115, v115
	v_fma_f32 v108, v108, s100, v52
	v_cvt_u32_f32_e32 v113, v113
	v_max_f32_e32 v114, 1.0, v114
	v_max_f32_e32 v115, 1.0, v115
	v_exp_f32_e32 v108, v108
	v_cvt_u32_f32_sdwa v114, v114 dst_sel:WORD_1 dst_unused:UNUSED_PAD src0_sel:DWORD
	v_cvt_u32_f32_sdwa v115, v115 dst_sel:BYTE_3 dst_unused:UNUSED_PAD src0_sel:DWORD
	v_mul_f32_e32 v116, 0x437f0000, v116
	v_mul_f32_e32 v112, 0x437f0000, v112
	v_rndne_f32_e32 v116, v116
	v_rndne_f32_e32 v112, v112
	v_lshl_or_b32 v113, v113, 8, v122
	v_add_f32_e32 v108, 1.0, v108
	v_max_f32_e32 v116, 1.0, v116
	v_max_f32_e32 v112, 1.0, v112
	v_mul_f32_e32 v117, 0x437f0000, v117
	v_mul_f32_e32 v118, 0x437f0000, v118
	v_or3_b32 v113, v113, v114, v115
	v_cvt_u32_f32_e32 v116, v116
	v_cvt_u32_f32_e32 v112, v112
	v_rndne_f32_e32 v117, v117
	v_rndne_f32_e32 v118, v118
	v_max_f32_e32 v117, 1.0, v117
	v_max_f32_e32 v118, 1.0, v118
	v_cvt_u32_f32_sdwa v117, v117 dst_sel:WORD_1 dst_unused:UNUSED_PAD src0_sel:DWORD
	v_cvt_u32_f32_sdwa v118, v118 dst_sel:BYTE_3 dst_unused:UNUSED_PAD src0_sel:DWORD
	v_lshl_or_b32 v112, v112, 8, v116
	v_fma_f32 v104, v104, s100, v48
	v_or3_b32 v112, v112, v117, v118
	v_exp_f32_e32 v104, v104
	s_nop 0
	v_add_f32_e32 v104, 1.0, v104
	v_rcp_f32_e32 v108, v108
	v_fma_f32 v109, v109, s100, v53
	v_exp_f32_e32 v109, v109
	s_nop 0
	v_add_f32_e32 v109, 1.0, v109
	v_rcp_f32_e32 v104, v104
	s_nop 0
	v_mul_f32_e32 v104, 0x437f0000, v104
	v_rndne_f32_e32 v104, v104
	v_max_f32_e32 v104, 1.0, v104
; __device__ __forceinline__ float sigmoidf_(float x) { return 1.0f / (1.0f + __expf(-x)); }
;     __device__ __forceinline__ void operator()(const f32x4 (&acc)[2][2][4][2], const Unit& u, int wr, int wc, int fr, int fq) const {
;     ...
;                 for (int bj = 0; bj < 2; ++bj) { const f32x4 v0 = acc[ai][bj][m][0] + bv[bj][0], v1 = acc[ai][bj][m][1] + bv[bj][1];
;                     unsigned q[8];
; #pragma unroll
;                     for (int j = 0; j < 4; ++j) { q[j] = (unsigned)fmaxf(__builtin_rintf(sigmoidf_(v0[j]) * 255.f), 1.f); q[4 + j] = (unsigned)fmaxf(__builtin_rintf(sigmoidf_(v1[j]) * 255.f), 1.f); }
;                     u32x2 w; w.x = q[0] | (q[1] << 8) | (q[2] << 16) | (q[3] << 24); w.y = q[4] | (q[5] << 8) | (q[6] << 16) | (q[7] << 24);
;                     *(u32x2*)(rowp + bj * HALF) = w; } }
	v_cvt_u32_f32_e32 v116, v104
	v_fma_f32 v105, v105, s100, v49
	v_exp_f32_e32 v105, v105
	s_nop 0
	v_add_f32_e32 v105, 1.0, v105
	v_rcp_f32_e32 v104, v109
	v_fma_f32 v110, v110, s100, v54
	v_exp_f32_e32 v110, v110
	v_rcp_f32_e32 v105, v105
	v_add_f32_e32 v109, 1.0, v110
	v_fma_f32 v106, v106, s100, v50
	v_exp_f32_e32 v106, v106
	s_nop 0
	v_add_f32_e32 v106, 1.0, v106
	v_rcp_f32_e32 v109, v109
	v_fma_f32 v111, v111, s100, v55
	v_exp_f32_e32 v111, v111
	v_rcp_f32_e32 v106, v106
	v_add_f32_e32 v110, 1.0, v111
	v_fma_f32 v107, v107, s100, v51
	v_exp_f32_e32 v107, v107
	s_nop 0
	v_add_f32_e32 v107, 1.0, v107
	v_rcp_f32_e32 v110, v110
	v_mul_f32_e32 v108, 0x437f0000, v108
	v_mul_f32_e32 v104, 0x437f0000, v104
	v_rndne_f32_e32 v108, v108
	v_rndne_f32_e32 v104, v104
	v_mul_f32_e32 v109, 0x437f0000, v109
	v_mul_f32_e32 v110, 0x437f0000, v110
	v_fma_f32 v100, v100, s100, v36
	v_max_f32_e32 v108, 1.0, v108
	v_max_f32_e32 v104, 1.0, v104
	v_rndne_f32_e32 v109, v109
	v_rndne_f32_e32 v110, v110
	v_exp_f32_e32 v100, v100
	v_cvt_u32_f32_e32 v108, v108
	v_cvt_u32_f32_e32 v104, v104
	v_mul_f32_e32 v105, 0x437f0000, v105
	v_max_f32_e32 v109, 1.0, v109
	v_max_f32_e32 v110, 1.0, v110
	v_rcp_f32_e32 v107, v107
	v_rndne_f32_e32 v105, v105
	v_cvt_u32_f32_sdwa v109, v109 dst_sel:WORD_1 dst_unused:UNUSED_PAD src0_sel:DWORD
	v_mul_f32_e32 v106, 0x437f0000, v106
	v_cvt_u32_f32_sdwa v110, v110 dst_sel:BYTE_3 dst_unused:UNUSED_PAD src0_sel:DWORD
	v_mul_f32_e32 v107, 0x437f0000, v107
	v_max_f32_e32 v105, 1.0, v105
	v_rndne_f32_e32 v106, v106
	v_rndne_f32_e32 v107, v107
	v_cvt_u32_f32_e32 v105, v105
	v_max_f32_e32 v106, 1.0, v106
	v_max_f32_e32 v107, 1.0, v107
	v_add_f32_e32 v100, 1.0, v100
	v_cvt_u32_f32_sdwa v106, v106 dst_sel:WORD_1 dst_unused:UNUSED_PAD src0_sel:DWORD
	v_cvt_u32_f32_sdwa v107, v107 dst_sel:BYTE_3 dst_unused:UNUSED_PAD src0_sel:DWORD
	v_lshl_or_b32 v104, v104, 8, v108
	v_or3_b32 v104, v104, v109, v110
	global_store_dwordx2 v[128:129], v[112:113], off offset:128
	v_or_b32_e32 v112, 32, v174
	v_mad_i64_i32 v[112:113], s[2:3], v112, s55, v[164:165]
	v_lshl_or_b32 v105, v105, 8, v116
	v_lshl_add_u64 v[112:113], v[112:113], 0, v[162:163]
	v_or3_b32 v105, v105, v106, v107
	global_store_dwordx2 v[112:113], v[104:105], off
	v_fma_f32 v96, v96, s100, v32
	v_exp_f32_e32 v96, v96
	s_nop 0
	v_add_f32_e32 v96, 1.0, v96
	v_rcp_f32_e32 v100, v100
	v_fma_f32 v101, v101, s100, v37
	v_exp_f32_e32 v101, v101
	s_nop 0
	v_add_f32_e32 v101, 1.0, v101
	v_rcp_f32_e32 v96, v96
	s_nop 0
	v_mul_f32_e32 v96, 0x437f0000, v96
	v_rndne_f32_e32 v96, v96
	v_max_f32_e32 v96, 1.0, v96
	v_cvt_u32_f32_e32 v106, v96
	v_fma_f32 v97, v97, s100, v33
	v_exp_f32_e32 v97, v97
	s_nop 0
	v_add_f32_e32 v97, 1.0, v97
	v_rcp_f32_e32 v96, v101
	v_fma_f32 v102, v102, s100, v38
	v_exp_f32_e32 v102, v102
	v_rcp_f32_e32 v97, v97
	v_add_f32_e32 v101, 1.0, v102
	v_fma_f32 v98, v98, s100, v34
	v_exp_f32_e32 v98, v98
	s_nop 0
	v_add_f32_e32 v98, 1.0, v98
	v_rcp_f32_e32 v101, v101
	v_fma_f32 v103, v103, s100, v39
	v_exp_f32_e32 v103, v103
	v_rcp_f32_e32 v98, v98
	v_add_f32_e32 v102, 1.0, v103
	v_fma_f32 v99, v99, s100, v35
	v_exp_f32_e32 v99, v99
	s_nop 0
	v_add_f32_e32 v99, 1.0, v99
	v_rcp_f32_e32 v102, v102
	v_mul_f32_e32 v97, 0x437f0000, v97
	v_rndne_f32_e32 v97, v97
	v_mul_f32_e32 v98, 0x437f0000, v98
	v_rcp_f32_e32 v99, v99
	s_nop 0
	v_mul_f32_e32 v99, 0x437f0000, v99
	v_max_f32_e32 v97, 1.0, v97
	v_rndne_f32_e32 v98, v98
	v_rndne_f32_e32 v99, v99
	v_fma_f32 v92, v92, s100, v52
	v_cvt_u32_f32_e32 v97, v97
	v_max_f32_e32 v98, 1.0, v98
	v_max_f32_e32 v99, 1.0, v99
	v_exp_f32_e32 v92, v92
	v_cvt_u32_f32_sdwa v98, v98 dst_sel:WORD_1 dst_unused:UNUSED_PAD src0_sel:DWORD
	v_cvt_u32_f32_sdwa v99, v99 dst_sel:BYTE_3 dst_unused:UNUSED_PAD src0_sel:DWORD
	v_mul_f32_e32 v100, 0x437f0000, v100
	v_mul_f32_e32 v96, 0x437f0000, v96
	v_rndne_f32_e32 v100, v100
	v_rndne_f32_e32 v96, v96
	v_lshl_or_b32 v97, v97, 8, v106
	v_add_f32_e32 v92, 1.0, v92
	v_max_f32_e32 v100, 1.0, v100
	v_max_f32_e32 v96, 1.0, v96
	v_mul_f32_e32 v101, 0x437f0000, v101
	v_mul_f32_e32 v102, 0x437f0000, v102
	v_or3_b32 v97, v97, v98, v99
	v_cvt_u32_f32_e32 v100, v100
	v_cvt_u32_f32_e32 v96, v96
	v_rndne_f32_e32 v101, v101
	v_rndne_f32_e32 v102, v102
	v_max_f32_e32 v101, 1.0, v101
	v_max_f32_e32 v102, 1.0, v102
	v_cvt_u32_f32_sdwa v101, v101 dst_sel:WORD_1 dst_unused:UNUSED_PAD src0_sel:DWORD
	v_cvt_u32_f32_sdwa v102, v102 dst_sel:BYTE_3 dst_unused:UNUSED_PAD src0_sel:DWORD
	v_lshl_or_b32 v96, v96, 8, v100
	v_fma_f32 v88, v88, s100, v48
	v_or3_b32 v96, v96, v101, v102
	v_exp_f32_e32 v88, v88
	s_nop 0
	v_add_f32_e32 v88, 1.0, v88
	v_rcp_f32_e32 v92, v92
	v_fma_f32 v93, v93, s100, v53
	v_exp_f32_e32 v93, v93
	s_nop 0
	v_add_f32_e32 v93, 1.0, v93
	v_rcp_f32_e32 v88, v88
	s_nop 0
	v_mul_f32_e32 v88, 0x437f0000, v88
	v_rndne_f32_e32 v88, v88
	v_max_f32_e32 v88, 1.0, v88
	v_cvt_u32_f32_e32 v100, v88
	v_fma_f32 v89, v89, s100, v49
	v_exp_f32_e32 v89, v89
	s_nop 0
	v_add_f32_e32 v89, 1.0, v89
	v_rcp_f32_e32 v88, v93
	v_fma_f32 v94, v94, s100, v54
	v_exp_f32_e32 v94, v94
	v_rcp_f32_e32 v89, v89
	v_add_f32_e32 v93, 1.0, v94
	v_fma_f32 v90, v90, s100, v50
	v_exp_f32_e32 v90, v90
	s_nop 0
	v_add_f32_e32 v90, 1.0, v90
	v_rcp_f32_e32 v93, v93
	v_fma_f32 v95, v95, s100, v55
	v_exp_f32_e32 v95, v95
	v_rcp_f32_e32 v90, v90
	v_add_f32_e32 v94, 1.0, v95
	v_fma_f32 v91, v91, s100, v51
	v_exp_f32_e32 v91, v91
	s_nop 0
	v_add_f32_e32 v91, 1.0, v91
	v_rcp_f32_e32 v94, v94
	v_mul_f32_e32 v92, 0x437f0000, v92
	v_mul_f32_e32 v88, 0x437f0000, v88
	v_rndne_f32_e32 v92, v92
	v_rndne_f32_e32 v88, v88
	v_mul_f32_e32 v93, 0x437f0000, v93
	v_mul_f32_e32 v94, 0x437f0000, v94
; __device__ __forceinline__ float sigmoidf_(float x) { return 1.0f / (1.0f + __expf(-x)); }
;     __device__ __forceinline__ void operator()(const f32x4 (&acc)[2][2][4][2], const Unit& u, int wr, int wc, int fr, int fq) const {
;     ...
;                 for (int bj = 0; bj < 2; ++bj) { const f32x4 v0 = acc[ai][bj][m][0] + bv[bj][0], v1 = acc[ai][bj][m][1] + bv[bj][1];
;                     unsigned q[8];
; #pragma unroll
;                     for (int j = 0; j < 4; ++j) { q[j] = (unsigned)fmaxf(__builtin_rintf(sigmoidf_(v0[j]) * 255.f), 1.f); q[4 + j] = (unsigned)fmaxf(__builtin_rintf(sigmoidf_(v1[j]) * 255.f), 1.f); }
;                     u32x2 w; w.x = q[0] | (q[1] << 8) | (q[2] << 16) | (q[3] << 24); w.y = q[4] | (q[5] << 8) | (q[6] << 16) | (q[7] << 24);
;                     *(u32x2*)(rowp + bj * HALF) = w; } }
	v_fma_f32 v84, v84, s100, v36
	v_max_f32_e32 v92, 1.0, v92
	v_max_f32_e32 v88, 1.0, v88
	v_rndne_f32_e32 v93, v93
	v_rndne_f32_e32 v94, v94
	v_exp_f32_e32 v84, v84
	v_cvt_u32_f32_e32 v92, v92
	v_cvt_u32_f32_e32 v88, v88
	v_mul_f32_e32 v89, 0x437f0000, v89
	v_max_f32_e32 v93, 1.0, v93
	v_max_f32_e32 v94, 1.0, v94
	v_rcp_f32_e32 v91, v91
	v_rndne_f32_e32 v89, v89
	v_cvt_u32_f32_sdwa v93, v93 dst_sel:WORD_1 dst_unused:UNUSED_PAD src0_sel:DWORD
	v_mul_f32_e32 v90, 0x437f0000, v90
	v_cvt_u32_f32_sdwa v94, v94 dst_sel:BYTE_3 dst_unused:UNUSED_PAD src0_sel:DWORD
	v_mul_f32_e32 v91, 0x437f0000, v91
	v_max_f32_e32 v89, 1.0, v89
	v_rndne_f32_e32 v90, v90
	v_rndne_f32_e32 v91, v91
	v_cvt_u32_f32_e32 v89, v89
	v_max_f32_e32 v90, 1.0, v90
	v_max_f32_e32 v91, 1.0, v91
	v_add_f32_e32 v84, 1.0, v84
	v_cvt_u32_f32_sdwa v90, v90 dst_sel:WORD_1 dst_unused:UNUSED_PAD src0_sel:DWORD
	v_cvt_u32_f32_sdwa v91, v91 dst_sel:BYTE_3 dst_unused:UNUSED_PAD src0_sel:DWORD
	v_lshl_or_b32 v88, v88, 8, v92
	v_or3_b32 v88, v88, v93, v94
	global_store_dwordx2 v[112:113], v[96:97], off offset:128
	v_or_b32_e32 v96, 48, v174
	v_mad_i64_i32 v[96:97], s[2:3], v96, s55, v[164:165]
	v_lshl_or_b32 v89, v89, 8, v100
	v_lshl_add_u64 v[96:97], v[96:97], 0, v[162:163]
	v_or3_b32 v89, v89, v90, v91
	global_store_dwordx2 v[96:97], v[88:89], off
	v_fma_f32 v80, v80, s100, v32
	v_exp_f32_e32 v80, v80
	s_nop 0
	v_add_f32_e32 v80, 1.0, v80
	v_rcp_f32_e32 v84, v84
	v_fma_f32 v85, v85, s100, v37
	v_exp_f32_e32 v85, v85
	s_nop 0
	v_add_f32_e32 v85, 1.0, v85
	v_rcp_f32_e32 v80, v80
	s_nop 0
	v_mul_f32_e32 v80, 0x437f0000, v80
	v_rndne_f32_e32 v80, v80
	v_max_f32_e32 v80, 1.0, v80
	v_cvt_u32_f32_e32 v90, v80
	v_fma_f32 v81, v81, s100, v33
	v_exp_f32_e32 v81, v81
	s_nop 0
	v_add_f32_e32 v81, 1.0, v81
	v_rcp_f32_e32 v80, v85
	v_fma_f32 v86, v86, s100, v38
	v_exp_f32_e32 v86, v86
	v_rcp_f32_e32 v81, v81
	v_add_f32_e32 v85, 1.0, v86
	v_fma_f32 v82, v82, s100, v34
	v_exp_f32_e32 v82, v82
	s_nop 0
	v_add_f32_e32 v82, 1.0, v82
	v_rcp_f32_e32 v85, v85
	v_fma_f32 v87, v87, s100, v39
	v_exp_f32_e32 v87, v87
	v_rcp_f32_e32 v82, v82
	v_add_f32_e32 v86, 1.0, v87
	v_fma_f32 v83, v83, s100, v35
	v_exp_f32_e32 v83, v83
	s_nop 0
	v_add_f32_e32 v83, 1.0, v83
	v_rcp_f32_e32 v86, v86
	v_mul_f32_e32 v81, 0x437f0000, v81
	v_rndne_f32_e32 v81, v81
	v_mul_f32_e32 v82, 0x437f0000, v82
	v_rcp_f32_e32 v83, v83
	s_nop 0
	v_mul_f32_e32 v83, 0x437f0000, v83
	v_max_f32_e32 v81, 1.0, v81
	v_rndne_f32_e32 v82, v82
	v_rndne_f32_e32 v83, v83
	v_fma_f32 v76, v76, s100, v52
	v_cvt_u32_f32_e32 v81, v81
	v_max_f32_e32 v82, 1.0, v82
	v_max_f32_e32 v83, 1.0, v83
	v_exp_f32_e32 v76, v76
	v_cvt_u32_f32_sdwa v82, v82 dst_sel:WORD_1 dst_unused:UNUSED_PAD src0_sel:DWORD
	v_cvt_u32_f32_sdwa v83, v83 dst_sel:BYTE_3 dst_unused:UNUSED_PAD src0_sel:DWORD
	v_mul_f32_e32 v84, 0x437f0000, v84
	v_mul_f32_e32 v80, 0x437f0000, v80
	v_rndne_f32_e32 v84, v84
	v_rndne_f32_e32 v80, v80
	v_lshl_or_b32 v81, v81, 8, v90
	v_add_f32_e32 v76, 1.0, v76
	v_max_f32_e32 v84, 1.0, v84
	v_max_f32_e32 v80, 1.0, v80
	v_mul_f32_e32 v85, 0x437f0000, v85
	v_mul_f32_e32 v86, 0x437f0000, v86
	v_or3_b32 v81, v81, v82, v83
	v_cvt_u32_f32_e32 v84, v84
	v_cvt_u32_f32_e32 v80, v80
	v_rndne_f32_e32 v85, v85
	v_rndne_f32_e32 v86, v86
	v_max_f32_e32 v85, 1.0, v85
	v_max_f32_e32 v86, 1.0, v86
	v_cvt_u32_f32_sdwa v85, v85 dst_sel:WORD_1 dst_unused:UNUSED_PAD src0_sel:DWORD
	v_cvt_u32_f32_sdwa v86, v86 dst_sel:BYTE_3 dst_unused:UNUSED_PAD src0_sel:DWORD
	v_lshl_or_b32 v80, v80, 8, v84
	v_fma_f32 v72, v72, s100, v48
	v_or3_b32 v80, v80, v85, v86
	v_exp_f32_e32 v72, v72
	s_nop 0
	v_add_f32_e32 v72, 1.0, v72
	v_rcp_f32_e32 v76, v76
	v_fma_f32 v77, v77, s100, v53
	v_exp_f32_e32 v77, v77
	s_nop 0
	v_add_f32_e32 v77, 1.0, v77
	v_rcp_f32_e32 v72, v72
	s_nop 0
	v_mul_f32_e32 v72, 0x437f0000, v72
	v_rndne_f32_e32 v72, v72
	v_max_f32_e32 v72, 1.0, v72
	v_cvt_u32_f32_e32 v84, v72
	v_fma_f32 v73, v73, s100, v49
	v_exp_f32_e32 v73, v73
	s_nop 0
	v_add_f32_e32 v73, 1.0, v73
	v_rcp_f32_e32 v72, v77
	v_fma_f32 v78, v78, s100, v54
	v_exp_f32_e32 v78, v78
	v_rcp_f32_e32 v73, v73
	v_add_f32_e32 v77, 1.0, v78
	v_fma_f32 v74, v74, s100, v50
	v_exp_f32_e32 v74, v74
	s_nop 0
	v_add_f32_e32 v74, 1.0, v74
	v_rcp_f32_e32 v77, v77
	v_fma_f32 v79, v79, s100, v55
	v_exp_f32_e32 v79, v79
	v_rcp_f32_e32 v74, v74
	v_add_f32_e32 v78, 1.0, v79
	v_fma_f32 v75, v75, s100, v51
	v_exp_f32_e32 v75, v75
	s_nop 0
	v_add_f32_e32 v75, 1.0, v75
	v_rcp_f32_e32 v78, v78
	v_mul_f32_e32 v76, 0x437f0000, v76
	v_mul_f32_e32 v72, 0x437f0000, v72
	v_rndne_f32_e32 v76, v76
	v_rndne_f32_e32 v72, v72
	v_mul_f32_e32 v77, 0x437f0000, v77
	v_mul_f32_e32 v78, 0x437f0000, v78
	v_fma_f32 v68, v68, s100, v36
	v_max_f32_e32 v76, 1.0, v76
	v_max_f32_e32 v72, 1.0, v72
	v_rndne_f32_e32 v77, v77
	v_rndne_f32_e32 v78, v78
	v_exp_f32_e32 v68, v68
	v_cvt_u32_f32_e32 v76, v76
	v_cvt_u32_f32_e32 v72, v72
	v_mul_f32_e32 v73, 0x437f0000, v73
	v_max_f32_e32 v77, 1.0, v77
	v_max_f32_e32 v78, 1.0, v78
	v_rcp_f32_e32 v75, v75
	v_rndne_f32_e32 v73, v73
	v_cvt_u32_f32_sdwa v77, v77 dst_sel:WORD_1 dst_unused:UNUSED_PAD src0_sel:DWORD
	v_mul_f32_e32 v74, 0x437f0000, v74
	v_cvt_u32_f32_sdwa v78, v78 dst_sel:BYTE_3 dst_unused:UNUSED_PAD src0_sel:DWORD
	v_mul_f32_e32 v75, 0x437f0000, v75
	v_max_f32_e32 v73, 1.0, v73
	v_rndne_f32_e32 v74, v74
	v_rndne_f32_e32 v75, v75
	v_cvt_u32_f32_e32 v73, v73
	v_max_f32_e32 v74, 1.0, v74
	v_max_f32_e32 v75, 1.0, v75
	v_add_f32_e32 v68, 1.0, v68
	v_cvt_u32_f32_sdwa v74, v74 dst_sel:WORD_1 dst_unused:UNUSED_PAD src0_sel:DWORD
	v_cvt_u32_f32_sdwa v75, v75 dst_sel:BYTE_3 dst_unused:UNUSED_PAD src0_sel:DWORD
	v_lshl_or_b32 v72, v72, 8, v76
; __device__ __forceinline__ float sigmoidf_(float x) { return 1.0f / (1.0f + __expf(-x)); }
;     __device__ __forceinline__ void operator()(const f32x4 (&acc)[2][2][4][2], const Unit& u, int wr, int wc, int fr, int fq) const {
;     ...
;                 for (int bj = 0; bj < 2; ++bj) { const f32x4 v0 = acc[ai][bj][m][0] + bv[bj][0], v1 = acc[ai][bj][m][1] + bv[bj][1];
;                     unsigned q[8];
; #pragma unroll
;                     for (int j = 0; j < 4; ++j) { q[j] = (unsigned)fmaxf(__builtin_rintf(sigmoidf_(v0[j]) * 255.f), 1.f); q[4 + j] = (unsigned)fmaxf(__builtin_rintf(sigmoidf_(v1[j]) * 255.f), 1.f); }
;                     u32x2 w; w.x = q[0] | (q[1] << 8) | (q[2] << 16) | (q[3] << 24); w.y = q[4] | (q[5] << 8) | (q[6] << 16) | (q[7] << 24);
;                     *(u32x2*)(rowp + bj * HALF) = w; } }
	v_or3_b32 v72, v72, v77, v78
	global_store_dwordx2 v[96:97], v[80:81], off offset:128
	v_add_u32_e32 v80, 0x80, v174
	v_mad_i64_i32 v[80:81], s[2:3], v80, s55, v[164:165]
	v_lshl_or_b32 v73, v73, 8, v84
	v_lshl_add_u64 v[80:81], v[80:81], 0, v[162:163]
	v_or3_b32 v73, v73, v74, v75
	global_store_dwordx2 v[80:81], v[72:73], off
	v_fma_f32 v64, v64, s100, v32
	v_exp_f32_e32 v64, v64
	s_nop 0
	v_add_f32_e32 v64, 1.0, v64
	v_rcp_f32_e32 v68, v68
	v_fma_f32 v69, v69, s100, v37
	v_exp_f32_e32 v69, v69
	s_nop 0
	v_add_f32_e32 v69, 1.0, v69
	v_rcp_f32_e32 v64, v64
	s_nop 0
	v_mul_f32_e32 v64, 0x437f0000, v64
	v_rndne_f32_e32 v64, v64
	v_max_f32_e32 v64, 1.0, v64
	v_cvt_u32_f32_e32 v74, v64
	v_fma_f32 v65, v65, s100, v33
	v_exp_f32_e32 v65, v65
	s_nop 0
	v_add_f32_e32 v65, 1.0, v65
	v_rcp_f32_e32 v64, v69
	v_fma_f32 v70, v70, s100, v38
	v_exp_f32_e32 v70, v70
	v_rcp_f32_e32 v65, v65
	v_add_f32_e32 v69, 1.0, v70
	v_fma_f32 v66, v66, s100, v34
	v_exp_f32_e32 v66, v66
	s_nop 0
	v_add_f32_e32 v66, 1.0, v66
	v_rcp_f32_e32 v69, v69
	v_fma_f32 v71, v71, s100, v39
	v_exp_f32_e32 v71, v71
	v_rcp_f32_e32 v66, v66
	v_add_f32_e32 v70, 1.0, v71
	v_fma_f32 v67, v67, s100, v35
	v_exp_f32_e32 v67, v67
	s_nop 0
	v_add_f32_e32 v67, 1.0, v67
	v_rcp_f32_e32 v70, v70
	v_mul_f32_e32 v65, 0x437f0000, v65
	v_rndne_f32_e32 v65, v65
	v_mul_f32_e32 v66, 0x437f0000, v66
	v_rcp_f32_e32 v67, v67
	s_nop 0
	v_mul_f32_e32 v67, 0x437f0000, v67
	v_max_f32_e32 v65, 1.0, v65
	v_rndne_f32_e32 v66, v66
	v_rndne_f32_e32 v67, v67
	v_fma_f32 v60, v60, s100, v52
	v_cvt_u32_f32_e32 v65, v65
	v_max_f32_e32 v66, 1.0, v66
	v_max_f32_e32 v67, 1.0, v67
	v_exp_f32_e32 v60, v60
	v_cvt_u32_f32_sdwa v66, v66 dst_sel:WORD_1 dst_unused:UNUSED_PAD src0_sel:DWORD
	v_cvt_u32_f32_sdwa v67, v67 dst_sel:BYTE_3 dst_unused:UNUSED_PAD src0_sel:DWORD
	v_mul_f32_e32 v68, 0x437f0000, v68
	v_mul_f32_e32 v64, 0x437f0000, v64
	v_rndne_f32_e32 v68, v68
	v_rndne_f32_e32 v64, v64
	v_lshl_or_b32 v65, v65, 8, v74
	v_add_f32_e32 v60, 1.0, v60
	v_max_f32_e32 v68, 1.0, v68
	v_max_f32_e32 v64, 1.0, v64
	v_mul_f32_e32 v69, 0x437f0000, v69
	v_mul_f32_e32 v70, 0x437f0000, v70
	v_or3_b32 v65, v65, v66, v67
	v_cvt_u32_f32_e32 v68, v68
	v_cvt_u32_f32_e32 v64, v64
	v_rndne_f32_e32 v69, v69
	v_rndne_f32_e32 v70, v70
	v_max_f32_e32 v69, 1.0, v69
	v_max_f32_e32 v70, 1.0, v70
	v_cvt_u32_f32_sdwa v69, v69 dst_sel:WORD_1 dst_unused:UNUSED_PAD src0_sel:DWORD
	v_cvt_u32_f32_sdwa v70, v70 dst_sel:BYTE_3 dst_unused:UNUSED_PAD src0_sel:DWORD
	v_lshl_or_b32 v64, v64, 8, v68
	v_fma_f32 v56, v56, s100, v48
	v_or3_b32 v64, v64, v69, v70
	v_exp_f32_e32 v56, v56
	s_nop 0
	v_add_f32_e32 v56, 1.0, v56
	v_rcp_f32_e32 v60, v60
	v_fma_f32 v61, v61, s100, v53
	v_exp_f32_e32 v61, v61
	s_nop 0
	v_add_f32_e32 v61, 1.0, v61
	v_rcp_f32_e32 v56, v56
	s_nop 0
	v_mul_f32_e32 v56, 0x437f0000, v56
	v_rndne_f32_e32 v56, v56
	v_max_f32_e32 v56, 1.0, v56
	v_cvt_u32_f32_e32 v68, v56
	v_fma_f32 v57, v57, s100, v49
	v_exp_f32_e32 v57, v57
	s_nop 0
	v_add_f32_e32 v57, 1.0, v57
	v_rcp_f32_e32 v56, v61
	v_fma_f32 v62, v62, s100, v54
	v_exp_f32_e32 v62, v62
	v_rcp_f32_e32 v57, v57
	v_add_f32_e32 v61, 1.0, v62
	v_fma_f32 v58, v58, s100, v50
	v_exp_f32_e32 v58, v58
	s_nop 0
	v_add_f32_e32 v58, 1.0, v58
	v_rcp_f32_e32 v61, v61
	v_fma_f32 v63, v63, s100, v55
	v_exp_f32_e32 v63, v63
	v_rcp_f32_e32 v58, v58
	v_add_f32_e32 v62, 1.0, v63
	v_fma_f32 v59, v59, s100, v51
	v_exp_f32_e32 v59, v59
	s_nop 0
	v_add_f32_e32 v59, 1.0, v59
	v_rcp_f32_e32 v62, v62
	v_mul_f32_e32 v60, 0x437f0000, v60
	v_mul_f32_e32 v56, 0x437f0000, v56
	v_rndne_f32_e32 v60, v60
	v_rndne_f32_e32 v56, v56
	v_mul_f32_e32 v61, 0x437f0000, v61
	v_mul_f32_e32 v62, 0x437f0000, v62
	v_fma_f32 v44, v44, s100, v36
	v_max_f32_e32 v60, 1.0, v60
	v_max_f32_e32 v56, 1.0, v56
	v_rndne_f32_e32 v61, v61
	v_rndne_f32_e32 v62, v62
	v_exp_f32_e32 v44, v44
	v_cvt_u32_f32_e32 v60, v60
	v_cvt_u32_f32_e32 v56, v56
	v_mul_f32_e32 v57, 0x437f0000, v57
	v_max_f32_e32 v61, 1.0, v61
	v_max_f32_e32 v62, 1.0, v62
	v_rcp_f32_e32 v59, v59
	v_rndne_f32_e32 v57, v57
	v_cvt_u32_f32_sdwa v61, v61 dst_sel:WORD_1 dst_unused:UNUSED_PAD src0_sel:DWORD
	v_mul_f32_e32 v58, 0x437f0000, v58
	v_cvt_u32_f32_sdwa v62, v62 dst_sel:BYTE_3 dst_unused:UNUSED_PAD src0_sel:DWORD
	v_mul_f32_e32 v59, 0x437f0000, v59
	v_max_f32_e32 v57, 1.0, v57
	v_rndne_f32_e32 v58, v58
	v_rndne_f32_e32 v59, v59
	v_cvt_u32_f32_e32 v57, v57
	v_max_f32_e32 v58, 1.0, v58
	v_max_f32_e32 v59, 1.0, v59
	v_add_f32_e32 v44, 1.0, v44
	v_cvt_u32_f32_sdwa v58, v58 dst_sel:WORD_1 dst_unused:UNUSED_PAD src0_sel:DWORD
	v_cvt_u32_f32_sdwa v59, v59 dst_sel:BYTE_3 dst_unused:UNUSED_PAD src0_sel:DWORD
	v_lshl_or_b32 v56, v56, 8, v60
	v_or3_b32 v56, v56, v61, v62
	global_store_dwordx2 v[80:81], v[64:65], off offset:128
	v_add_u32_e32 v64, 0x90, v174
	v_mad_i64_i32 v[64:65], s[2:3], v64, s55, v[164:165]
	v_lshl_or_b32 v57, v57, 8, v68
	v_lshl_add_u64 v[64:65], v[64:65], 0, v[162:163]
	v_or3_b32 v57, v57, v58, v59
	global_store_dwordx2 v[64:65], v[56:57], off
	v_fma_f32 v40, v40, s100, v32
	v_exp_f32_e32 v40, v40
	s_nop 0
	v_add_f32_e32 v40, 1.0, v40
	v_rcp_f32_e32 v44, v44
	v_fma_f32 v45, v45, s100, v37
	v_exp_f32_e32 v45, v45
	s_nop 0
	v_add_f32_e32 v45, 1.0, v45
	v_rcp_f32_e32 v40, v40
	s_nop 0
	v_mul_f32_e32 v40, 0x437f0000, v40
	v_rndne_f32_e32 v40, v40
	v_max_f32_e32 v40, 1.0, v40
	v_cvt_u32_f32_e32 v58, v40
	v_fma_f32 v41, v41, s100, v33
	v_exp_f32_e32 v41, v41
	s_nop 0
	v_add_f32_e32 v41, 1.0, v41
	v_rcp_f32_e32 v40, v45
	v_fma_f32 v46, v46, s100, v38
	v_exp_f32_e32 v46, v46
	v_rcp_f32_e32 v41, v41
	v_add_f32_e32 v45, 1.0, v46
	v_fma_f32 v42, v42, s100, v34
	v_exp_f32_e32 v42, v42
	s_nop 0
; __device__ __forceinline__ float sigmoidf_(float x) { return 1.0f / (1.0f + __expf(-x)); }
;     __device__ __forceinline__ void operator()(const f32x4 (&acc)[2][2][4][2], const Unit& u, int wr, int wc, int fr, int fq) const {
;     ...
;                 for (int bj = 0; bj < 2; ++bj) { const f32x4 v0 = acc[ai][bj][m][0] + bv[bj][0], v1 = acc[ai][bj][m][1] + bv[bj][1];
;                     unsigned q[8];
; #pragma unroll
;                     for (int j = 0; j < 4; ++j) { q[j] = (unsigned)fmaxf(__builtin_rintf(sigmoidf_(v0[j]) * 255.f), 1.f); q[4 + j] = (unsigned)fmaxf(__builtin_rintf(sigmoidf_(v1[j]) * 255.f), 1.f); }
;                     u32x2 w; w.x = q[0] | (q[1] << 8) | (q[2] << 16) | (q[3] << 24); w.y = q[4] | (q[5] << 8) | (q[6] << 16) | (q[7] << 24);
;                     *(u32x2*)(rowp + bj * HALF) = w; } }
	v_add_f32_e32 v42, 1.0, v42
	v_rcp_f32_e32 v45, v45
	v_fma_f32 v47, v47, s100, v39
	v_exp_f32_e32 v47, v47
	v_rcp_f32_e32 v42, v42
	v_add_f32_e32 v46, 1.0, v47
	v_fma_f32 v43, v43, s100, v35
	v_exp_f32_e32 v43, v43
	s_nop 0
	v_add_f32_e32 v43, 1.0, v43
	v_rcp_f32_e32 v46, v46
	v_mul_f32_e32 v41, 0x437f0000, v41
	v_rndne_f32_e32 v41, v41
	v_mul_f32_e32 v42, 0x437f0000, v42
	v_rcp_f32_e32 v43, v43
	s_nop 0
	v_mul_f32_e32 v43, 0x437f0000, v43
	v_max_f32_e32 v41, 1.0, v41
	v_rndne_f32_e32 v42, v42
	v_rndne_f32_e32 v43, v43
	v_fma_f32 v28, v28, s100, v52
	v_cvt_u32_f32_e32 v41, v41
	v_max_f32_e32 v42, 1.0, v42
	v_max_f32_e32 v43, 1.0, v43
	v_exp_f32_e32 v28, v28
	v_cvt_u32_f32_sdwa v42, v42 dst_sel:WORD_1 dst_unused:UNUSED_PAD src0_sel:DWORD
	v_cvt_u32_f32_sdwa v43, v43 dst_sel:BYTE_3 dst_unused:UNUSED_PAD src0_sel:DWORD
	v_mul_f32_e32 v44, 0x437f0000, v44
	v_mul_f32_e32 v40, 0x437f0000, v40
	v_rndne_f32_e32 v44, v44
	v_rndne_f32_e32 v40, v40
	v_lshl_or_b32 v41, v41, 8, v58
	v_add_f32_e32 v28, 1.0, v28
	v_max_f32_e32 v44, 1.0, v44
	v_max_f32_e32 v40, 1.0, v40
	v_mul_f32_e32 v45, 0x437f0000, v45
	v_mul_f32_e32 v46, 0x437f0000, v46
	v_or3_b32 v41, v41, v42, v43
	v_cvt_u32_f32_e32 v44, v44
	v_cvt_u32_f32_e32 v40, v40
	v_rndne_f32_e32 v45, v45
	v_rndne_f32_e32 v46, v46
	v_max_f32_e32 v45, 1.0, v45
	v_max_f32_e32 v46, 1.0, v46
	v_cvt_u32_f32_sdwa v45, v45 dst_sel:WORD_1 dst_unused:UNUSED_PAD src0_sel:DWORD
	v_cvt_u32_f32_sdwa v46, v46 dst_sel:BYTE_3 dst_unused:UNUSED_PAD src0_sel:DWORD
	v_lshl_or_b32 v40, v40, 8, v44
	v_fma_f32 v24, v24, s100, v48
	v_or3_b32 v40, v40, v45, v46
	v_exp_f32_e32 v24, v24
	s_nop 0
	v_add_f32_e32 v24, 1.0, v24
	v_rcp_f32_e32 v28, v28
	v_fma_f32 v29, v29, s100, v53
	v_exp_f32_e32 v29, v29
	s_nop 0
	v_add_f32_e32 v29, 1.0, v29
	v_rcp_f32_e32 v24, v24
	s_nop 0
	v_mul_f32_e32 v24, 0x437f0000, v24
	v_rndne_f32_e32 v24, v24
	v_max_f32_e32 v24, 1.0, v24
	v_cvt_u32_f32_e32 v44, v24
	v_fma_f32 v25, v25, s100, v49
	v_exp_f32_e32 v25, v25
	s_nop 0
	v_add_f32_e32 v25, 1.0, v25
	v_rcp_f32_e32 v24, v29
	v_fma_f32 v30, v30, s100, v54
	v_exp_f32_e32 v30, v30
	v_rcp_f32_e32 v25, v25
	v_add_f32_e32 v29, 1.0, v30
	v_fma_f32 v26, v26, s100, v50
	v_exp_f32_e32 v26, v26
	s_nop 0
	v_add_f32_e32 v26, 1.0, v26
	v_rcp_f32_e32 v29, v29
	v_fma_f32 v31, v31, s100, v55
	v_exp_f32_e32 v31, v31
	v_rcp_f32_e32 v26, v26
	v_add_f32_e32 v30, 1.0, v31
	v_fma_f32 v27, v27, s100, v51
	v_exp_f32_e32 v27, v27
	s_nop 0
	v_add_f32_e32 v27, 1.0, v27
	v_rcp_f32_e32 v30, v30
	v_mul_f32_e32 v28, 0x437f0000, v28
	v_mul_f32_e32 v24, 0x437f0000, v24
	v_rndne_f32_e32 v28, v28
	v_rndne_f32_e32 v24, v24
	v_mul_f32_e32 v29, 0x437f0000, v29
	v_mul_f32_e32 v30, 0x437f0000, v30
	v_fma_f32 v20, v20, s100, v36
	v_max_f32_e32 v28, 1.0, v28
	v_max_f32_e32 v24, 1.0, v24
	v_rndne_f32_e32 v29, v29
	v_rndne_f32_e32 v30, v30
	v_exp_f32_e32 v20, v20
	v_cvt_u32_f32_e32 v28, v28
	v_cvt_u32_f32_e32 v24, v24
	v_mul_f32_e32 v25, 0x437f0000, v25
	v_max_f32_e32 v29, 1.0, v29
	v_max_f32_e32 v30, 1.0, v30
	v_rcp_f32_e32 v27, v27
	v_rndne_f32_e32 v25, v25
	v_cvt_u32_f32_sdwa v29, v29 dst_sel:WORD_1 dst_unused:UNUSED_PAD src0_sel:DWORD
	v_mul_f32_e32 v26, 0x437f0000, v26
	v_cvt_u32_f32_sdwa v30, v30 dst_sel:BYTE_3 dst_unused:UNUSED_PAD src0_sel:DWORD
	v_mul_f32_e32 v27, 0x437f0000, v27
	v_max_f32_e32 v25, 1.0, v25
	v_rndne_f32_e32 v26, v26
	v_rndne_f32_e32 v27, v27
	v_cvt_u32_f32_e32 v25, v25
	v_max_f32_e32 v26, 1.0, v26
	v_max_f32_e32 v27, 1.0, v27
	v_add_f32_e32 v20, 1.0, v20
	v_cvt_u32_f32_sdwa v26, v26 dst_sel:WORD_1 dst_unused:UNUSED_PAD src0_sel:DWORD
	v_cvt_u32_f32_sdwa v27, v27 dst_sel:BYTE_3 dst_unused:UNUSED_PAD src0_sel:DWORD
	v_lshl_or_b32 v24, v24, 8, v28
	v_or3_b32 v24, v24, v29, v30
	global_store_dwordx2 v[64:65], v[40:41], off offset:128
	v_add_u32_e32 v40, 0xa0, v174
	v_mad_i64_i32 v[40:41], s[2:3], v40, s55, v[164:165]
	v_lshl_or_b32 v25, v25, 8, v44
	v_lshl_add_u64 v[40:41], v[40:41], 0, v[162:163]
	v_or3_b32 v25, v25, v26, v27
	global_store_dwordx2 v[40:41], v[24:25], off
	v_fma_f32 v16, v16, s100, v32
	v_exp_f32_e32 v16, v16
	s_nop 0
	v_add_f32_e32 v16, 1.0, v16
	v_rcp_f32_e32 v20, v20
	v_fma_f32 v21, v21, s100, v37
	v_exp_f32_e32 v21, v21
	s_nop 0
	v_add_f32_e32 v21, 1.0, v21
	v_rcp_f32_e32 v16, v16
	s_nop 0
	v_mul_f32_e32 v16, 0x437f0000, v16
	v_rndne_f32_e32 v16, v16
	v_max_f32_e32 v16, 1.0, v16
	v_cvt_u32_f32_e32 v26, v16
	v_fma_f32 v17, v17, s100, v33
	v_exp_f32_e32 v17, v17
	s_nop 0
	v_add_f32_e32 v17, 1.0, v17
	v_rcp_f32_e32 v16, v21
	v_fma_f32 v22, v22, s100, v38
	v_exp_f32_e32 v22, v22
	v_rcp_f32_e32 v17, v17
	v_add_f32_e32 v21, 1.0, v22
	v_fma_f32 v18, v18, s100, v34
	v_exp_f32_e32 v18, v18
	s_nop 0
	v_add_f32_e32 v18, 1.0, v18
	v_rcp_f32_e32 v21, v21
	v_fma_f32 v23, v23, s100, v39
	v_exp_f32_e32 v23, v23
	v_rcp_f32_e32 v18, v18
	v_add_f32_e32 v22, 1.0, v23
	v_fma_f32 v19, v19, s100, v35
	v_exp_f32_e32 v19, v19
	s_nop 0
	v_add_f32_e32 v19, 1.0, v19
	v_rcp_f32_e32 v22, v22
	v_mul_f32_e32 v17, 0x437f0000, v17
	v_rndne_f32_e32 v17, v17
	v_mul_f32_e32 v18, 0x437f0000, v18
	v_rcp_f32_e32 v19, v19
	s_nop 0
	v_mul_f32_e32 v19, 0x437f0000, v19
	v_max_f32_e32 v17, 1.0, v17
	v_rndne_f32_e32 v18, v18
	v_rndne_f32_e32 v19, v19
	v_fma_f32 v12, v12, s100, v52
	v_cvt_u32_f32_e32 v17, v17
	v_max_f32_e32 v18, 1.0, v18
	v_max_f32_e32 v19, 1.0, v19
	v_exp_f32_e32 v12, v12
	v_cvt_u32_f32_sdwa v18, v18 dst_sel:WORD_1 dst_unused:UNUSED_PAD src0_sel:DWORD
; __device__ __forceinline__ float sigmoidf_(float x) { return 1.0f / (1.0f + __expf(-x)); }
; #define PG8_BAR __builtin_amdgcn_s_barrier()
;     __device__ __forceinline__ void operator()(const f32x4 (&acc)[2][2][4][2], const Unit& u, int wr, int wc, int fr, int fq) const {
;     ...
;                 for (int bj = 0; bj < 2; ++bj) { const f32x4 v0 = acc[ai][bj][m][0] + bv[bj][0], v1 = acc[ai][bj][m][1] + bv[bj][1];
;                     unsigned q[8];
; #pragma unroll
;                     for (int j = 0; j < 4; ++j) { q[j] = (unsigned)fmaxf(__builtin_rintf(sigmoidf_(v0[j]) * 255.f), 1.f); q[4 + j] = (unsigned)fmaxf(__builtin_rintf(sigmoidf_(v1[j]) * 255.f), 1.f); }
;                     u32x2 w; w.x = q[0] | (q[1] << 8) | (q[2] << 16) | (q[3] << 24); w.y = q[4] | (q[5] << 8) | (q[6] << 16) | (q[7] << 24);
;                     *(u32x2*)(rowp + bj * HALF) = w; } }
; template <class Epi, class Sched, bool ALIGN_EPI = true>
; __device__ __forceinline__ void gemm_phase(LAS unsigned char* lds, const Gemm g, const Sched& S, const Epi& E) {
;     ...
;         if (!has_next) break;
; #pragma unroll
;         for (int a = 0; a < 2; ++a)
; #pragma unroll
;             for (int b = 0; b < 2; ++b)
; #pragma unroll
;                 for (int m = 0; m < 4; ++m)
; #pragma unroll
;                     for (int n = 0; n < 2; ++n) acc[a][b][m][n] = (f32x4){0.f, 0.f, 0.f, 0.f};
;         cur = nxt; cA = nA; cB = nB; ++ui;
;         if constexpr (ALIGN_EPI) { if (wr == 1) PG8_BAR; }
	v_cvt_u32_f32_sdwa v19, v19 dst_sel:BYTE_3 dst_unused:UNUSED_PAD src0_sel:DWORD
	v_mul_f32_e32 v20, 0x437f0000, v20
	v_mul_f32_e32 v16, 0x437f0000, v16
	v_rndne_f32_e32 v20, v20
	v_rndne_f32_e32 v16, v16
	v_lshl_or_b32 v17, v17, 8, v26
	v_add_f32_e32 v12, 1.0, v12
	v_max_f32_e32 v20, 1.0, v20
	v_max_f32_e32 v16, 1.0, v16
	v_mul_f32_e32 v21, 0x437f0000, v21
	v_mul_f32_e32 v22, 0x437f0000, v22
	v_or3_b32 v17, v17, v18, v19
	v_cvt_u32_f32_e32 v20, v20
	v_cvt_u32_f32_e32 v16, v16
	v_rndne_f32_e32 v21, v21
	v_rndne_f32_e32 v22, v22
	v_max_f32_e32 v21, 1.0, v21
	v_max_f32_e32 v22, 1.0, v22
	v_cvt_u32_f32_sdwa v21, v21 dst_sel:WORD_1 dst_unused:UNUSED_PAD src0_sel:DWORD
	v_cvt_u32_f32_sdwa v22, v22 dst_sel:BYTE_3 dst_unused:UNUSED_PAD src0_sel:DWORD
	v_lshl_or_b32 v16, v16, 8, v20
	v_fma_f32 v8, v8, s100, v48
	v_or3_b32 v16, v16, v21, v22
	v_exp_f32_e32 v8, v8
	s_nop 0
	v_add_f32_e32 v8, 1.0, v8
	v_rcp_f32_e32 v12, v12
	v_fma_f32 v13, v13, s100, v53
	v_exp_f32_e32 v13, v13
	s_nop 0
	v_add_f32_e32 v13, 1.0, v13
	v_rcp_f32_e32 v8, v8
	s_nop 0
	v_mul_f32_e32 v8, 0x437f0000, v8
	v_rndne_f32_e32 v8, v8
	v_max_f32_e32 v8, 1.0, v8
	v_cvt_u32_f32_e32 v20, v8
	v_fma_f32 v9, v9, s100, v49
	v_exp_f32_e32 v9, v9
	s_nop 0
	v_add_f32_e32 v9, 1.0, v9
	v_rcp_f32_e32 v8, v13
	v_fma_f32 v14, v14, s100, v54
	v_exp_f32_e32 v14, v14
	v_rcp_f32_e32 v9, v9
	v_add_f32_e32 v13, 1.0, v14
	v_fma_f32 v10, v10, s100, v50
	v_exp_f32_e32 v10, v10
	s_nop 0
	v_add_f32_e32 v10, 1.0, v10
	v_rcp_f32_e32 v13, v13
	v_fma_f32 v15, v15, s100, v55
	v_exp_f32_e32 v15, v15
	v_rcp_f32_e32 v10, v10
	v_add_f32_e32 v14, 1.0, v15
	v_fma_f32 v11, v11, s100, v51
	v_exp_f32_e32 v11, v11
	s_nop 0
	v_add_f32_e32 v11, 1.0, v11
	v_rcp_f32_e32 v14, v14
	v_mul_f32_e32 v12, 0x437f0000, v12
	v_mul_f32_e32 v8, 0x437f0000, v8
	v_rndne_f32_e32 v12, v12
	v_rndne_f32_e32 v8, v8
	v_mul_f32_e32 v13, 0x437f0000, v13
	v_mul_f32_e32 v14, 0x437f0000, v14
	v_fma_f32 v4, v4, s100, v36
	v_max_f32_e32 v12, 1.0, v12
	v_max_f32_e32 v8, 1.0, v8
	v_rndne_f32_e32 v13, v13
	v_rndne_f32_e32 v14, v14
	v_exp_f32_e32 v4, v4
	v_cvt_u32_f32_e32 v12, v12
	v_cvt_u32_f32_e32 v8, v8
	v_mul_f32_e32 v9, 0x437f0000, v9
	v_max_f32_e32 v13, 1.0, v13
	v_max_f32_e32 v14, 1.0, v14
	v_rcp_f32_e32 v11, v11
	v_rndne_f32_e32 v9, v9
	v_cvt_u32_f32_sdwa v13, v13 dst_sel:WORD_1 dst_unused:UNUSED_PAD src0_sel:DWORD
	v_mul_f32_e32 v10, 0x437f0000, v10
	v_cvt_u32_f32_sdwa v14, v14 dst_sel:BYTE_3 dst_unused:UNUSED_PAD src0_sel:DWORD
	v_mul_f32_e32 v11, 0x437f0000, v11
	v_max_f32_e32 v9, 1.0, v9
	v_rndne_f32_e32 v10, v10
	v_rndne_f32_e32 v11, v11
	v_cvt_u32_f32_e32 v9, v9
	v_max_f32_e32 v10, 1.0, v10
	v_max_f32_e32 v11, 1.0, v11
	v_add_f32_e32 v4, 1.0, v4
	v_cvt_u32_f32_sdwa v10, v10 dst_sel:WORD_1 dst_unused:UNUSED_PAD src0_sel:DWORD
	v_cvt_u32_f32_sdwa v11, v11 dst_sel:BYTE_3 dst_unused:UNUSED_PAD src0_sel:DWORD
	v_lshl_or_b32 v8, v8, 8, v12
	v_or3_b32 v8, v8, v13, v14
	global_store_dwordx2 v[40:41], v[16:17], off offset:128
	v_add_u32_e32 v16, 0xb0, v174
	v_mad_i64_i32 v[16:17], s[2:3], v16, s55, v[164:165]
	v_lshl_or_b32 v9, v9, 8, v20
	v_lshl_add_u64 v[16:17], v[16:17], 0, v[162:163]
	v_or3_b32 v9, v9, v10, v11
	global_store_dwordx2 v[16:17], v[8:9], off
	v_fma_f32 v0, v0, s100, v32
	v_exp_f32_e32 v0, v0
	s_nop 0
	v_add_f32_e32 v0, 1.0, v0
	v_rcp_f32_e32 v4, v4
	v_fma_f32 v5, v5, s100, v37
	v_exp_f32_e32 v5, v5
	s_nop 0
	v_add_f32_e32 v5, 1.0, v5
	v_rcp_f32_e32 v0, v0
	s_nop 0
	v_mul_f32_e32 v0, 0x437f0000, v0
	v_rndne_f32_e32 v0, v0
	v_max_f32_e32 v0, 1.0, v0
	v_cvt_u32_f32_e32 v10, v0
	v_fma_f32 v1, v1, s100, v33
	v_exp_f32_e32 v1, v1
	s_nop 0
	v_add_f32_e32 v1, 1.0, v1
	v_rcp_f32_e32 v0, v5
	v_fma_f32 v6, v6, s100, v38
	v_exp_f32_e32 v6, v6
	v_rcp_f32_e32 v1, v1
	v_add_f32_e32 v5, 1.0, v6
	v_fma_f32 v2, v2, s100, v34
	v_exp_f32_e32 v2, v2
	s_nop 0
	v_add_f32_e32 v2, 1.0, v2
	v_rcp_f32_e32 v5, v5
	v_fma_f32 v7, v7, s100, v39
	v_exp_f32_e32 v7, v7
	v_rcp_f32_e32 v2, v2
	v_add_f32_e32 v6, 1.0, v7
	v_fma_f32 v3, v3, s100, v35
	v_exp_f32_e32 v3, v3
	s_nop 0
	v_add_f32_e32 v3, 1.0, v3
	v_rcp_f32_e32 v6, v6
	v_mul_f32_e32 v4, 0x437f0000, v4
	v_mul_f32_e32 v0, 0x437f0000, v0
	v_mul_f32_e32 v1, 0x437f0000, v1
	v_rcp_f32_e32 v3, v3
	v_rndne_f32_e32 v4, v4
	v_rndne_f32_e32 v0, v0
	v_rndne_f32_e32 v1, v1
	v_mul_f32_e32 v5, 0x437f0000, v5
	v_mul_f32_e32 v2, 0x437f0000, v2
	v_mul_f32_e32 v6, 0x437f0000, v6
	v_mul_f32_e32 v3, 0x437f0000, v3
	v_max_f32_e32 v4, 1.0, v4
	v_max_f32_e32 v0, 1.0, v0
	v_max_f32_e32 v1, 1.0, v1
	v_rndne_f32_e32 v5, v5
	v_rndne_f32_e32 v2, v2
	v_rndne_f32_e32 v6, v6
	v_rndne_f32_e32 v3, v3
	v_cvt_u32_f32_e32 v4, v4
	v_cvt_u32_f32_e32 v0, v0
	v_cvt_u32_f32_e32 v1, v1
	v_max_f32_e32 v5, 1.0, v5
	v_max_f32_e32 v2, 1.0, v2
	v_max_f32_e32 v6, 1.0, v6
	v_max_f32_e32 v3, 1.0, v3
	v_cvt_u32_f32_sdwa v5, v5 dst_sel:WORD_1 dst_unused:UNUSED_PAD src0_sel:DWORD
	v_cvt_u32_f32_sdwa v2, v2 dst_sel:WORD_1 dst_unused:UNUSED_PAD src0_sel:DWORD
	v_cvt_u32_f32_sdwa v6, v6 dst_sel:BYTE_3 dst_unused:UNUSED_PAD src0_sel:DWORD
	v_cvt_u32_f32_sdwa v3, v3 dst_sel:BYTE_3 dst_unused:UNUSED_PAD src0_sel:DWORD
	v_lshl_or_b32 v0, v0, 8, v4
	v_lshl_or_b32 v1, v1, 8, v10
	v_or3_b32 v0, v0, v5, v6
	v_or3_b32 v1, v1, v2, v3
	s_andn2_b64 vcc, exec, s[0:1]
	s_mov_b64 s[0:1], -1
	global_store_dwordx2 v[16:17], v[0:1], off offset:128
	s_cbranch_vccnz .LBB0_804
	s_andn2_b64 vcc, exec, s[10:11]
	s_cbranch_vccnz .LBB0_803
	s_barrier
	s_branch .LBB0_803
